# plus: LDS buffer base addresses (vBase+const) hoisted out of the 8 SP2 GEMM k-loops into free VGPRs
# speedup vs baseline: 1.0017x; 1.0006x over previous
; #define PG8_STAGE(bufoff, gbase, voff) do { _Pragma("unroll") for (int _i = 0; _i < 2; ++_i) \
;         __builtin_amdgcn_global_load_lds((const unsigned*)((const char*)(gbase) + (voff)[_i]), (LAS unsigned*)(lds + (bufoff) + ldsw + _i * 8192), 16, 0, 0); } while (0)
; #define PG8_LDA(dst, b, h) do { _Pragma("unroll") for (int m = 0; m < 4; ++m) _Pragma("unroll") for (int k = 0; k < 2; ++k) dst[m][k] = *(const LAS bf16x8*)(lds + PG8_SA(b, h) + aoff + m * 2048 + k * 1024); } while (0)
; #define PG8_LDB(dst, b, h) do { _Pragma("unroll") for (int n = 0; n < 2; ++n) _Pragma("unroll") for (int k = 0; k < 2; ++k) dst[n][k] = *(const LAS bf16x8*)(lds + PG8_SB(b, h) + boff + n * 2048 + k * 1024); } while (0)
; #define PG8_WAIT_V(n) asm volatile("s_waitcnt vmcnt(" #n ")" ::: "memory")
; #define PG8_WAIT_L(n) asm volatile("s_waitcnt lgkmcnt(" #n ")" ::: "memory")
; #define PG8_BAR __builtin_amdgcn_s_barrier()
; #define PG8_SCHED __builtin_amdgcn_sched_barrier(0)
;     ...
;             PG8_LDB(B0, 0, 0); PG8_LDB(B1, 0, 1); PG8_SCHED; PG8_LDA(At, 0, 0); PG8_STAGE(PG8_SA(1, 1), a1 + hstepA, voffA);
;             PG8_WAIT_V(8); PG8_WAIT_L(0); PG8_BAR; PG8_MMA(0, 0, At, B0); PG8_MMA(0, 1, At, B1); PG8_BAR; PG8_SCHED;
;     ...
; #pragma unroll
;         for (int a = 0; a < 2; ++a)
; #pragma unroll
;             for (int b = 0; b < 2; ++b)
; #pragma unroll
;                 for (int m = 0; m < 4; ++m)
; #pragma unroll
;                     for (int n = 0; n < 2; ++n) acc[a][b][m][n] = (f32x4){0.f, 0.f, 0.f, 0.f};
.LBB0_164:
	v_lshl_add_u64 v[6:7], v[148:149], 0, s[52:53]
	v_lshl_add_u64 v[154:155], v[4:5], 0, s[4:5]
	v_mov_b32_e32 v4, 0
	v_lshl_add_u64 v[150:151], v[6:7], 0, v[140:141]
	v_lshl_add_u64 v[152:153], v[6:7], 0, v[142:143]
	s_mov_b32 s60, -2
	s_mov_b64 s[38:39], 0
	v_mov_b32_e32 v5, v4
	v_mov_b32_e32 v6, v4
	v_mov_b32_e32 v7, v4
	v_mov_b32_e32 v8, v4
	v_mov_b32_e32 v9, v4
	v_mov_b32_e32 v10, v4
	v_mov_b32_e32 v11, v4
	v_mov_b32_e32 v20, v4
	v_mov_b32_e32 v21, v4
	v_mov_b32_e32 v22, v4
	v_mov_b32_e32 v23, v4
	v_mov_b32_e32 v24, v4
	v_mov_b32_e32 v25, v4
	v_mov_b32_e32 v26, v4
	v_mov_b32_e32 v27, v4
	v_mov_b32_e32 v36, v4
	v_mov_b32_e32 v37, v4
	v_mov_b32_e32 v38, v4
	v_mov_b32_e32 v39, v4
	v_mov_b32_e32 v40, v4
	v_mov_b32_e32 v41, v4
	v_mov_b32_e32 v42, v4
	v_mov_b32_e32 v43, v4
	v_mov_b32_e32 v52, v4
	v_mov_b32_e32 v53, v4
	v_mov_b32_e32 v54, v4
	v_mov_b32_e32 v55, v4
	v_mov_b32_e32 v56, v4
	v_mov_b32_e32 v57, v4
	v_mov_b32_e32 v58, v4
	v_mov_b32_e32 v59, v4
	v_mov_b32_e32 v12, v4
	v_mov_b32_e32 v13, v4
	v_mov_b32_e32 v14, v4
	v_mov_b32_e32 v15, v4
	v_mov_b32_e32 v16, v4
	v_mov_b32_e32 v17, v4
	v_mov_b32_e32 v18, v4
	v_mov_b32_e32 v19, v4
	v_mov_b32_e32 v28, v4
	v_mov_b32_e32 v29, v4
	v_mov_b32_e32 v30, v4
	v_mov_b32_e32 v31, v4
	v_mov_b32_e32 v32, v4
	v_mov_b32_e32 v33, v4
	v_mov_b32_e32 v34, v4
	v_mov_b32_e32 v35, v4
	v_mov_b32_e32 v44, v4
	v_mov_b32_e32 v45, v4
	v_mov_b32_e32 v46, v4
	v_mov_b32_e32 v47, v4
	v_mov_b32_e32 v48, v4
	v_mov_b32_e32 v49, v4
	v_mov_b32_e32 v50, v4
	v_mov_b32_e32 v51, v4
	v_mov_b32_e32 v60, v4
	v_mov_b32_e32 v61, v4
	v_mov_b32_e32 v62, v4
	v_mov_b32_e32 v63, v4
	v_mov_b32_e32 v64, v4
	v_mov_b32_e32 v65, v4
	v_mov_b32_e32 v66, v4
	v_mov_b32_e32 v67, v4
	v_mov_b32_e32 v68, v4
	v_mov_b32_e32 v69, v4
	v_mov_b32_e32 v70, v4
	v_mov_b32_e32 v71, v4
	v_mov_b32_e32 v72, v4
	v_mov_b32_e32 v73, v4
	v_mov_b32_e32 v74, v4
	v_mov_b32_e32 v75, v4
	v_mov_b32_e32 v84, v4
	v_mov_b32_e32 v85, v4
	v_mov_b32_e32 v86, v4
	v_mov_b32_e32 v87, v4
	v_mov_b32_e32 v88, v4
	v_mov_b32_e32 v89, v4
	v_mov_b32_e32 v90, v4
	v_mov_b32_e32 v91, v4
	v_mov_b32_e32 v100, v4
	v_mov_b32_e32 v101, v4
	v_mov_b32_e32 v102, v4
	v_mov_b32_e32 v103, v4
	v_mov_b32_e32 v104, v4
	v_mov_b32_e32 v105, v4
	v_mov_b32_e32 v106, v4
	v_mov_b32_e32 v107, v4
	v_mov_b32_e32 v116, v4
	v_mov_b32_e32 v117, v4
	v_mov_b32_e32 v118, v4
	v_mov_b32_e32 v119, v4
	v_mov_b32_e32 v120, v4
	v_mov_b32_e32 v121, v4
	v_mov_b32_e32 v122, v4
	v_mov_b32_e32 v123, v4
	v_mov_b32_e32 v76, v4
	v_mov_b32_e32 v77, v4
	v_mov_b32_e32 v78, v4
	v_mov_b32_e32 v79, v4
	v_mov_b32_e32 v80, v4
	v_mov_b32_e32 v81, v4
	v_mov_b32_e32 v82, v4
	v_mov_b32_e32 v83, v4
	v_mov_b32_e32 v92, v4
	v_mov_b32_e32 v93, v4
	v_mov_b32_e32 v94, v4
	v_mov_b32_e32 v95, v4
	v_mov_b32_e32 v96, v4
	v_mov_b32_e32 v97, v4
	v_mov_b32_e32 v98, v4
	v_mov_b32_e32 v99, v4
	v_mov_b32_e32 v108, v4
	v_mov_b32_e32 v109, v4
	v_mov_b32_e32 v110, v4
	v_mov_b32_e32 v111, v4
	v_mov_b32_e32 v112, v4
	v_mov_b32_e32 v113, v4
	v_mov_b32_e32 v114, v4
	v_mov_b32_e32 v115, v4
	v_mov_b32_e32 v124, v4
	v_mov_b32_e32 v125, v4
	v_mov_b32_e32 v126, v4
	v_mov_b32_e32 v127, v4
	v_mov_b32_e32 v128, v4
	v_mov_b32_e32 v129, v4
	v_mov_b32_e32 v130, v4
	v_mov_b32_e32 v131, v4
	v_add_u32_e32 v246, 0x10000, v158
	v_add_u32_e32 v247, 0x14000, v158
	v_add_u32_e32 v248, 0x18000, v158
	v_add_u32_e32 v249, 0x1c000, v158
.LBB0_165:
	s_add_i32 s62, 0, 0x10000
	v_lshl_add_u64 v[162:163], v[148:149], 0, s[38:39]
	s_cmpk_eq_i32 s38, 0xf00
	v_lshl_add_u64 v[162:163], v[162:163], 0, s[4:5]
	s_cselect_b64 vcc, -1, 0
	s_add_i32 s63, 0, 0x14000
	v_lshl_add_u64 v[178:179], v[154:155], 0, s[38:39]
	v_cndmask_b32_e32 v231, v163, v145, vcc
	v_cndmask_b32_e32 v230, v162, v144, vcc
	ds_read_b128 v[162:165], v246
	ds_read_b128 v[166:169], v246 offset:1024
	ds_read_b128 v[170:173], v246 offset:2048
	ds_read_b128 v[174:177], v246 offset:3072
	v_cndmask_b32_e32 v233, v179, v147, vcc
	v_cndmask_b32_e32 v232, v178, v146, vcc
	ds_read_b128 v[178:181], v247
	ds_read_b128 v[182:185], v247 offset:1024
	ds_read_b128 v[186:189], v247 offset:2048
	ds_read_b128 v[190:193], v247 offset:3072
	v_lshl_add_u64 v[234:235], v[152:153], 0, s[38:39]
	s_add_i32 m0, s3, 0xc000
	ds_read_b128 v[194:197], v160
	ds_read_b128 v[198:201], v160 offset:1024
	ds_read_b128 v[202:205], v160 offset:2048
	ds_read_b128 v[206:209], v160 offset:3072
	ds_read_b128 v[210:213], v160 offset:4096
	ds_read_b128 v[214:217], v160 offset:5120
	ds_read_b128 v[218:221], v160 offset:6144
	ds_read_b128 v[226:229], v160 offset:7168
	global_load_lds_dwordx4 v[234:235], off
	v_lshl_add_u64 v[234:235], v[150:151], 0, s[38:39]
	s_add_i32 m0, s3, 0xe000
	s_nop 0
	global_load_lds_dwordx4 v[234:235], off
	s_waitcnt vmcnt(8)
	s_waitcnt lgkmcnt(0)
	s_barrier
; #define PG8_STAGE(bufoff, gbase, voff) do { _Pragma("unroll") for (int _i = 0; _i < 2; ++_i) \
;         __builtin_amdgcn_global_load_lds((const unsigned*)((const char*)(gbase) + (voff)[_i]), (LAS unsigned*)(lds + (bufoff) + ldsw + _i * 8192), 16, 0, 0); } while (0)
; #define PG8_LDA(dst, b, h) do { _Pragma("unroll") for (int m = 0; m < 4; ++m) _Pragma("unroll") for (int k = 0; k < 2; ++k) dst[m][k] = *(const LAS bf16x8*)(lds + PG8_SA(b, h) + aoff + m * 2048 + k * 1024); } while (0)
; #define PG8_WAIT_V(n) asm volatile("s_waitcnt vmcnt(" #n ")" ::: "memory")
; #define PG8_WAIT_L(n) asm volatile("s_waitcnt lgkmcnt(" #n ")" ::: "memory")
; #define PG8_BAR __builtin_amdgcn_s_barrier()
; #define PG8_SCHED __builtin_amdgcn_sched_barrier(0)
;     ...
;             PG8_WAIT_V(8); PG8_WAIT_L(0); PG8_BAR; PG8_MMA(0, 0, At, B0); PG8_MMA(0, 1, At, B1); PG8_BAR; PG8_SCHED;
;             PG8_LDA(At, 0, 1); PG8_STAGE(PG8_SB(0, 0), b2, voffB); PG8_STAGE(PG8_SB(0, 1), b2 + hstepB, voffB); PG8_STAGE(PG8_SA(0, 0), a2, voffA);
;             PG8_WAIT_V(8); PG8_WAIT_L(0); PG8_BAR; PG8_MMA(1, 0, At, B0); PG8_MMA(1, 1, At, B1); PG8_BAR; PG8_SCHED;
	s_setprio 1
	v_mfma_i32_16x16x64_i8 v[128:131], v[162:165], v[194:197], v[128:131]
	v_mfma_i32_16x16x64_i8 v[124:127], v[170:173], v[194:197], v[124:127]
	v_mfma_i32_16x16x64_i8 v[112:115], v[162:165], v[202:205], v[112:115]
	v_mfma_i32_16x16x64_i8 v[108:111], v[170:173], v[202:205], v[108:111]
	v_mfma_i32_16x16x64_i8 v[96:99], v[162:165], v[210:213], v[96:99]
	v_mfma_i32_16x16x64_i8 v[92:95], v[170:173], v[210:213], v[92:95]
	v_mfma_i32_16x16x64_i8 v[80:83], v[162:165], v[218:221], v[80:83]
	v_mfma_i32_16x16x64_i8 v[76:79], v[170:173], v[218:221], v[76:79]
	v_mfma_i32_16x16x64_i8 v[128:131], v[166:169], v[198:201], v[128:131]
	v_mfma_i32_16x16x64_i8 v[124:127], v[174:177], v[198:201], v[124:127]
	v_mfma_i32_16x16x64_i8 v[112:115], v[166:169], v[206:209], v[112:115]
	v_mfma_i32_16x16x64_i8 v[108:111], v[174:177], v[206:209], v[108:111]
	v_mfma_i32_16x16x64_i8 v[96:99], v[166:169], v[214:217], v[96:99]
	v_mfma_i32_16x16x64_i8 v[92:95], v[174:177], v[214:217], v[92:95]
	v_mfma_i32_16x16x64_i8 v[80:83], v[166:169], v[226:229], v[80:83]
	v_mfma_i32_16x16x64_i8 v[76:79], v[174:177], v[226:229], v[76:79]
	v_mfma_i32_16x16x64_i8 v[120:123], v[178:181], v[194:197], v[120:123]
	v_mfma_i32_16x16x64_i8 v[116:119], v[186:189], v[194:197], v[116:119]
	v_mfma_i32_16x16x64_i8 v[104:107], v[178:181], v[202:205], v[104:107]
	v_mfma_i32_16x16x64_i8 v[100:103], v[186:189], v[202:205], v[100:103]
	v_mfma_i32_16x16x64_i8 v[88:91], v[178:181], v[210:213], v[88:91]
	v_mfma_i32_16x16x64_i8 v[84:87], v[186:189], v[210:213], v[84:87]
	v_mfma_i32_16x16x64_i8 v[72:75], v[178:181], v[218:221], v[72:75]
	v_mfma_i32_16x16x64_i8 v[68:71], v[186:189], v[218:221], v[68:71]
	v_mfma_i32_16x16x64_i8 v[120:123], v[182:185], v[198:201], v[120:123]
	v_mfma_i32_16x16x64_i8 v[116:119], v[190:193], v[198:201], v[116:119]
	v_mfma_i32_16x16x64_i8 v[104:107], v[182:185], v[206:209], v[104:107]
	v_mfma_i32_16x16x64_i8 v[100:103], v[190:193], v[206:209], v[100:103]
	v_mfma_i32_16x16x64_i8 v[88:91], v[182:185], v[214:217], v[88:91]
	v_mfma_i32_16x16x64_i8 v[84:87], v[190:193], v[214:217], v[84:87]
	v_mfma_i32_16x16x64_i8 v[72:75], v[182:185], v[226:229], v[72:75]
	v_mfma_i32_16x16x64_i8 v[68:71], v[190:193], v[226:229], v[68:71]
	s_setprio 0
	s_barrier
	s_add_i32 s62, s62, s2
	v_lshl_add_u64 v[234:235], v[232:233], 0, v[2:3]
	s_mov_b32 m0, s62
	ds_read_b128 v[194:197], v160 offset:16384
	ds_read_b128 v[198:201], v160 offset:17408
	ds_read_b128 v[202:205], v160 offset:18432
	ds_read_b128 v[206:209], v160 offset:19456
	ds_read_b128 v[210:213], v160 offset:20480
	ds_read_b128 v[214:217], v160 offset:21504
	ds_read_b128 v[218:221], v160 offset:22528
	ds_read_b128 v[226:229], v160 offset:23552
	global_load_lds_dwordx4 v[234:235], off
	v_lshl_add_u64 v[236:237], v[232:233], 0, v[134:135]
	s_add_i32 m0, s62, 0x2000
	v_lshl_add_u64 v[232:233], v[232:233], 0, v[138:139]
	s_add_i32 s62, s63, s2
	global_load_lds_dwordx4 v[236:237], off
	v_lshl_add_u64 v[238:239], v[232:233], 0, v[2:3]
	s_mov_b32 m0, s62
	v_lshl_add_u64 v[232:233], v[232:233], 0, v[134:135]
	global_load_lds_dwordx4 v[238:239], off
	s_add_i32 m0, s62, 0x2000
	v_lshl_add_u64 v[240:241], v[230:231], 0, v[0:1]
	global_load_lds_dwordx4 v[232:233], off
	s_mov_b32 m0, s3
	v_lshl_add_u64 v[242:243], v[230:231], 0, v[132:133]
	global_load_lds_dwordx4 v[240:241], off
	s_mov_b32 m0, s8
	s_nop 0
	global_load_lds_dwordx4 v[242:243], off
	s_waitcnt vmcnt(8)
	s_waitcnt lgkmcnt(0)
	s_barrier
	s_setprio 1
	v_mfma_i32_16x16x64_i8 v[64:67], v[162:165], v[194:197], v[64:67]
	v_mfma_i32_16x16x64_i8 v[60:63], v[170:173], v[194:197], v[60:63]
	v_mfma_i32_16x16x64_i8 v[48:51], v[162:165], v[202:205], v[48:51]
	v_mfma_i32_16x16x64_i8 v[44:47], v[170:173], v[202:205], v[44:47]
	v_mfma_i32_16x16x64_i8 v[32:35], v[162:165], v[210:213], v[32:35]
	v_mfma_i32_16x16x64_i8 v[28:31], v[170:173], v[210:213], v[28:31]
	v_mfma_i32_16x16x64_i8 v[16:19], v[162:165], v[218:221], v[16:19]
	v_mfma_i32_16x16x64_i8 v[12:15], v[170:173], v[218:221], v[12:15]
	v_mfma_i32_16x16x64_i8 v[64:67], v[166:169], v[198:201], v[64:67]
	v_mfma_i32_16x16x64_i8 v[60:63], v[174:177], v[198:201], v[60:63]
	v_mfma_i32_16x16x64_i8 v[48:51], v[166:169], v[206:209], v[48:51]
	v_mfma_i32_16x16x64_i8 v[44:47], v[174:177], v[206:209], v[44:47]
	v_mfma_i32_16x16x64_i8 v[32:35], v[166:169], v[214:217], v[32:35]
	v_mfma_i32_16x16x64_i8 v[28:31], v[174:177], v[214:217], v[28:31]
	v_mfma_i32_16x16x64_i8 v[16:19], v[166:169], v[226:229], v[16:19]
	v_mfma_i32_16x16x64_i8 v[12:15], v[174:177], v[226:229], v[12:15]
	v_mfma_i32_16x16x64_i8 v[56:59], v[178:181], v[194:197], v[56:59]
	v_mfma_i32_16x16x64_i8 v[52:55], v[186:189], v[194:197], v[52:55]
	v_mfma_i32_16x16x64_i8 v[40:43], v[178:181], v[202:205], v[40:43]
	v_mfma_i32_16x16x64_i8 v[36:39], v[186:189], v[202:205], v[36:39]
	v_mfma_i32_16x16x64_i8 v[24:27], v[178:181], v[210:213], v[24:27]
	v_mfma_i32_16x16x64_i8 v[20:23], v[186:189], v[210:213], v[20:23]
	v_mfma_i32_16x16x64_i8 v[8:11], v[178:181], v[218:221], v[8:11]
	v_mfma_i32_16x16x64_i8 v[4:7], v[186:189], v[218:221], v[4:7]
	v_mfma_i32_16x16x64_i8 v[56:59], v[182:185], v[198:201], v[56:59]
	v_mfma_i32_16x16x64_i8 v[52:55], v[190:193], v[198:201], v[52:55]
	v_mfma_i32_16x16x64_i8 v[40:43], v[182:185], v[206:209], v[40:43]
	v_mfma_i32_16x16x64_i8 v[36:39], v[190:193], v[206:209], v[36:39]
	v_mfma_i32_16x16x64_i8 v[24:27], v[182:185], v[214:217], v[24:27]
	v_mfma_i32_16x16x64_i8 v[20:23], v[190:193], v[214:217], v[20:23]
	v_mfma_i32_16x16x64_i8 v[8:11], v[182:185], v[226:229], v[8:11]
	v_mfma_i32_16x16x64_i8 v[4:7], v[190:193], v[226:229], v[4:7]
	s_setprio 0
	s_barrier
; #define PG8_STAGE(bufoff, gbase, voff) do { _Pragma("unroll") for (int _i = 0; _i < 2; ++_i) \
;         __builtin_amdgcn_global_load_lds((const unsigned*)((const char*)(gbase) + (voff)[_i]), (LAS unsigned*)(lds + (bufoff) + ldsw + _i * 8192), 16, 0, 0); } while (0)
; #define PG8_LDA(dst, b, h) do { _Pragma("unroll") for (int m = 0; m < 4; ++m) _Pragma("unroll") for (int k = 0; k < 2; ++k) dst[m][k] = *(const LAS bf16x8*)(lds + PG8_SA(b, h) + aoff + m * 2048 + k * 1024); } while (0)
; #define PG8_LDB(dst, b, h) do { _Pragma("unroll") for (int n = 0; n < 2; ++n) _Pragma("unroll") for (int k = 0; k < 2; ++k) dst[n][k] = *(const LAS bf16x8*)(lds + PG8_SB(b, h) + boff + n * 2048 + k * 1024); } while (0)
; #define PG8_WAIT_V(n) asm volatile("s_waitcnt vmcnt(" #n ")" ::: "memory")
; #define PG8_WAIT_L(n) asm volatile("s_waitcnt lgkmcnt(" #n ")" ::: "memory")
; #define PG8_BAR __builtin_amdgcn_s_barrier()
; #define PG8_SCHED __builtin_amdgcn_sched_barrier(0)
;     ...
;             PG8_LDB(B0, 1, 0); PG8_LDB(B1, 1, 1); PG8_SCHED; PG8_LDA(At, 1, 0); PG8_STAGE(PG8_SA(0, 1), a2 + hstepA, voffA);
;             PG8_WAIT_V(8); PG8_WAIT_L(0); PG8_BAR; PG8_MMA(0, 0, At, B0); PG8_MMA(0, 1, At, B1); PG8_BAR; PG8_SCHED;
;             PG8_LDA(At, 1, 1); PG8_STAGE(PG8_SB(1, 0), b3, voffB); PG8_STAGE(PG8_SB(1, 1), b3 + hstepB, voffB); PG8_STAGE(PG8_SA(1, 0), a3, voffA);
;             PG8_WAIT_V(8); PG8_WAIT_L(0); PG8_BAR; PG8_MMA(1, 0, At, B0); PG8_MMA(1, 1, At, B1); PG8_BAR; PG8_SCHED;
	s_add_i32 s62, 0, 0x18000
	s_add_i32 s63, 0, 0x1c000
	ds_read_b128 v[162:165], v248
	ds_read_b128 v[166:169], v248 offset:1024
	ds_read_b128 v[170:173], v248 offset:2048
	ds_read_b128 v[174:177], v248 offset:3072
	ds_read_b128 v[178:181], v249
	ds_read_b128 v[182:185], v249 offset:1024
	ds_read_b128 v[186:189], v249 offset:2048
	ds_read_b128 v[190:193], v249 offset:3072
	v_lshl_add_u64 v[230:231], v[230:231], 0, v[136:137]
	s_mov_b32 m0, s9
	v_lshl_add_u64 v[244:245], v[230:231], 0, v[0:1]
	ds_read_b128 v[194:197], v160 offset:32768
	ds_read_b128 v[198:201], v160 offset:33792
	ds_read_b128 v[202:205], v160 offset:34816
	ds_read_b128 v[206:209], v160 offset:35840
	ds_read_b128 v[210:213], v160 offset:36864
	ds_read_b128 v[214:217], v160 offset:37888
	ds_read_b128 v[218:221], v160 offset:38912
	ds_read_b128 v[226:229], v160 offset:39936
	global_load_lds_dwordx4 v[244:245], off
	v_lshl_add_u64 v[230:231], v[230:231], 0, v[132:133]
	s_mov_b32 m0, s15
	s_nop 0
	global_load_lds_dwordx4 v[230:231], off
	s_waitcnt vmcnt(8)
	s_waitcnt lgkmcnt(0)
	s_barrier
	s_setprio 1
	v_mfma_i32_16x16x64_i8 v[128:131], v[162:165], v[194:197], v[128:131]
	v_mfma_i32_16x16x64_i8 v[124:127], v[170:173], v[194:197], v[124:127]
	v_mfma_i32_16x16x64_i8 v[112:115], v[162:165], v[202:205], v[112:115]
	v_mfma_i32_16x16x64_i8 v[108:111], v[170:173], v[202:205], v[108:111]
	v_mfma_i32_16x16x64_i8 v[96:99], v[162:165], v[210:213], v[96:99]
	v_mfma_i32_16x16x64_i8 v[92:95], v[170:173], v[210:213], v[92:95]
	v_mfma_i32_16x16x64_i8 v[80:83], v[162:165], v[218:221], v[80:83]
	v_mfma_i32_16x16x64_i8 v[76:79], v[170:173], v[218:221], v[76:79]
	v_mfma_i32_16x16x64_i8 v[128:131], v[166:169], v[198:201], v[128:131]
	v_mfma_i32_16x16x64_i8 v[124:127], v[174:177], v[198:201], v[124:127]
	v_mfma_i32_16x16x64_i8 v[112:115], v[166:169], v[206:209], v[112:115]
	v_mfma_i32_16x16x64_i8 v[108:111], v[174:177], v[206:209], v[108:111]
	v_mfma_i32_16x16x64_i8 v[96:99], v[166:169], v[214:217], v[96:99]
	v_mfma_i32_16x16x64_i8 v[92:95], v[174:177], v[214:217], v[92:95]
	v_mfma_i32_16x16x64_i8 v[80:83], v[166:169], v[226:229], v[80:83]
	v_mfma_i32_16x16x64_i8 v[76:79], v[174:177], v[226:229], v[76:79]
	v_mfma_i32_16x16x64_i8 v[120:123], v[178:181], v[194:197], v[120:123]
	v_mfma_i32_16x16x64_i8 v[116:119], v[186:189], v[194:197], v[116:119]
	v_mfma_i32_16x16x64_i8 v[104:107], v[178:181], v[202:205], v[104:107]
	v_mfma_i32_16x16x64_i8 v[100:103], v[186:189], v[202:205], v[100:103]
	v_mfma_i32_16x16x64_i8 v[88:91], v[178:181], v[210:213], v[88:91]
	v_mfma_i32_16x16x64_i8 v[84:87], v[186:189], v[210:213], v[84:87]
	v_mfma_i32_16x16x64_i8 v[72:75], v[178:181], v[218:221], v[72:75]
	v_mfma_i32_16x16x64_i8 v[68:71], v[186:189], v[218:221], v[68:71]
	v_mfma_i32_16x16x64_i8 v[120:123], v[182:185], v[198:201], v[120:123]
	v_mfma_i32_16x16x64_i8 v[116:119], v[190:193], v[198:201], v[116:119]
	v_mfma_i32_16x16x64_i8 v[104:107], v[182:185], v[206:209], v[104:107]
	v_mfma_i32_16x16x64_i8 v[100:103], v[190:193], v[206:209], v[100:103]
	v_mfma_i32_16x16x64_i8 v[88:91], v[182:185], v[214:217], v[88:91]
	v_mfma_i32_16x16x64_i8 v[84:87], v[190:193], v[214:217], v[84:87]
	v_mfma_i32_16x16x64_i8 v[72:75], v[182:185], v[226:229], v[72:75]
	v_mfma_i32_16x16x64_i8 v[68:71], v[190:193], v[226:229], v[68:71]
	s_setprio 0
	s_barrier
	s_add_i32 s62, s62, s2
	v_lshl_add_u64 v[230:231], v[234:235], 0, s[52:53]
	s_mov_b32 m0, s62
	ds_read_b128 v[194:197], v160 offset:49152
	ds_read_b128 v[198:201], v160 offset:50176
	ds_read_b128 v[202:205], v160 offset:51200
	ds_read_b128 v[206:209], v160 offset:52224
	ds_read_b128 v[210:213], v160 offset:53248
	ds_read_b128 v[214:217], v160 offset:54272
	ds_read_b128 v[218:221], v160 offset:55296
	ds_read_b128 v[226:229], v160 offset:56320
	global_load_lds_dwordx4 v[230:231], off
	v_lshl_add_u64 v[230:231], v[236:237], 0, s[52:53]
	s_add_i32 m0, s62, 0x2000
	s_add_i32 s62, s63, s2
	global_load_lds_dwordx4 v[230:231], off
	v_lshl_add_u64 v[230:231], v[238:239], 0, s[52:53]
	s_mov_b32 m0, s62
	s_nop 0
	global_load_lds_dwordx4 v[230:231], off
	v_lshl_add_u64 v[230:231], v[232:233], 0, s[52:53]
	s_add_i32 m0, s62, 0x2000
	s_nop 0
	global_load_lds_dwordx4 v[230:231], off
	v_lshl_add_u64 v[230:231], v[240:241], 0, s[52:53]
	s_mov_b32 m0, s47
	s_nop 0
	global_load_lds_dwordx4 v[230:231], off
	v_lshl_add_u64 v[230:231], v[242:243], 0, s[52:53]
	s_mov_b32 m0, s48
	s_nop 0
	global_load_lds_dwordx4 v[230:231], off
	s_waitcnt vmcnt(8)
	s_waitcnt lgkmcnt(0)
	s_barrier
	s_setprio 1
	v_mfma_i32_16x16x64_i8 v[64:67], v[162:165], v[194:197], v[64:67]
	v_mfma_i32_16x16x64_i8 v[60:63], v[170:173], v[194:197], v[60:63]
	v_mfma_i32_16x16x64_i8 v[48:51], v[162:165], v[202:205], v[48:51]
	v_mfma_i32_16x16x64_i8 v[44:47], v[170:173], v[202:205], v[44:47]
	v_mfma_i32_16x16x64_i8 v[32:35], v[162:165], v[210:213], v[32:35]
	v_mfma_i32_16x16x64_i8 v[28:31], v[170:173], v[210:213], v[28:31]
	v_mfma_i32_16x16x64_i8 v[16:19], v[162:165], v[218:221], v[16:19]
	v_mfma_i32_16x16x64_i8 v[12:15], v[170:173], v[218:221], v[12:15]
	v_mfma_i32_16x16x64_i8 v[64:67], v[166:169], v[198:201], v[64:67]
	v_mfma_i32_16x16x64_i8 v[60:63], v[174:177], v[198:201], v[60:63]
	v_mfma_i32_16x16x64_i8 v[48:51], v[166:169], v[206:209], v[48:51]
	v_mfma_i32_16x16x64_i8 v[44:47], v[174:177], v[206:209], v[44:47]
	v_mfma_i32_16x16x64_i8 v[32:35], v[166:169], v[214:217], v[32:35]
	v_mfma_i32_16x16x64_i8 v[28:31], v[174:177], v[214:217], v[28:31]
	v_mfma_i32_16x16x64_i8 v[16:19], v[166:169], v[226:229], v[16:19]
	v_mfma_i32_16x16x64_i8 v[12:15], v[174:177], v[226:229], v[12:15]
	v_mfma_i32_16x16x64_i8 v[56:59], v[178:181], v[194:197], v[56:59]
	v_mfma_i32_16x16x64_i8 v[52:55], v[186:189], v[194:197], v[52:55]
	v_mfma_i32_16x16x64_i8 v[40:43], v[178:181], v[202:205], v[40:43]
	v_mfma_i32_16x16x64_i8 v[36:39], v[186:189], v[202:205], v[36:39]
	v_mfma_i32_16x16x64_i8 v[24:27], v[178:181], v[210:213], v[24:27]
	v_mfma_i32_16x16x64_i8 v[20:23], v[186:189], v[210:213], v[20:23]
	v_mfma_i32_16x16x64_i8 v[8:11], v[178:181], v[218:221], v[8:11]
	v_mfma_i32_16x16x64_i8 v[4:7], v[186:189], v[218:221], v[4:7]
	v_mfma_i32_16x16x64_i8 v[56:59], v[182:185], v[198:201], v[56:59]
	v_mfma_i32_16x16x64_i8 v[52:55], v[190:193], v[198:201], v[52:55]
	v_mfma_i32_16x16x64_i8 v[40:43], v[182:185], v[206:209], v[40:43]
	v_mfma_i32_16x16x64_i8 v[36:39], v[190:193], v[206:209], v[36:39]
	v_mfma_i32_16x16x64_i8 v[24:27], v[182:185], v[214:217], v[24:27]
	v_mfma_i32_16x16x64_i8 v[20:23], v[190:193], v[214:217], v[20:23]
	v_mfma_i32_16x16x64_i8 v[8:11], v[182:185], v[226:229], v[8:11]
	v_mfma_i32_16x16x64_i8 v[4:7], v[190:193], v[226:229], v[4:7]
	s_setprio 0
	s_barrier
	s_add_i32 s60, s60, 2
	s_add_u32 s38, s38, 0x100
	s_addc_u32 s39, s39, 0
	s_cmp_gt_u32 s60, 29
	s_cbranch_scc0 .LBB0_165
	s_and_b64 vcc, exec, s[42:43]
	s_cbranch_vccz .LBB0_168
	s_barrier

; #define PG8_STAGE(bufoff, gbase, voff) do { _Pragma("unroll") for (int _i = 0; _i < 2; ++_i) \
;         __builtin_amdgcn_global_load_lds((const unsigned*)((const char*)(gbase) + (voff)[_i]), (LAS unsigned*)(lds + (bufoff) + ldsw + _i * 8192), 16, 0, 0); } while (0)
; #define PG8_LDA(dst, b, h) do { _Pragma("unroll") for (int m = 0; m < 4; ++m) _Pragma("unroll") for (int k = 0; k < 2; ++k) dst[m][k] = *(const LAS bf16x8*)(lds + PG8_SA(b, h) + aoff + m * 2048 + k * 1024); } while (0)
; #define PG8_LDB(dst, b, h) do { _Pragma("unroll") for (int n = 0; n < 2; ++n) _Pragma("unroll") for (int k = 0; k < 2; ++k) dst[n][k] = *(const LAS bf16x8*)(lds + PG8_SB(b, h) + boff + n * 2048 + k * 1024); } while (0)
; #define PG8_WAIT_V(n) asm volatile("s_waitcnt vmcnt(" #n ")" ::: "memory")
; #define PG8_WAIT_L(n) asm volatile("s_waitcnt lgkmcnt(" #n ")" ::: "memory")
; #define PG8_BAR __builtin_amdgcn_s_barrier()
; #define PG8_SCHED __builtin_amdgcn_sched_barrier(0)
;     ...
;     for (;;) {
;         const bool has_next = S.next(ui + 1, nxt);
;         const char* nA = has_next ? PG8_ABASE(nxt) : cA; const char* nB = has_next ? (const char*)g.Bt + (size_t)nxt.pn * tstepB : cB;
; #pragma unroll 1
;         for (int t = 0; t < nt; t += 2) {
;             const bool last = (t == nt - 2);
;             const char* a1 = cA + (size_t)(t + 1) * kstep;
;             const char* a2 = last ? nA : cA + (size_t)(t + 2) * kstep; const char* b2 = last ? nB : cB + (size_t)(t + 2) * kstep;
;             const char* a3 = a2 + kstep; const char* b3 = b2 + kstep;
;             if constexpr (SP2) {
;             PG8_LDB(B0, 0, 0); PG8_LDB(B1, 0, 1); PG8_SCHED; PG8_LDA(At, 0, 0); PG8_STAGE(PG8_SA(1, 1), a1 + hstepA, voffA);
;             PG8_WAIT_V(8); PG8_WAIT_L(0); PG8_BAR; PG8_MMA(0, 0, At, B0); PG8_MMA(0, 1, At, B1); PG8_BAR; PG8_SCHED;
;     ...
; #pragma unroll
;         for (int a = 0; a < 2; ++a)
; #pragma unroll
;             for (int b = 0; b < 2; ++b)
; #pragma unroll
;                 for (int m = 0; m < 4; ++m)
; #pragma unroll
;                     for (int n = 0; n < 2; ++n) acc[a][b][m][n] = (f32x4){0.f, 0.f, 0.f, 0.f};
.LBB0_439:
	v_lshl_add_u64 v[6:7], v[180:181], 0, s[52:53]
	v_mov_b32_e32 v36, 0
	v_lshl_add_u64 v[182:183], v[6:7], 0, v[172:173]
	v_lshl_add_u64 v[184:185], v[6:7], 0, v[174:175]
	v_lshl_add_u64 v[186:187], v[4:5], 0, s[4:5]
	s_mov_b32 s62, -2
	s_mov_b64 s[38:39], 0
	v_mov_b32_e32 v37, v36
	v_mov_b32_e32 v38, v36
	v_mov_b32_e32 v39, v36
	v_mov_b32_e32 v40, v36
	v_mov_b32_e32 v41, v36
	v_mov_b32_e32 v42, v36
	v_mov_b32_e32 v43, v36
	v_mov_b32_e32 v48, v36
	v_mov_b32_e32 v49, v36
	v_mov_b32_e32 v50, v36
	v_mov_b32_e32 v51, v36
	v_mov_b32_e32 v56, v36
	v_mov_b32_e32 v57, v36
	v_mov_b32_e32 v58, v36
	v_mov_b32_e32 v59, v36
	v_mov_b32_e32 v64, v36
	v_mov_b32_e32 v65, v36
	v_mov_b32_e32 v66, v36
	v_mov_b32_e32 v67, v36
	v_mov_b32_e32 v72, v36
	v_mov_b32_e32 v73, v36
	v_mov_b32_e32 v74, v36
	v_mov_b32_e32 v75, v36
	v_mov_b32_e32 v80, v36
	v_mov_b32_e32 v81, v36
	v_mov_b32_e32 v82, v36
	v_mov_b32_e32 v83, v36
	v_mov_b32_e32 v88, v36
	v_mov_b32_e32 v89, v36
	v_mov_b32_e32 v90, v36
	v_mov_b32_e32 v91, v36
	v_mov_b32_e32 v44, v36
	v_mov_b32_e32 v45, v36
	v_mov_b32_e32 v46, v36
	v_mov_b32_e32 v47, v36
	v_mov_b32_e32 v52, v36
	v_mov_b32_e32 v53, v36
	v_mov_b32_e32 v54, v36
	v_mov_b32_e32 v55, v36
	v_mov_b32_e32 v60, v36
	v_mov_b32_e32 v61, v36
	v_mov_b32_e32 v62, v36
	v_mov_b32_e32 v63, v36
	v_mov_b32_e32 v68, v36
	v_mov_b32_e32 v69, v36
	v_mov_b32_e32 v70, v36
	v_mov_b32_e32 v71, v36
	v_mov_b32_e32 v76, v36
	v_mov_b32_e32 v77, v36
	v_mov_b32_e32 v78, v36
	v_mov_b32_e32 v79, v36
	v_mov_b32_e32 v84, v36
	v_mov_b32_e32 v85, v36
	v_mov_b32_e32 v86, v36
	v_mov_b32_e32 v87, v36
	v_mov_b32_e32 v92, v36
	v_mov_b32_e32 v93, v36
	v_mov_b32_e32 v94, v36
	v_mov_b32_e32 v95, v36
	v_mov_b32_e32 v96, v36
	v_mov_b32_e32 v97, v36
	v_mov_b32_e32 v98, v36
	v_mov_b32_e32 v99, v36
	v_mov_b32_e32 v100, v36
	v_mov_b32_e32 v101, v36
	v_mov_b32_e32 v102, v36
	v_mov_b32_e32 v103, v36
	v_mov_b32_e32 v104, v36
	v_mov_b32_e32 v105, v36
	v_mov_b32_e32 v106, v36
	v_mov_b32_e32 v107, v36
	v_mov_b32_e32 v112, v36
	v_mov_b32_e32 v113, v36
	v_mov_b32_e32 v114, v36
	v_mov_b32_e32 v115, v36
	v_mov_b32_e32 v120, v36
	v_mov_b32_e32 v121, v36
	v_mov_b32_e32 v122, v36
	v_mov_b32_e32 v123, v36
	v_mov_b32_e32 v128, v36
	v_mov_b32_e32 v129, v36
	v_mov_b32_e32 v130, v36
	v_mov_b32_e32 v131, v36
	v_mov_b32_e32 v136, v36
	v_mov_b32_e32 v137, v36
	v_mov_b32_e32 v138, v36
	v_mov_b32_e32 v139, v36
	v_mov_b32_e32 v144, v36
	v_mov_b32_e32 v145, v36
	v_mov_b32_e32 v146, v36
	v_mov_b32_e32 v147, v36
	v_mov_b32_e32 v152, v36
	v_mov_b32_e32 v153, v36
	v_mov_b32_e32 v154, v36
	v_mov_b32_e32 v155, v36
	v_mov_b32_e32 v108, v36
	v_mov_b32_e32 v109, v36
	v_mov_b32_e32 v110, v36
	v_mov_b32_e32 v111, v36
	v_mov_b32_e32 v116, v36
	v_mov_b32_e32 v117, v36
	v_mov_b32_e32 v118, v36
	v_mov_b32_e32 v119, v36
	v_mov_b32_e32 v124, v36
	v_mov_b32_e32 v125, v36
	v_mov_b32_e32 v126, v36
	v_mov_b32_e32 v127, v36
	v_mov_b32_e32 v132, v36
	v_mov_b32_e32 v133, v36
	v_mov_b32_e32 v134, v36
	v_mov_b32_e32 v135, v36
	v_mov_b32_e32 v140, v36
	v_mov_b32_e32 v141, v36
	v_mov_b32_e32 v142, v36
	v_mov_b32_e32 v143, v36
	v_mov_b32_e32 v148, v36
	v_mov_b32_e32 v149, v36
	v_mov_b32_e32 v150, v36
	v_mov_b32_e32 v151, v36
	v_mov_b32_e32 v156, v36
	v_mov_b32_e32 v157, v36
	v_mov_b32_e32 v158, v36
	v_mov_b32_e32 v159, v36
	v_mov_b32_e32 v160, v36
	v_mov_b32_e32 v161, v36
	v_mov_b32_e32 v162, v36
	v_mov_b32_e32 v163, v36
	v_add_u32_e32 v204, 0x10000, v210
	v_add_u32_e32 v205, 0x14000, v210
	v_add_u32_e32 v206, 0x18000, v210
	v_add_u32_e32 v207, 0x1c000, v210
.LBB0_440:
	s_add_i32 s63, 0, 0x10000
	v_lshl_add_u64 v[4:5], v[180:181], 0, s[38:39]
	s_cmpk_eq_i32 s38, 0x300
	v_lshl_add_u64 v[4:5], v[4:5], 0, s[4:5]
	s_cselect_b64 vcc, -1, 0
	s_add_i32 s64, 0, 0x14000
	v_lshl_add_u64 v[6:7], v[186:187], 0, s[38:39]
	v_cndmask_b32_e32 v188, v4, v176, vcc
	v_cndmask_b32_e32 v189, v5, v177, vcc
	ds_read_b128 v[28:31], v204
	ds_read_b128 v[32:35], v204 offset:1024
	ds_read_b128 v[20:23], v204 offset:2048
	ds_read_b128 v[24:27], v204 offset:3072
	v_cndmask_b32_e32 v199, v7, v179, vcc
	v_cndmask_b32_e32 v198, v6, v178, vcc
	ds_read_b128 v[12:15], v205
	ds_read_b128 v[16:19], v205 offset:1024
	ds_read_b128 v[4:7], v205 offset:2048
	ds_read_b128 v[8:11], v205 offset:3072
	v_lshl_add_u64 v[200:201], v[184:185], 0, s[38:39]
	s_add_i32 m0, s15, 0xc000
	ds_read_b128 v[190:193], v212
	ds_read_b128 v[194:197], v212 offset:1024
	ds_read_b128 v[226:229], v212 offset:2048
	ds_read_b128 v[230:233], v212 offset:3072
	ds_read_b128 v[234:237], v212 offset:4096
	ds_read_b128 v[238:241], v212 offset:5120
	ds_read_b128 v[242:245], v212 offset:6144
	ds_read_b128 v[246:249], v212 offset:7168
	global_load_lds_dwordx4 v[200:201], off
	v_lshl_add_u64 v[200:201], v[182:183], 0, s[38:39]
	s_add_i32 m0, s15, 0xe000
	s_nop 0
	global_load_lds_dwordx4 v[200:201], off
	s_waitcnt vmcnt(8)
	s_waitcnt lgkmcnt(0)
	s_barrier
	s_setprio 1
	v_mfma_f32_16x16x128_f8f6f4 v[160:163], v[28:35], v[190:197], v[160:163]
	v_mfma_f32_16x16x128_f8f6f4 v[156:159], v[20:27], v[190:197], v[156:159]
	v_mfma_f32_16x16x128_f8f6f4 v[148:151], v[28:35], v[226:233], v[148:151]
	v_mfma_f32_16x16x128_f8f6f4 v[140:143], v[20:27], v[226:233], v[140:143]
	v_mfma_f32_16x16x128_f8f6f4 v[132:135], v[28:35], v[234:241], v[132:135]
	v_mfma_f32_16x16x128_f8f6f4 v[124:127], v[20:27], v[234:241], v[124:127]
	v_mfma_f32_16x16x128_f8f6f4 v[116:119], v[28:35], v[242:249], v[116:119]
	v_mfma_f32_16x16x128_f8f6f4 v[108:111], v[20:27], v[242:249], v[108:111]
	v_mfma_f32_16x16x128_f8f6f4 v[152:155], v[12:19], v[190:197], v[152:155]
	v_mfma_f32_16x16x128_f8f6f4 v[144:147], v[4:11], v[190:197], v[144:147]
	v_mfma_f32_16x16x128_f8f6f4 v[136:139], v[12:19], v[226:233], v[136:139]
	v_mfma_f32_16x16x128_f8f6f4 v[128:131], v[4:11], v[226:233], v[128:131]
	v_mfma_f32_16x16x128_f8f6f4 v[120:123], v[12:19], v[234:241], v[120:123]
	v_mfma_f32_16x16x128_f8f6f4 v[112:115], v[4:11], v[234:241], v[112:115]
	v_mfma_f32_16x16x128_f8f6f4 v[104:107], v[12:19], v[242:249], v[104:107]
	v_mfma_f32_16x16x128_f8f6f4 v[100:103], v[4:11], v[242:249], v[100:103]
	s_setprio 0
	s_barrier
; #define PG8_STAGE(bufoff, gbase, voff) do { _Pragma("unroll") for (int _i = 0; _i < 2; ++_i) \
;         __builtin_amdgcn_global_load_lds((const unsigned*)((const char*)(gbase) + (voff)[_i]), (LAS unsigned*)(lds + (bufoff) + ldsw + _i * 8192), 16, 0, 0); } while (0)
; #define PG8_LDA(dst, b, h) do { _Pragma("unroll") for (int m = 0; m < 4; ++m) _Pragma("unroll") for (int k = 0; k < 2; ++k) dst[m][k] = *(const LAS bf16x8*)(lds + PG8_SA(b, h) + aoff + m * 2048 + k * 1024); } while (0)
; #define PG8_LDB(dst, b, h) do { _Pragma("unroll") for (int n = 0; n < 2; ++n) _Pragma("unroll") for (int k = 0; k < 2; ++k) dst[n][k] = *(const LAS bf16x8*)(lds + PG8_SB(b, h) + boff + n * 2048 + k * 1024); } while (0)
; #define PG8_WAIT_V(n) asm volatile("s_waitcnt vmcnt(" #n ")" ::: "memory")
; #define PG8_WAIT_L(n) asm volatile("s_waitcnt lgkmcnt(" #n ")" ::: "memory")
; #define PG8_BAR __builtin_amdgcn_s_barrier()
; #define PG8_SCHED __builtin_amdgcn_sched_barrier(0)
;     ...
;             PG8_WAIT_V(8); PG8_WAIT_L(0); PG8_BAR; PG8_MMA(0, 0, At, B0); PG8_MMA(0, 1, At, B1); PG8_BAR; PG8_SCHED;
;             PG8_LDA(At, 0, 1); PG8_STAGE(PG8_SB(0, 0), b2, voffB); PG8_STAGE(PG8_SB(0, 1), b2 + hstepB, voffB); PG8_STAGE(PG8_SA(0, 0), a2, voffA);
;             PG8_WAIT_V(8); PG8_WAIT_L(0); PG8_BAR; PG8_MMA(1, 0, At, B0); PG8_MMA(1, 1, At, B1); PG8_BAR; PG8_SCHED;
;             PG8_LDB(B0, 1, 0); PG8_LDB(B1, 1, 1); PG8_SCHED; PG8_LDA(At, 1, 0); PG8_STAGE(PG8_SA(0, 1), a2 + hstepA, voffA);
;             PG8_WAIT_V(8); PG8_WAIT_L(0); PG8_BAR; PG8_MMA(0, 0, At, B0); PG8_MMA(0, 1, At, B1); PG8_BAR; PG8_SCHED;
	s_add_i32 s63, s63, s8
	v_lshl_add_u64 v[190:191], v[198:199], 0, v[2:3]
	s_mov_b32 m0, s63
	ds_read_b128 v[226:229], v212 offset:16384
	ds_read_b128 v[230:233], v212 offset:17408
	ds_read_b128 v[234:237], v212 offset:18432
	ds_read_b128 v[238:241], v212 offset:19456
	ds_read_b128 v[242:245], v212 offset:20480
	ds_read_b128 v[246:249], v212 offset:21504
	ds_read_b128 v[214:217], v212 offset:22528
	ds_read_b128 v[218:221], v212 offset:23552
	global_load_lds_dwordx4 v[190:191], off
	v_lshl_add_u64 v[192:193], v[198:199], 0, v[166:167]
	s_add_i32 m0, s63, 0x2000
	v_lshl_add_u64 v[196:197], v[198:199], 0, v[164:165]
	s_add_i32 s63, s64, s8
	global_load_lds_dwordx4 v[192:193], off
	v_lshl_add_u64 v[194:195], v[196:197], 0, v[2:3]
	s_mov_b32 m0, s63
	v_lshl_add_u64 v[196:197], v[196:197], 0, v[166:167]
	global_load_lds_dwordx4 v[194:195], off
	s_add_i32 m0, s63, 0x2000
	v_lshl_add_u64 v[198:199], v[188:189], 0, v[170:171]
	global_load_lds_dwordx4 v[196:197], off
	s_mov_b32 m0, s15
	v_lshl_add_u64 v[200:201], v[188:189], 0, v[168:169]
	global_load_lds_dwordx4 v[198:199], off
	s_mov_b32 m0, s33
	s_nop 0
	global_load_lds_dwordx4 v[200:201], off
	s_waitcnt vmcnt(8)
	s_waitcnt lgkmcnt(0)
	s_barrier
	s_setprio 1
	v_mfma_f32_16x16x128_f8f6f4 v[96:99], v[28:35], v[226:233], v[96:99]
	v_mfma_f32_16x16x128_f8f6f4 v[92:95], v[20:27], v[226:233], v[92:95]
	v_mfma_f32_16x16x128_f8f6f4 v[84:87], v[28:35], v[234:241], v[84:87]
	v_mfma_f32_16x16x128_f8f6f4 v[76:79], v[20:27], v[234:241], v[76:79]
	v_mfma_f32_16x16x128_f8f6f4 v[68:71], v[28:35], v[242:249], v[68:71]
	v_mfma_f32_16x16x128_f8f6f4 v[60:63], v[20:27], v[242:249], v[60:63]
	v_mfma_f32_16x16x128_f8f6f4 v[52:55], v[28:35], v[214:221], v[52:55]
	v_mfma_f32_16x16x128_f8f6f4 v[44:47], v[20:27], v[214:221], v[44:47]
	v_mfma_f32_16x16x128_f8f6f4 v[88:91], v[12:19], v[226:233], v[88:91]
	v_mfma_f32_16x16x128_f8f6f4 v[80:83], v[4:11], v[226:233], v[80:83]
	v_mfma_f32_16x16x128_f8f6f4 v[72:75], v[12:19], v[234:241], v[72:75]
	v_mfma_f32_16x16x128_f8f6f4 v[64:67], v[4:11], v[234:241], v[64:67]
	v_mfma_f32_16x16x128_f8f6f4 v[56:59], v[12:19], v[242:249], v[56:59]
	v_mfma_f32_16x16x128_f8f6f4 v[48:51], v[4:11], v[242:249], v[48:51]
	v_mfma_f32_16x16x128_f8f6f4 v[40:43], v[12:19], v[214:221], v[40:43]
	v_mfma_f32_16x16x128_f8f6f4 v[36:39], v[4:11], v[214:221], v[36:39]
	s_setprio 0
	s_barrier
	s_add_i32 s63, 0, 0x18000
	s_add_i32 s64, 0, 0x1c000
	ds_read_b128 v[4:7], v206
	ds_read_b128 v[8:11], v206 offset:1024
	ds_read_b128 v[12:15], v206 offset:2048
	ds_read_b128 v[16:19], v206 offset:3072
	ds_read_b128 v[20:23], v207
	ds_read_b128 v[24:27], v207 offset:1024
	ds_read_b128 v[28:31], v207 offset:2048
	ds_read_b128 v[32:35], v207 offset:3072
	v_lshl_add_u64 v[188:189], v[188:189], 0, v[0:1]
	s_mov_b32 m0, s44
	v_lshl_add_u64 v[202:203], v[188:189], 0, v[170:171]
	ds_read_b128 v[214:217], v212 offset:32768
	ds_read_b128 v[218:221], v212 offset:33792
	ds_read_b128 v[226:229], v212 offset:34816
	ds_read_b128 v[230:233], v212 offset:35840
	ds_read_b128 v[234:237], v212 offset:36864
	ds_read_b128 v[238:241], v212 offset:37888
	ds_read_b128 v[242:245], v212 offset:38912
	ds_read_b128 v[246:249], v212 offset:39936
	global_load_lds_dwordx4 v[202:203], off
	v_lshl_add_u64 v[188:189], v[188:189], 0, v[168:169]
	s_mov_b32 m0, s45
	s_nop 0
	global_load_lds_dwordx4 v[188:189], off
	s_waitcnt vmcnt(8)
	s_waitcnt lgkmcnt(0)
	s_barrier
; #define PG8_STAGE(bufoff, gbase, voff) do { _Pragma("unroll") for (int _i = 0; _i < 2; ++_i) \
;         __builtin_amdgcn_global_load_lds((const unsigned*)((const char*)(gbase) + (voff)[_i]), (LAS unsigned*)(lds + (bufoff) + ldsw + _i * 8192), 16, 0, 0); } while (0)
; #define PG8_LDA(dst, b, h) do { _Pragma("unroll") for (int m = 0; m < 4; ++m) _Pragma("unroll") for (int k = 0; k < 2; ++k) dst[m][k] = *(const LAS bf16x8*)(lds + PG8_SA(b, h) + aoff + m * 2048 + k * 1024); } while (0)
; #define PG8_WAIT_V(n) asm volatile("s_waitcnt vmcnt(" #n ")" ::: "memory")
; #define PG8_WAIT_L(n) asm volatile("s_waitcnt lgkmcnt(" #n ")" ::: "memory")
; #define PG8_BAR __builtin_amdgcn_s_barrier()
; #define PG8_SCHED __builtin_amdgcn_sched_barrier(0)
;     ...
;             PG8_WAIT_V(8); PG8_WAIT_L(0); PG8_BAR; PG8_MMA(0, 0, At, B0); PG8_MMA(0, 1, At, B1); PG8_BAR; PG8_SCHED;
;             PG8_LDA(At, 1, 1); PG8_STAGE(PG8_SB(1, 0), b3, voffB); PG8_STAGE(PG8_SB(1, 1), b3 + hstepB, voffB); PG8_STAGE(PG8_SA(1, 0), a3, voffA);
;             PG8_WAIT_V(8); PG8_WAIT_L(0); PG8_BAR; PG8_MMA(1, 0, At, B0); PG8_MMA(1, 1, At, B1); PG8_BAR; PG8_SCHED;
	s_setprio 1
	v_mfma_f32_16x16x128_f8f6f4 v[160:163], v[4:11], v[214:221], v[160:163]
	v_mfma_f32_16x16x128_f8f6f4 v[156:159], v[12:19], v[214:221], v[156:159]
	v_mfma_f32_16x16x128_f8f6f4 v[148:151], v[4:11], v[226:233], v[148:151]
	v_mfma_f32_16x16x128_f8f6f4 v[140:143], v[12:19], v[226:233], v[140:143]
	v_mfma_f32_16x16x128_f8f6f4 v[132:135], v[4:11], v[234:241], v[132:135]
	v_mfma_f32_16x16x128_f8f6f4 v[124:127], v[12:19], v[234:241], v[124:127]
	v_mfma_f32_16x16x128_f8f6f4 v[116:119], v[4:11], v[242:249], v[116:119]
	v_mfma_f32_16x16x128_f8f6f4 v[108:111], v[12:19], v[242:249], v[108:111]
	v_mfma_f32_16x16x128_f8f6f4 v[152:155], v[20:27], v[214:221], v[152:155]
	v_mfma_f32_16x16x128_f8f6f4 v[144:147], v[28:35], v[214:221], v[144:147]
	v_mfma_f32_16x16x128_f8f6f4 v[136:139], v[20:27], v[226:233], v[136:139]
	v_mfma_f32_16x16x128_f8f6f4 v[128:131], v[28:35], v[226:233], v[128:131]
	v_mfma_f32_16x16x128_f8f6f4 v[120:123], v[20:27], v[234:241], v[120:123]
	v_mfma_f32_16x16x128_f8f6f4 v[112:115], v[28:35], v[234:241], v[112:115]
	v_mfma_f32_16x16x128_f8f6f4 v[104:107], v[20:27], v[242:249], v[104:107]
	v_mfma_f32_16x16x128_f8f6f4 v[100:103], v[28:35], v[242:249], v[100:103]
	s_setprio 0
	s_barrier
	s_add_i32 s63, s63, s8
	v_lshl_add_u64 v[188:189], v[190:191], 0, s[52:53]
	s_mov_b32 m0, s63
	ds_read_b128 v[214:217], v212 offset:49152
	ds_read_b128 v[218:221], v212 offset:50176
	ds_read_b128 v[226:229], v212 offset:51200
	ds_read_b128 v[230:233], v212 offset:52224
	ds_read_b128 v[234:237], v212 offset:53248
	ds_read_b128 v[238:241], v212 offset:54272
	ds_read_b128 v[242:245], v212 offset:55296
	ds_read_b128 v[246:249], v212 offset:56320
	global_load_lds_dwordx4 v[188:189], off
	v_lshl_add_u64 v[188:189], v[192:193], 0, s[52:53]
	s_add_i32 m0, s63, 0x2000
	s_add_i32 s63, s64, s8
	global_load_lds_dwordx4 v[188:189], off
	v_lshl_add_u64 v[188:189], v[194:195], 0, s[52:53]
	s_mov_b32 m0, s63
	s_nop 0
	global_load_lds_dwordx4 v[188:189], off
	v_lshl_add_u64 v[188:189], v[196:197], 0, s[52:53]
	s_add_i32 m0, s63, 0x2000
	s_nop 0
	global_load_lds_dwordx4 v[188:189], off
	v_lshl_add_u64 v[188:189], v[198:199], 0, s[52:53]
	s_mov_b32 m0, s46
	s_nop 0
	global_load_lds_dwordx4 v[188:189], off
	v_lshl_add_u64 v[188:189], v[200:201], 0, s[52:53]
	s_mov_b32 m0, s47
	s_nop 0
	global_load_lds_dwordx4 v[188:189], off
	s_waitcnt vmcnt(8)
	s_waitcnt lgkmcnt(0)
	s_barrier
	s_setprio 1
	v_mfma_f32_16x16x128_f8f6f4 v[96:99], v[4:11], v[214:221], v[96:99]
	v_mfma_f32_16x16x128_f8f6f4 v[92:95], v[12:19], v[214:221], v[92:95]
	v_mfma_f32_16x16x128_f8f6f4 v[84:87], v[4:11], v[226:233], v[84:87]
	v_mfma_f32_16x16x128_f8f6f4 v[76:79], v[12:19], v[226:233], v[76:79]
	v_mfma_f32_16x16x128_f8f6f4 v[68:71], v[4:11], v[234:241], v[68:71]
	v_mfma_f32_16x16x128_f8f6f4 v[60:63], v[12:19], v[234:241], v[60:63]
	v_mfma_f32_16x16x128_f8f6f4 v[52:55], v[4:11], v[242:249], v[52:55]
	v_mfma_f32_16x16x128_f8f6f4 v[44:47], v[12:19], v[242:249], v[44:47]
	v_mfma_f32_16x16x128_f8f6f4 v[88:91], v[20:27], v[214:221], v[88:91]
	v_mfma_f32_16x16x128_f8f6f4 v[80:83], v[28:35], v[214:221], v[80:83]
	v_mfma_f32_16x16x128_f8f6f4 v[72:75], v[20:27], v[226:233], v[72:75]
	v_mfma_f32_16x16x128_f8f6f4 v[64:67], v[28:35], v[226:233], v[64:67]
	v_mfma_f32_16x16x128_f8f6f4 v[56:59], v[20:27], v[234:241], v[56:59]
	v_mfma_f32_16x16x128_f8f6f4 v[48:51], v[28:35], v[234:241], v[48:51]
	v_mfma_f32_16x16x128_f8f6f4 v[40:43], v[20:27], v[242:249], v[40:43]
	v_mfma_f32_16x16x128_f8f6f4 v[36:39], v[28:35], v[242:249], v[36:39]
	s_setprio 0
	s_barrier
	s_add_i32 s62, s62, 2
	s_add_u32 s38, s38, 0x100
	s_addc_u32 s39, s39, 0
	s_cmp_gt_u32 s62, 5
	s_cbranch_scc0 .LBB0_440
	s_and_b64 vcc, exec, s[42:43]
	s_cbranch_vccz .LBB0_443
	s_barrier

; #define PG8_STAGE(bufoff, gbase, voff) do { _Pragma("unroll") for (int _i = 0; _i < 2; ++_i) \
;         __builtin_amdgcn_global_load_lds((const unsigned*)((const char*)(gbase) + (voff)[_i]), (LAS unsigned*)(lds + (bufoff) + ldsw + _i * 8192), 16, 0, 0); } while (0)
; #define PG8_LDA(dst, b, h) do { _Pragma("unroll") for (int m = 0; m < 4; ++m) _Pragma("unroll") for (int k = 0; k < 2; ++k) dst[m][k] = *(const LAS bf16x8*)(lds + PG8_SA(b, h) + aoff + m * 2048 + k * 1024); } while (0)
; #define PG8_LDB(dst, b, h) do { _Pragma("unroll") for (int n = 0; n < 2; ++n) _Pragma("unroll") for (int k = 0; k < 2; ++k) dst[n][k] = *(const LAS bf16x8*)(lds + PG8_SB(b, h) + boff + n * 2048 + k * 1024); } while (0)
; #define PG8_WAIT_V(n) asm volatile("s_waitcnt vmcnt(" #n ")" ::: "memory")
; #define PG8_WAIT_L(n) asm volatile("s_waitcnt lgkmcnt(" #n ")" ::: "memory")
; #define PG8_BAR __builtin_amdgcn_s_barrier()
; #define PG8_SCHED __builtin_amdgcn_sched_barrier(0)
;     ...
;             PG8_LDB(B0, 0, 0); PG8_LDB(B1, 0, 1); PG8_SCHED; PG8_LDA(At, 0, 0); PG8_STAGE(PG8_SA(1, 1), a1 + hstepA, voffA);
;             PG8_WAIT_V(8); PG8_WAIT_L(0); PG8_BAR; PG8_MMA(0, 0, At, B0); PG8_MMA(0, 1, At, B1); PG8_BAR; PG8_SCHED;
;     ...
; #pragma unroll
;         for (int a = 0; a < 2; ++a)
; #pragma unroll
;             for (int b = 0; b < 2; ++b)
; #pragma unroll
;                 for (int m = 0; m < 4; ++m)
; #pragma unroll
;                     for (int n = 0; n < 2; ++n) acc[a][b][m][n] = (f32x4){0.f, 0.f, 0.f, 0.f};
.LBB0_782:
	v_lshl_add_u64 v[6:7], v[148:149], 0, s[52:53]
	v_lshl_add_u64 v[154:155], v[4:5], 0, s[4:5]
	v_mov_b32_e32 v4, 0
	v_lshl_add_u64 v[150:151], v[6:7], 0, v[140:141]
	v_lshl_add_u64 v[152:153], v[6:7], 0, v[142:143]
	s_mov_b32 s38, -2
	s_mov_b64 s[28:29], 0
	v_mov_b32_e32 v5, v4
	v_mov_b32_e32 v6, v4
	v_mov_b32_e32 v7, v4
	v_mov_b32_e32 v8, v4
	v_mov_b32_e32 v9, v4
	v_mov_b32_e32 v10, v4
	v_mov_b32_e32 v11, v4
	v_mov_b32_e32 v20, v4
	v_mov_b32_e32 v21, v4
	v_mov_b32_e32 v22, v4
	v_mov_b32_e32 v23, v4
	v_mov_b32_e32 v24, v4
	v_mov_b32_e32 v25, v4
	v_mov_b32_e32 v26, v4
	v_mov_b32_e32 v27, v4
	v_mov_b32_e32 v36, v4
	v_mov_b32_e32 v37, v4
	v_mov_b32_e32 v38, v4
	v_mov_b32_e32 v39, v4
	v_mov_b32_e32 v40, v4
	v_mov_b32_e32 v41, v4
	v_mov_b32_e32 v42, v4
	v_mov_b32_e32 v43, v4
	v_mov_b32_e32 v52, v4
	v_mov_b32_e32 v53, v4
	v_mov_b32_e32 v54, v4
	v_mov_b32_e32 v55, v4
	v_mov_b32_e32 v56, v4
	v_mov_b32_e32 v57, v4
	v_mov_b32_e32 v58, v4
	v_mov_b32_e32 v59, v4
	v_mov_b32_e32 v12, v4
	v_mov_b32_e32 v13, v4
	v_mov_b32_e32 v14, v4
	v_mov_b32_e32 v15, v4
	v_mov_b32_e32 v16, v4
	v_mov_b32_e32 v17, v4
	v_mov_b32_e32 v18, v4
	v_mov_b32_e32 v19, v4
	v_mov_b32_e32 v28, v4
	v_mov_b32_e32 v29, v4
	v_mov_b32_e32 v30, v4
	v_mov_b32_e32 v31, v4
	v_mov_b32_e32 v32, v4
	v_mov_b32_e32 v33, v4
	v_mov_b32_e32 v34, v4
	v_mov_b32_e32 v35, v4
	v_mov_b32_e32 v44, v4
	v_mov_b32_e32 v45, v4
	v_mov_b32_e32 v46, v4
	v_mov_b32_e32 v47, v4
	v_mov_b32_e32 v48, v4
	v_mov_b32_e32 v49, v4
	v_mov_b32_e32 v50, v4
	v_mov_b32_e32 v51, v4
	v_mov_b32_e32 v60, v4
	v_mov_b32_e32 v61, v4
	v_mov_b32_e32 v62, v4
	v_mov_b32_e32 v63, v4
	v_mov_b32_e32 v64, v4
	v_mov_b32_e32 v65, v4
	v_mov_b32_e32 v66, v4
	v_mov_b32_e32 v67, v4
	v_mov_b32_e32 v68, v4
	v_mov_b32_e32 v69, v4
	v_mov_b32_e32 v70, v4
	v_mov_b32_e32 v71, v4
	v_mov_b32_e32 v72, v4
	v_mov_b32_e32 v73, v4
	v_mov_b32_e32 v74, v4
	v_mov_b32_e32 v75, v4
	v_mov_b32_e32 v84, v4
	v_mov_b32_e32 v85, v4
	v_mov_b32_e32 v86, v4
	v_mov_b32_e32 v87, v4
	v_mov_b32_e32 v88, v4
	v_mov_b32_e32 v89, v4
	v_mov_b32_e32 v90, v4
	v_mov_b32_e32 v91, v4
	v_mov_b32_e32 v100, v4
	v_mov_b32_e32 v101, v4
	v_mov_b32_e32 v102, v4
	v_mov_b32_e32 v103, v4
	v_mov_b32_e32 v104, v4
	v_mov_b32_e32 v105, v4
	v_mov_b32_e32 v106, v4
	v_mov_b32_e32 v107, v4
	v_mov_b32_e32 v116, v4
	v_mov_b32_e32 v117, v4
	v_mov_b32_e32 v118, v4
	v_mov_b32_e32 v119, v4
	v_mov_b32_e32 v120, v4
	v_mov_b32_e32 v121, v4
	v_mov_b32_e32 v122, v4
	v_mov_b32_e32 v123, v4
	v_mov_b32_e32 v76, v4
	v_mov_b32_e32 v77, v4
	v_mov_b32_e32 v78, v4
	v_mov_b32_e32 v79, v4
	v_mov_b32_e32 v80, v4
	v_mov_b32_e32 v81, v4
	v_mov_b32_e32 v82, v4
	v_mov_b32_e32 v83, v4
	v_mov_b32_e32 v92, v4
	v_mov_b32_e32 v93, v4
	v_mov_b32_e32 v94, v4
	v_mov_b32_e32 v95, v4
	v_mov_b32_e32 v96, v4
	v_mov_b32_e32 v97, v4
	v_mov_b32_e32 v98, v4
	v_mov_b32_e32 v99, v4
	v_mov_b32_e32 v108, v4
	v_mov_b32_e32 v109, v4
	v_mov_b32_e32 v110, v4
	v_mov_b32_e32 v111, v4
	v_mov_b32_e32 v112, v4
	v_mov_b32_e32 v113, v4
	v_mov_b32_e32 v114, v4
	v_mov_b32_e32 v115, v4
	v_mov_b32_e32 v124, v4
	v_mov_b32_e32 v125, v4
	v_mov_b32_e32 v126, v4
	v_mov_b32_e32 v127, v4
	v_mov_b32_e32 v128, v4
	v_mov_b32_e32 v129, v4
	v_mov_b32_e32 v130, v4
	v_mov_b32_e32 v131, v4
	v_add_u32_e32 v246, 0x10000, v157
	v_add_u32_e32 v247, 0x14000, v157
	v_add_u32_e32 v248, 0x18000, v157
	v_add_u32_e32 v249, 0x1c000, v157
.LBB0_783:
	s_add_i32 s39, 0, 0x10000
	s_cmpk_eq_i32 s28, 0xf00
	v_lshl_add_u64 v[160:161], v[148:149], 0, s[28:29]
	s_cselect_b64 vcc, -1, 0
	s_add_i32 s75, 0, 0x14000
	v_lshl_add_u64 v[160:161], v[160:161], 0, s[4:5]
	v_lshl_add_u64 v[176:177], v[154:155], 0, s[28:29]
	v_cndmask_b32_e32 v231, v161, v145, vcc
	v_cndmask_b32_e32 v230, v160, v144, vcc
	ds_read_b128 v[160:163], v246
	ds_read_b128 v[164:167], v246 offset:1024
	ds_read_b128 v[168:171], v246 offset:2048
	ds_read_b128 v[172:175], v246 offset:3072
	v_cndmask_b32_e32 v233, v177, v147, vcc
	v_cndmask_b32_e32 v232, v176, v146, vcc
	ds_read_b128 v[176:179], v247
	ds_read_b128 v[180:183], v247 offset:1024
	ds_read_b128 v[184:187], v247 offset:2048
	ds_read_b128 v[188:191], v247 offset:3072
	v_lshl_add_u64 v[234:235], v[152:153], 0, s[28:29]
	s_add_i32 m0, s33, 0xc000
	ds_read_b128 v[192:195], v159
	ds_read_b128 v[196:199], v159 offset:1024
	ds_read_b128 v[200:203], v159 offset:2048
	ds_read_b128 v[204:207], v159 offset:3072
	ds_read_b128 v[210:213], v159 offset:4096
	ds_read_b128 v[214:217], v159 offset:5120
	ds_read_b128 v[218:221], v159 offset:6144
	ds_read_b128 v[226:229], v159 offset:7168
	global_load_lds_dwordx4 v[234:235], off
	v_lshl_add_u64 v[234:235], v[150:151], 0, s[28:29]
	s_add_i32 m0, s33, 0xe000
	s_nop 0
	global_load_lds_dwordx4 v[234:235], off
	s_waitcnt vmcnt(8)
	s_waitcnt lgkmcnt(0)
	s_barrier
; #define PG8_STAGE(bufoff, gbase, voff) do { _Pragma("unroll") for (int _i = 0; _i < 2; ++_i) \
;         __builtin_amdgcn_global_load_lds((const unsigned*)((const char*)(gbase) + (voff)[_i]), (LAS unsigned*)(lds + (bufoff) + ldsw + _i * 8192), 16, 0, 0); } while (0)
; #define PG8_LDA(dst, b, h) do { _Pragma("unroll") for (int m = 0; m < 4; ++m) _Pragma("unroll") for (int k = 0; k < 2; ++k) dst[m][k] = *(const LAS bf16x8*)(lds + PG8_SA(b, h) + aoff + m * 2048 + k * 1024); } while (0)
; #define PG8_WAIT_V(n) asm volatile("s_waitcnt vmcnt(" #n ")" ::: "memory")
; #define PG8_WAIT_L(n) asm volatile("s_waitcnt lgkmcnt(" #n ")" ::: "memory")
; #define PG8_BAR __builtin_amdgcn_s_barrier()
; #define PG8_SCHED __builtin_amdgcn_sched_barrier(0)
;     ...
;             PG8_WAIT_V(8); PG8_WAIT_L(0); PG8_BAR; PG8_MMA(0, 0, At, B0); PG8_MMA(0, 1, At, B1); PG8_BAR; PG8_SCHED;
;             PG8_LDA(At, 0, 1); PG8_STAGE(PG8_SB(0, 0), b2, voffB); PG8_STAGE(PG8_SB(0, 1), b2 + hstepB, voffB); PG8_STAGE(PG8_SA(0, 0), a2, voffA);
;             PG8_WAIT_V(8); PG8_WAIT_L(0); PG8_BAR; PG8_MMA(1, 0, At, B0); PG8_MMA(1, 1, At, B1); PG8_BAR; PG8_SCHED;
	s_setprio 1
	v_mfma_i32_16x16x64_i8 v[128:131], v[160:163], v[192:195], v[128:131]
	v_mfma_i32_16x16x64_i8 v[124:127], v[168:171], v[192:195], v[124:127]
	v_mfma_i32_16x16x64_i8 v[112:115], v[160:163], v[200:203], v[112:115]
	v_mfma_i32_16x16x64_i8 v[108:111], v[168:171], v[200:203], v[108:111]
	v_mfma_i32_16x16x64_i8 v[96:99], v[160:163], v[210:213], v[96:99]
	v_mfma_i32_16x16x64_i8 v[92:95], v[168:171], v[210:213], v[92:95]
	v_mfma_i32_16x16x64_i8 v[80:83], v[160:163], v[218:221], v[80:83]
	v_mfma_i32_16x16x64_i8 v[76:79], v[168:171], v[218:221], v[76:79]
	v_mfma_i32_16x16x64_i8 v[128:131], v[164:167], v[196:199], v[128:131]
	v_mfma_i32_16x16x64_i8 v[124:127], v[172:175], v[196:199], v[124:127]
	v_mfma_i32_16x16x64_i8 v[112:115], v[164:167], v[204:207], v[112:115]
	v_mfma_i32_16x16x64_i8 v[108:111], v[172:175], v[204:207], v[108:111]
	v_mfma_i32_16x16x64_i8 v[96:99], v[164:167], v[214:217], v[96:99]
	v_mfma_i32_16x16x64_i8 v[92:95], v[172:175], v[214:217], v[92:95]
	v_mfma_i32_16x16x64_i8 v[80:83], v[164:167], v[226:229], v[80:83]
	v_mfma_i32_16x16x64_i8 v[76:79], v[172:175], v[226:229], v[76:79]
	v_mfma_i32_16x16x64_i8 v[120:123], v[176:179], v[192:195], v[120:123]
	v_mfma_i32_16x16x64_i8 v[116:119], v[184:187], v[192:195], v[116:119]
	v_mfma_i32_16x16x64_i8 v[104:107], v[176:179], v[200:203], v[104:107]
	v_mfma_i32_16x16x64_i8 v[100:103], v[184:187], v[200:203], v[100:103]
	v_mfma_i32_16x16x64_i8 v[88:91], v[176:179], v[210:213], v[88:91]
	v_mfma_i32_16x16x64_i8 v[84:87], v[184:187], v[210:213], v[84:87]
	v_mfma_i32_16x16x64_i8 v[72:75], v[176:179], v[218:221], v[72:75]
	v_mfma_i32_16x16x64_i8 v[68:71], v[184:187], v[218:221], v[68:71]
	v_mfma_i32_16x16x64_i8 v[120:123], v[180:183], v[196:199], v[120:123]
	v_mfma_i32_16x16x64_i8 v[116:119], v[188:191], v[196:199], v[116:119]
	v_mfma_i32_16x16x64_i8 v[104:107], v[180:183], v[204:207], v[104:107]
	v_mfma_i32_16x16x64_i8 v[100:103], v[188:191], v[204:207], v[100:103]
	v_mfma_i32_16x16x64_i8 v[88:91], v[180:183], v[214:217], v[88:91]
	v_mfma_i32_16x16x64_i8 v[84:87], v[188:191], v[214:217], v[84:87]
	v_mfma_i32_16x16x64_i8 v[72:75], v[180:183], v[226:229], v[72:75]
	v_mfma_i32_16x16x64_i8 v[68:71], v[188:191], v[226:229], v[68:71]
	s_setprio 0
	s_barrier
	s_add_i32 s39, s39, s15
	v_lshl_add_u64 v[234:235], v[232:233], 0, v[2:3]
	s_mov_b32 m0, s39
	ds_read_b128 v[192:195], v159 offset:16384
	ds_read_b128 v[196:199], v159 offset:17408
	ds_read_b128 v[200:203], v159 offset:18432
	ds_read_b128 v[204:207], v159 offset:19456
	ds_read_b128 v[210:213], v159 offset:20480
	ds_read_b128 v[214:217], v159 offset:21504
	ds_read_b128 v[218:221], v159 offset:22528
	ds_read_b128 v[226:229], v159 offset:23552
	global_load_lds_dwordx4 v[234:235], off
	v_lshl_add_u64 v[236:237], v[232:233], 0, v[134:135]
	s_add_i32 m0, s39, 0x2000
	v_lshl_add_u64 v[232:233], v[232:233], 0, v[138:139]
	s_add_i32 s39, s75, s15
	global_load_lds_dwordx4 v[236:237], off
	v_lshl_add_u64 v[238:239], v[232:233], 0, v[2:3]
	s_mov_b32 m0, s39
	v_lshl_add_u64 v[232:233], v[232:233], 0, v[134:135]
	global_load_lds_dwordx4 v[238:239], off
	s_add_i32 m0, s39, 0x2000
	v_lshl_add_u64 v[240:241], v[230:231], 0, v[0:1]
	global_load_lds_dwordx4 v[232:233], off
	s_mov_b32 m0, s33
	v_lshl_add_u64 v[242:243], v[230:231], 0, v[132:133]
	global_load_lds_dwordx4 v[240:241], off
	s_mov_b32 m0, s57
	s_nop 0
	global_load_lds_dwordx4 v[242:243], off
	s_waitcnt vmcnt(8)
	s_waitcnt lgkmcnt(0)
	s_barrier
	s_setprio 1
	v_mfma_i32_16x16x64_i8 v[64:67], v[160:163], v[192:195], v[64:67]
	v_mfma_i32_16x16x64_i8 v[60:63], v[168:171], v[192:195], v[60:63]
	v_mfma_i32_16x16x64_i8 v[48:51], v[160:163], v[200:203], v[48:51]
	v_mfma_i32_16x16x64_i8 v[44:47], v[168:171], v[200:203], v[44:47]
	v_mfma_i32_16x16x64_i8 v[32:35], v[160:163], v[210:213], v[32:35]
	v_mfma_i32_16x16x64_i8 v[28:31], v[168:171], v[210:213], v[28:31]
	v_mfma_i32_16x16x64_i8 v[16:19], v[160:163], v[218:221], v[16:19]
	v_mfma_i32_16x16x64_i8 v[12:15], v[168:171], v[218:221], v[12:15]
	v_mfma_i32_16x16x64_i8 v[64:67], v[164:167], v[196:199], v[64:67]
	v_mfma_i32_16x16x64_i8 v[60:63], v[172:175], v[196:199], v[60:63]
	v_mfma_i32_16x16x64_i8 v[48:51], v[164:167], v[204:207], v[48:51]
	v_mfma_i32_16x16x64_i8 v[44:47], v[172:175], v[204:207], v[44:47]
	v_mfma_i32_16x16x64_i8 v[32:35], v[164:167], v[214:217], v[32:35]
	v_mfma_i32_16x16x64_i8 v[28:31], v[172:175], v[214:217], v[28:31]
	v_mfma_i32_16x16x64_i8 v[16:19], v[164:167], v[226:229], v[16:19]
	v_mfma_i32_16x16x64_i8 v[12:15], v[172:175], v[226:229], v[12:15]
	v_mfma_i32_16x16x64_i8 v[56:59], v[176:179], v[192:195], v[56:59]
	v_mfma_i32_16x16x64_i8 v[52:55], v[184:187], v[192:195], v[52:55]
	v_mfma_i32_16x16x64_i8 v[40:43], v[176:179], v[200:203], v[40:43]
	v_mfma_i32_16x16x64_i8 v[36:39], v[184:187], v[200:203], v[36:39]
	v_mfma_i32_16x16x64_i8 v[24:27], v[176:179], v[210:213], v[24:27]
	v_mfma_i32_16x16x64_i8 v[20:23], v[184:187], v[210:213], v[20:23]
	v_mfma_i32_16x16x64_i8 v[8:11], v[176:179], v[218:221], v[8:11]
	v_mfma_i32_16x16x64_i8 v[4:7], v[184:187], v[218:221], v[4:7]
	v_mfma_i32_16x16x64_i8 v[56:59], v[180:183], v[196:199], v[56:59]
	v_mfma_i32_16x16x64_i8 v[52:55], v[188:191], v[196:199], v[52:55]
	v_mfma_i32_16x16x64_i8 v[40:43], v[180:183], v[204:207], v[40:43]
	v_mfma_i32_16x16x64_i8 v[36:39], v[188:191], v[204:207], v[36:39]
	v_mfma_i32_16x16x64_i8 v[24:27], v[180:183], v[214:217], v[24:27]
	v_mfma_i32_16x16x64_i8 v[20:23], v[188:191], v[214:217], v[20:23]
	v_mfma_i32_16x16x64_i8 v[8:11], v[180:183], v[226:229], v[8:11]
	v_mfma_i32_16x16x64_i8 v[4:7], v[188:191], v[226:229], v[4:7]
	s_setprio 0
	s_barrier
; #define PG8_STAGE(bufoff, gbase, voff) do { _Pragma("unroll") for (int _i = 0; _i < 2; ++_i) \
;         __builtin_amdgcn_global_load_lds((const unsigned*)((const char*)(gbase) + (voff)[_i]), (LAS unsigned*)(lds + (bufoff) + ldsw + _i * 8192), 16, 0, 0); } while (0)
; #define PG8_LDA(dst, b, h) do { _Pragma("unroll") for (int m = 0; m < 4; ++m) _Pragma("unroll") for (int k = 0; k < 2; ++k) dst[m][k] = *(const LAS bf16x8*)(lds + PG8_SA(b, h) + aoff + m * 2048 + k * 1024); } while (0)
; #define PG8_LDB(dst, b, h) do { _Pragma("unroll") for (int n = 0; n < 2; ++n) _Pragma("unroll") for (int k = 0; k < 2; ++k) dst[n][k] = *(const LAS bf16x8*)(lds + PG8_SB(b, h) + boff + n * 2048 + k * 1024); } while (0)
; #define PG8_WAIT_V(n) asm volatile("s_waitcnt vmcnt(" #n ")" ::: "memory")
; #define PG8_WAIT_L(n) asm volatile("s_waitcnt lgkmcnt(" #n ")" ::: "memory")
; #define PG8_BAR __builtin_amdgcn_s_barrier()
; #define PG8_SCHED __builtin_amdgcn_sched_barrier(0)
;     ...
;             PG8_LDB(B0, 1, 0); PG8_LDB(B1, 1, 1); PG8_SCHED; PG8_LDA(At, 1, 0); PG8_STAGE(PG8_SA(0, 1), a2 + hstepA, voffA);
;             PG8_WAIT_V(8); PG8_WAIT_L(0); PG8_BAR; PG8_MMA(0, 0, At, B0); PG8_MMA(0, 1, At, B1); PG8_BAR; PG8_SCHED;
;             PG8_LDA(At, 1, 1); PG8_STAGE(PG8_SB(1, 0), b3, voffB); PG8_STAGE(PG8_SB(1, 1), b3 + hstepB, voffB); PG8_STAGE(PG8_SA(1, 0), a3, voffA);
;             PG8_WAIT_V(8); PG8_WAIT_L(0); PG8_BAR; PG8_MMA(1, 0, At, B0); PG8_MMA(1, 1, At, B1); PG8_BAR; PG8_SCHED;
	s_add_i32 s39, 0, 0x18000
	s_add_i32 s75, 0, 0x1c000
	ds_read_b128 v[160:163], v248
	ds_read_b128 v[164:167], v248 offset:1024
	ds_read_b128 v[168:171], v248 offset:2048
	ds_read_b128 v[172:175], v248 offset:3072
	ds_read_b128 v[176:179], v249
	ds_read_b128 v[180:183], v249 offset:1024
	ds_read_b128 v[184:187], v249 offset:2048
	ds_read_b128 v[188:191], v249 offset:3072
	v_lshl_add_u64 v[230:231], v[230:231], 0, v[136:137]
	s_mov_b32 m0, s62
	v_lshl_add_u64 v[244:245], v[230:231], 0, v[0:1]
	ds_read_b128 v[192:195], v159 offset:32768
	ds_read_b128 v[196:199], v159 offset:33792
	ds_read_b128 v[200:203], v159 offset:34816
	ds_read_b128 v[204:207], v159 offset:35840
	ds_read_b128 v[210:213], v159 offset:36864
	ds_read_b128 v[214:217], v159 offset:37888
	ds_read_b128 v[218:221], v159 offset:38912
	ds_read_b128 v[226:229], v159 offset:39936
	global_load_lds_dwordx4 v[244:245], off
	v_lshl_add_u64 v[230:231], v[230:231], 0, v[132:133]
	s_mov_b32 m0, s63
	s_nop 0
	global_load_lds_dwordx4 v[230:231], off
	s_waitcnt vmcnt(8)
	s_waitcnt lgkmcnt(0)
	s_barrier
	s_setprio 1
	v_mfma_i32_16x16x64_i8 v[128:131], v[160:163], v[192:195], v[128:131]
	v_mfma_i32_16x16x64_i8 v[124:127], v[168:171], v[192:195], v[124:127]
	v_mfma_i32_16x16x64_i8 v[112:115], v[160:163], v[200:203], v[112:115]
	v_mfma_i32_16x16x64_i8 v[108:111], v[168:171], v[200:203], v[108:111]
	v_mfma_i32_16x16x64_i8 v[96:99], v[160:163], v[210:213], v[96:99]
	v_mfma_i32_16x16x64_i8 v[92:95], v[168:171], v[210:213], v[92:95]
	v_mfma_i32_16x16x64_i8 v[80:83], v[160:163], v[218:221], v[80:83]
	v_mfma_i32_16x16x64_i8 v[76:79], v[168:171], v[218:221], v[76:79]
	v_mfma_i32_16x16x64_i8 v[128:131], v[164:167], v[196:199], v[128:131]
	v_mfma_i32_16x16x64_i8 v[124:127], v[172:175], v[196:199], v[124:127]
	v_mfma_i32_16x16x64_i8 v[112:115], v[164:167], v[204:207], v[112:115]
	v_mfma_i32_16x16x64_i8 v[108:111], v[172:175], v[204:207], v[108:111]
	v_mfma_i32_16x16x64_i8 v[96:99], v[164:167], v[214:217], v[96:99]
	v_mfma_i32_16x16x64_i8 v[92:95], v[172:175], v[214:217], v[92:95]
	v_mfma_i32_16x16x64_i8 v[80:83], v[164:167], v[226:229], v[80:83]
	v_mfma_i32_16x16x64_i8 v[76:79], v[172:175], v[226:229], v[76:79]
	v_mfma_i32_16x16x64_i8 v[120:123], v[176:179], v[192:195], v[120:123]
	v_mfma_i32_16x16x64_i8 v[116:119], v[184:187], v[192:195], v[116:119]
	v_mfma_i32_16x16x64_i8 v[104:107], v[176:179], v[200:203], v[104:107]
	v_mfma_i32_16x16x64_i8 v[100:103], v[184:187], v[200:203], v[100:103]
	v_mfma_i32_16x16x64_i8 v[88:91], v[176:179], v[210:213], v[88:91]
	v_mfma_i32_16x16x64_i8 v[84:87], v[184:187], v[210:213], v[84:87]
	v_mfma_i32_16x16x64_i8 v[72:75], v[176:179], v[218:221], v[72:75]
	v_mfma_i32_16x16x64_i8 v[68:71], v[184:187], v[218:221], v[68:71]
	v_mfma_i32_16x16x64_i8 v[120:123], v[180:183], v[196:199], v[120:123]
	v_mfma_i32_16x16x64_i8 v[116:119], v[188:191], v[196:199], v[116:119]
	v_mfma_i32_16x16x64_i8 v[104:107], v[180:183], v[204:207], v[104:107]
	v_mfma_i32_16x16x64_i8 v[100:103], v[188:191], v[204:207], v[100:103]
	v_mfma_i32_16x16x64_i8 v[88:91], v[180:183], v[214:217], v[88:91]
	v_mfma_i32_16x16x64_i8 v[84:87], v[188:191], v[214:217], v[84:87]
	v_mfma_i32_16x16x64_i8 v[72:75], v[180:183], v[226:229], v[72:75]
	v_mfma_i32_16x16x64_i8 v[68:71], v[188:191], v[226:229], v[68:71]
	s_setprio 0
	s_barrier
	s_add_i32 s39, s39, s15
	v_lshl_add_u64 v[230:231], v[234:235], 0, s[52:53]
	s_mov_b32 m0, s39
	ds_read_b128 v[192:195], v159 offset:49152
	ds_read_b128 v[196:199], v159 offset:50176
	ds_read_b128 v[200:203], v159 offset:51200
	ds_read_b128 v[204:207], v159 offset:52224
	ds_read_b128 v[210:213], v159 offset:53248
	ds_read_b128 v[214:217], v159 offset:54272
	ds_read_b128 v[218:221], v159 offset:55296
	ds_read_b128 v[226:229], v159 offset:56320
	global_load_lds_dwordx4 v[230:231], off
	v_lshl_add_u64 v[230:231], v[236:237], 0, s[52:53]
	s_add_i32 m0, s39, 0x2000
	s_add_i32 s39, s75, s15
	global_load_lds_dwordx4 v[230:231], off
	v_lshl_add_u64 v[230:231], v[238:239], 0, s[52:53]
	s_mov_b32 m0, s39
	s_nop 0
	global_load_lds_dwordx4 v[230:231], off
	v_lshl_add_u64 v[230:231], v[232:233], 0, s[52:53]
	s_add_i32 m0, s39, 0x2000
	s_nop 0
	global_load_lds_dwordx4 v[230:231], off
	v_lshl_add_u64 v[230:231], v[240:241], 0, s[52:53]
	s_mov_b32 m0, s64
	s_nop 0
	global_load_lds_dwordx4 v[230:231], off
	v_lshl_add_u64 v[230:231], v[242:243], 0, s[52:53]
	s_mov_b32 m0, s65
	s_nop 0
	global_load_lds_dwordx4 v[230:231], off
	s_waitcnt vmcnt(8)
	s_waitcnt lgkmcnt(0)
	s_barrier
	s_setprio 1
	v_mfma_i32_16x16x64_i8 v[64:67], v[160:163], v[192:195], v[64:67]
	v_mfma_i32_16x16x64_i8 v[60:63], v[168:171], v[192:195], v[60:63]
	v_mfma_i32_16x16x64_i8 v[48:51], v[160:163], v[200:203], v[48:51]
	v_mfma_i32_16x16x64_i8 v[44:47], v[168:171], v[200:203], v[44:47]
	v_mfma_i32_16x16x64_i8 v[32:35], v[160:163], v[210:213], v[32:35]
	v_mfma_i32_16x16x64_i8 v[28:31], v[168:171], v[210:213], v[28:31]
	v_mfma_i32_16x16x64_i8 v[16:19], v[160:163], v[218:221], v[16:19]
	v_mfma_i32_16x16x64_i8 v[12:15], v[168:171], v[218:221], v[12:15]
	v_mfma_i32_16x16x64_i8 v[64:67], v[164:167], v[196:199], v[64:67]
	v_mfma_i32_16x16x64_i8 v[60:63], v[172:175], v[196:199], v[60:63]
	v_mfma_i32_16x16x64_i8 v[48:51], v[164:167], v[204:207], v[48:51]
	v_mfma_i32_16x16x64_i8 v[44:47], v[172:175], v[204:207], v[44:47]
	v_mfma_i32_16x16x64_i8 v[32:35], v[164:167], v[214:217], v[32:35]
	v_mfma_i32_16x16x64_i8 v[28:31], v[172:175], v[214:217], v[28:31]
	v_mfma_i32_16x16x64_i8 v[16:19], v[164:167], v[226:229], v[16:19]
	v_mfma_i32_16x16x64_i8 v[12:15], v[172:175], v[226:229], v[12:15]
	v_mfma_i32_16x16x64_i8 v[56:59], v[176:179], v[192:195], v[56:59]
	v_mfma_i32_16x16x64_i8 v[52:55], v[184:187], v[192:195], v[52:55]
	v_mfma_i32_16x16x64_i8 v[40:43], v[176:179], v[200:203], v[40:43]
	v_mfma_i32_16x16x64_i8 v[36:39], v[184:187], v[200:203], v[36:39]
	v_mfma_i32_16x16x64_i8 v[24:27], v[176:179], v[210:213], v[24:27]
	v_mfma_i32_16x16x64_i8 v[20:23], v[184:187], v[210:213], v[20:23]
	v_mfma_i32_16x16x64_i8 v[8:11], v[176:179], v[218:221], v[8:11]
	v_mfma_i32_16x16x64_i8 v[4:7], v[184:187], v[218:221], v[4:7]
	v_mfma_i32_16x16x64_i8 v[56:59], v[180:183], v[196:199], v[56:59]
	v_mfma_i32_16x16x64_i8 v[52:55], v[188:191], v[196:199], v[52:55]
	v_mfma_i32_16x16x64_i8 v[40:43], v[180:183], v[204:207], v[40:43]
	v_mfma_i32_16x16x64_i8 v[36:39], v[188:191], v[204:207], v[36:39]
	v_mfma_i32_16x16x64_i8 v[24:27], v[180:183], v[214:217], v[24:27]
	v_mfma_i32_16x16x64_i8 v[20:23], v[188:191], v[214:217], v[20:23]
	v_mfma_i32_16x16x64_i8 v[8:11], v[180:183], v[226:229], v[8:11]
	v_mfma_i32_16x16x64_i8 v[4:7], v[188:191], v[226:229], v[4:7]
	s_setprio 0
	s_barrier
	s_add_i32 s38, s38, 2
	s_add_u32 s28, s28, 0x100
	s_addc_u32 s29, s29, 0
	s_cmp_gt_u32 s38, 29
	s_cbranch_scc0 .LBB0_783
	s_and_b64 vcc, exec, s[60:61]
	s_cbranch_vccz .LBB0_786
	s_barrier

; #define PG8_STAGE(bufoff, gbase, voff) do { _Pragma("unroll") for (int _i = 0; _i < 2; ++_i) \
;         __builtin_amdgcn_global_load_lds((const unsigned*)((const char*)(gbase) + (voff)[_i]), (LAS unsigned*)(lds + (bufoff) + ldsw + _i * 8192), 16, 0, 0); } while (0)
; #define PG8_LDA(dst, b, h) do { _Pragma("unroll") for (int m = 0; m < 4; ++m) _Pragma("unroll") for (int k = 0; k < 2; ++k) dst[m][k] = *(const LAS bf16x8*)(lds + PG8_SA(b, h) + aoff + m * 2048 + k * 1024); } while (0)
; #define PG8_LDB(dst, b, h) do { _Pragma("unroll") for (int n = 0; n < 2; ++n) _Pragma("unroll") for (int k = 0; k < 2; ++k) dst[n][k] = *(const LAS bf16x8*)(lds + PG8_SB(b, h) + boff + n * 2048 + k * 1024); } while (0)
; #define PG8_WAIT_V(n) asm volatile("s_waitcnt vmcnt(" #n ")" ::: "memory")
; #define PG8_WAIT_L(n) asm volatile("s_waitcnt lgkmcnt(" #n ")" ::: "memory")
; #define PG8_BAR __builtin_amdgcn_s_barrier()
; #define PG8_SCHED __builtin_amdgcn_sched_barrier(0)
;     ...
;             PG8_LDB(B0, 0, 0); PG8_LDB(B1, 0, 1); PG8_SCHED; PG8_LDA(At, 0, 0); PG8_STAGE(PG8_SA(1, 1), a1 + hstepA, voffA);
;             PG8_WAIT_V(8); PG8_WAIT_L(0); PG8_BAR; PG8_MMA(0, 0, At, B0); PG8_MMA(0, 1, At, B1); PG8_BAR; PG8_SCHED;
;     ...
; #pragma unroll
;         for (int a = 0; a < 2; ++a)
; #pragma unroll
;             for (int b = 0; b < 2; ++b)
; #pragma unroll
;                 for (int m = 0; m < 4; ++m)
; #pragma unroll
;                     for (int n = 0; n < 2; ++n) acc[a][b][m][n] = (f32x4){0.f, 0.f, 0.f, 0.f};
.LBB0_817:
	v_lshl_add_u64 v[6:7], v[180:181], 0, s[52:53]
	v_mov_b32_e32 v36, 0
	v_lshl_add_u64 v[182:183], v[6:7], 0, v[172:173]
	v_lshl_add_u64 v[184:185], v[6:7], 0, v[174:175]
	v_lshl_add_u64 v[186:187], v[4:5], 0, s[4:5]
	s_mov_b32 s42, -2
	s_mov_b64 s[28:29], 0
	v_mov_b32_e32 v37, v36
	v_mov_b32_e32 v38, v36
	v_mov_b32_e32 v39, v36
	v_mov_b32_e32 v40, v36
	v_mov_b32_e32 v41, v36
	v_mov_b32_e32 v42, v36
	v_mov_b32_e32 v43, v36
	v_mov_b32_e32 v52, v36
	v_mov_b32_e32 v53, v36
	v_mov_b32_e32 v54, v36
	v_mov_b32_e32 v55, v36
	v_mov_b32_e32 v56, v36
	v_mov_b32_e32 v57, v36
	v_mov_b32_e32 v58, v36
	v_mov_b32_e32 v59, v36
	v_mov_b32_e32 v68, v36
	v_mov_b32_e32 v69, v36
	v_mov_b32_e32 v70, v36
	v_mov_b32_e32 v71, v36
	v_mov_b32_e32 v72, v36
	v_mov_b32_e32 v73, v36
	v_mov_b32_e32 v74, v36
	v_mov_b32_e32 v75, v36
	v_mov_b32_e32 v84, v36
	v_mov_b32_e32 v85, v36
	v_mov_b32_e32 v86, v36
	v_mov_b32_e32 v87, v36
	v_mov_b32_e32 v88, v36
	v_mov_b32_e32 v89, v36
	v_mov_b32_e32 v90, v36
	v_mov_b32_e32 v91, v36
	v_mov_b32_e32 v44, v36
	v_mov_b32_e32 v45, v36
	v_mov_b32_e32 v46, v36
	v_mov_b32_e32 v47, v36
	v_mov_b32_e32 v48, v36
	v_mov_b32_e32 v49, v36
	v_mov_b32_e32 v50, v36
	v_mov_b32_e32 v51, v36
	v_mov_b32_e32 v60, v36
	v_mov_b32_e32 v61, v36
	v_mov_b32_e32 v62, v36
	v_mov_b32_e32 v63, v36
	v_mov_b32_e32 v64, v36
	v_mov_b32_e32 v65, v36
	v_mov_b32_e32 v66, v36
	v_mov_b32_e32 v67, v36
	v_mov_b32_e32 v76, v36
	v_mov_b32_e32 v77, v36
	v_mov_b32_e32 v78, v36
	v_mov_b32_e32 v79, v36
	v_mov_b32_e32 v80, v36
	v_mov_b32_e32 v81, v36
	v_mov_b32_e32 v82, v36
	v_mov_b32_e32 v83, v36
	v_mov_b32_e32 v92, v36
	v_mov_b32_e32 v93, v36
	v_mov_b32_e32 v94, v36
	v_mov_b32_e32 v95, v36
	v_mov_b32_e32 v96, v36
	v_mov_b32_e32 v97, v36
	v_mov_b32_e32 v98, v36
	v_mov_b32_e32 v99, v36
	v_mov_b32_e32 v100, v36
	v_mov_b32_e32 v101, v36
	v_mov_b32_e32 v102, v36
	v_mov_b32_e32 v103, v36
	v_mov_b32_e32 v104, v36
	v_mov_b32_e32 v105, v36
	v_mov_b32_e32 v106, v36
	v_mov_b32_e32 v107, v36
	v_mov_b32_e32 v116, v36
	v_mov_b32_e32 v117, v36
	v_mov_b32_e32 v118, v36
	v_mov_b32_e32 v119, v36
	v_mov_b32_e32 v120, v36
	v_mov_b32_e32 v121, v36
	v_mov_b32_e32 v122, v36
	v_mov_b32_e32 v123, v36
	v_mov_b32_e32 v132, v36
	v_mov_b32_e32 v133, v36
	v_mov_b32_e32 v134, v36
	v_mov_b32_e32 v135, v36
	v_mov_b32_e32 v136, v36
	v_mov_b32_e32 v137, v36
	v_mov_b32_e32 v138, v36
	v_mov_b32_e32 v139, v36
	v_mov_b32_e32 v148, v36
	v_mov_b32_e32 v149, v36
	v_mov_b32_e32 v150, v36
	v_mov_b32_e32 v151, v36
	v_mov_b32_e32 v152, v36
	v_mov_b32_e32 v153, v36
	v_mov_b32_e32 v154, v36
	v_mov_b32_e32 v155, v36
	v_mov_b32_e32 v108, v36
	v_mov_b32_e32 v109, v36
	v_mov_b32_e32 v110, v36
	v_mov_b32_e32 v111, v36
	v_mov_b32_e32 v112, v36
	v_mov_b32_e32 v113, v36
	v_mov_b32_e32 v114, v36
	v_mov_b32_e32 v115, v36
	v_mov_b32_e32 v124, v36
	v_mov_b32_e32 v125, v36
	v_mov_b32_e32 v126, v36
	v_mov_b32_e32 v127, v36
	v_mov_b32_e32 v128, v36
	v_mov_b32_e32 v129, v36
	v_mov_b32_e32 v130, v36
	v_mov_b32_e32 v131, v36
	v_mov_b32_e32 v140, v36
	v_mov_b32_e32 v141, v36
	v_mov_b32_e32 v142, v36
	v_mov_b32_e32 v143, v36
	v_mov_b32_e32 v144, v36
	v_mov_b32_e32 v145, v36
	v_mov_b32_e32 v146, v36
	v_mov_b32_e32 v147, v36
	v_mov_b32_e32 v156, v36
	v_mov_b32_e32 v157, v36
	v_mov_b32_e32 v158, v36
	v_mov_b32_e32 v159, v36
	v_mov_b32_e32 v160, v36
	v_mov_b32_e32 v161, v36
	v_mov_b32_e32 v162, v36
	v_mov_b32_e32 v163, v36
	v_add_u32_e32 v213, 0x10000, v210
	v_add_u32_e32 v250, 0x14000, v210
	v_add_u32_e32 v251, 0x18000, v210
.LBB0_818:
	s_add_i32 s43, 0, 0x10000
	v_lshl_add_u64 v[4:5], v[180:181], 0, s[28:29]
	s_cmpk_eq_i32 s28, 0xf00
	v_lshl_add_u64 v[4:5], v[4:5], 0, s[4:5]
	s_cselect_b64 vcc, -1, 0
	s_add_i32 s75, 0, 0x14000
	v_lshl_add_u64 v[6:7], v[186:187], 0, s[28:29]
	v_cndmask_b32_e32 v188, v4, v176, vcc
	v_cndmask_b32_e32 v189, v5, v177, vcc
	ds_read_b128 v[28:31], v213
	ds_read_b128 v[32:35], v213 offset:1024
	ds_read_b128 v[20:23], v213 offset:2048
	ds_read_b128 v[24:27], v213 offset:3072
	v_cndmask_b32_e32 v207, v7, v179, vcc
	v_cndmask_b32_e32 v206, v6, v178, vcc
	ds_read_b128 v[12:15], v250
	ds_read_b128 v[16:19], v250 offset:1024
	ds_read_b128 v[4:7], v250 offset:2048
	ds_read_b128 v[8:11], v250 offset:3072
	v_lshl_add_u64 v[234:235], v[184:185], 0, s[28:29]
	s_add_i32 m0, s57, 0xc000
	ds_read_b128 v[190:193], v212
	ds_read_b128 v[194:197], v212 offset:1024
	ds_read_b128 v[198:201], v212 offset:2048
	ds_read_b128 v[202:205], v212 offset:3072
	ds_read_b128 v[214:217], v212 offset:4096
	ds_read_b128 v[218:221], v212 offset:5120
	ds_read_b128 v[226:229], v212 offset:6144
	ds_read_b128 v[230:233], v212 offset:7168
	global_load_lds_dwordx4 v[234:235], off
	v_lshl_add_u64 v[234:235], v[182:183], 0, s[28:29]
	s_add_i32 m0, s57, 0xe000
	s_nop 0
	global_load_lds_dwordx4 v[234:235], off
	s_waitcnt vmcnt(8)
	s_waitcnt lgkmcnt(0)
	s_barrier
	s_setprio 1
	v_mfma_f32_16x16x128_f8f6f4 v[160:163], v[28:35], v[190:197], v[160:163]
	v_mfma_f32_16x16x128_f8f6f4 v[156:159], v[20:27], v[190:197], v[156:159]
	v_mfma_f32_16x16x128_f8f6f4 v[144:147], v[28:35], v[198:205], v[144:147]
	v_mfma_f32_16x16x128_f8f6f4 v[140:143], v[20:27], v[198:205], v[140:143]
	v_mfma_f32_16x16x128_f8f6f4 v[128:131], v[28:35], v[214:221], v[128:131]
	v_mfma_f32_16x16x128_f8f6f4 v[124:127], v[20:27], v[214:221], v[124:127]
	v_mfma_f32_16x16x128_f8f6f4 v[112:115], v[28:35], v[226:233], v[112:115]
	v_mfma_f32_16x16x128_f8f6f4 v[108:111], v[20:27], v[226:233], v[108:111]
	v_mfma_f32_16x16x128_f8f6f4 v[152:155], v[12:19], v[190:197], v[152:155]
	v_mfma_f32_16x16x128_f8f6f4 v[148:151], v[4:11], v[190:197], v[148:151]
	v_mfma_f32_16x16x128_f8f6f4 v[136:139], v[12:19], v[198:205], v[136:139]
	v_mfma_f32_16x16x128_f8f6f4 v[132:135], v[4:11], v[198:205], v[132:135]
	v_mfma_f32_16x16x128_f8f6f4 v[120:123], v[12:19], v[214:221], v[120:123]
	v_mfma_f32_16x16x128_f8f6f4 v[116:119], v[4:11], v[214:221], v[116:119]
	v_mfma_f32_16x16x128_f8f6f4 v[104:107], v[12:19], v[226:233], v[104:107]
	v_mfma_f32_16x16x128_f8f6f4 v[100:103], v[4:11], v[226:233], v[100:103]
	s_setprio 0
	s_barrier
; #define PG8_STAGE(bufoff, gbase, voff) do { _Pragma("unroll") for (int _i = 0; _i < 2; ++_i) \
;         __builtin_amdgcn_global_load_lds((const unsigned*)((const char*)(gbase) + (voff)[_i]), (LAS unsigned*)(lds + (bufoff) + ldsw + _i * 8192), 16, 0, 0); } while (0)
; #define PG8_LDA(dst, b, h) do { _Pragma("unroll") for (int m = 0; m < 4; ++m) _Pragma("unroll") for (int k = 0; k < 2; ++k) dst[m][k] = *(const LAS bf16x8*)(lds + PG8_SA(b, h) + aoff + m * 2048 + k * 1024); } while (0)
; #define PG8_LDB(dst, b, h) do { _Pragma("unroll") for (int n = 0; n < 2; ++n) _Pragma("unroll") for (int k = 0; k < 2; ++k) dst[n][k] = *(const LAS bf16x8*)(lds + PG8_SB(b, h) + boff + n * 2048 + k * 1024); } while (0)
; #define PG8_WAIT_V(n) asm volatile("s_waitcnt vmcnt(" #n ")" ::: "memory")
; #define PG8_WAIT_L(n) asm volatile("s_waitcnt lgkmcnt(" #n ")" ::: "memory")
; #define PG8_BAR __builtin_amdgcn_s_barrier()
; #define PG8_SCHED __builtin_amdgcn_sched_barrier(0)
;     ...
;             PG8_WAIT_V(8); PG8_WAIT_L(0); PG8_BAR; PG8_MMA(0, 0, At, B0); PG8_MMA(0, 1, At, B1); PG8_BAR; PG8_SCHED;
;             PG8_LDA(At, 0, 1); PG8_STAGE(PG8_SB(0, 0), b2, voffB); PG8_STAGE(PG8_SB(0, 1), b2 + hstepB, voffB); PG8_STAGE(PG8_SA(0, 0), a2, voffA);
;             PG8_WAIT_V(8); PG8_WAIT_L(0); PG8_BAR; PG8_MMA(1, 0, At, B0); PG8_MMA(1, 1, At, B1); PG8_BAR; PG8_SCHED;
;             PG8_LDB(B0, 1, 0); PG8_LDB(B1, 1, 1); PG8_SCHED; PG8_LDA(At, 1, 0); PG8_STAGE(PG8_SA(0, 1), a2 + hstepA, voffA);
;             PG8_WAIT_V(8); PG8_WAIT_L(0); PG8_BAR; PG8_MMA(0, 0, At, B0); PG8_MMA(0, 1, At, B1); PG8_BAR; PG8_SCHED;
	s_add_i32 s43, s43, s33
	v_lshl_add_u64 v[190:191], v[206:207], 0, v[2:3]
	s_mov_b32 m0, s43
	ds_read_b128 v[214:217], v212 offset:16384
	ds_read_b128 v[218:221], v212 offset:17408
	ds_read_b128 v[226:229], v212 offset:18432
	ds_read_b128 v[230:233], v212 offset:19456
	ds_read_b128 v[234:237], v212 offset:20480
	ds_read_b128 v[238:241], v212 offset:21504
	ds_read_b128 v[242:245], v212 offset:22528
	ds_read_b128 v[246:249], v212 offset:23552
	global_load_lds_dwordx4 v[190:191], off
	v_lshl_add_u64 v[192:193], v[206:207], 0, v[166:167]
	s_add_i32 m0, s43, 0x2000
	v_lshl_add_u64 v[196:197], v[206:207], 0, v[170:171]
	s_add_i32 s43, s75, s33
	global_load_lds_dwordx4 v[192:193], off
	v_lshl_add_u64 v[194:195], v[196:197], 0, v[2:3]
	s_mov_b32 m0, s43
	v_lshl_add_u64 v[196:197], v[196:197], 0, v[166:167]
	global_load_lds_dwordx4 v[194:195], off
	s_add_i32 m0, s43, 0x2000
	v_lshl_add_u64 v[198:199], v[188:189], 0, v[0:1]
	global_load_lds_dwordx4 v[196:197], off
	s_mov_b32 m0, s57
	v_lshl_add_u64 v[200:201], v[188:189], 0, v[164:165]
	global_load_lds_dwordx4 v[198:199], off
	s_mov_b32 m0, s62
	s_nop 0
	global_load_lds_dwordx4 v[200:201], off
	s_waitcnt vmcnt(8)
	s_waitcnt lgkmcnt(0)
	s_barrier
	s_setprio 1
	v_mfma_f32_16x16x128_f8f6f4 v[96:99], v[28:35], v[214:221], v[96:99]
	v_mfma_f32_16x16x128_f8f6f4 v[92:95], v[20:27], v[214:221], v[92:95]
	v_mfma_f32_16x16x128_f8f6f4 v[80:83], v[28:35], v[226:233], v[80:83]
	v_mfma_f32_16x16x128_f8f6f4 v[76:79], v[20:27], v[226:233], v[76:79]
	v_mfma_f32_16x16x128_f8f6f4 v[64:67], v[28:35], v[234:241], v[64:67]
	v_mfma_f32_16x16x128_f8f6f4 v[60:63], v[20:27], v[234:241], v[60:63]
	v_mfma_f32_16x16x128_f8f6f4 v[48:51], v[28:35], v[242:249], v[48:51]
	v_mfma_f32_16x16x128_f8f6f4 v[44:47], v[20:27], v[242:249], v[44:47]
	v_mfma_f32_16x16x128_f8f6f4 v[88:91], v[12:19], v[214:221], v[88:91]
	v_mfma_f32_16x16x128_f8f6f4 v[84:87], v[4:11], v[214:221], v[84:87]
	v_mfma_f32_16x16x128_f8f6f4 v[72:75], v[12:19], v[226:233], v[72:75]
	v_mfma_f32_16x16x128_f8f6f4 v[68:71], v[4:11], v[226:233], v[68:71]
	v_mfma_f32_16x16x128_f8f6f4 v[56:59], v[12:19], v[234:241], v[56:59]
	v_mfma_f32_16x16x128_f8f6f4 v[52:55], v[4:11], v[234:241], v[52:55]
	v_mfma_f32_16x16x128_f8f6f4 v[40:43], v[12:19], v[242:249], v[40:43]
	v_mfma_f32_16x16x128_f8f6f4 v[36:39], v[4:11], v[242:249], v[36:39]
	s_setprio 0
	s_barrier
	s_add_i32 s43, 0, 0x18000
	s_add_i32 s75, 0, 0x1c000
	v_add_u32_e32 v32, s75, v210
	ds_read_b128 v[4:7], v251
	ds_read_b128 v[8:11], v251 offset:1024
	ds_read_b128 v[12:15], v251 offset:2048
	ds_read_b128 v[16:19], v251 offset:3072
	ds_read_b128 v[20:23], v32
	ds_read_b128 v[24:27], v32 offset:1024
	ds_read_b128 v[28:31], v32 offset:2048
	ds_read_b128 v[32:35], v32 offset:3072
	v_lshl_add_u64 v[188:189], v[188:189], 0, v[168:169]
	s_mov_b32 m0, s63
	v_lshl_add_u64 v[202:203], v[188:189], 0, v[0:1]
	ds_read_b128 v[214:217], v212 offset:32768
	ds_read_b128 v[218:221], v212 offset:33792
	ds_read_b128 v[226:229], v212 offset:34816
	ds_read_b128 v[230:233], v212 offset:35840
	ds_read_b128 v[234:237], v212 offset:36864
	ds_read_b128 v[238:241], v212 offset:37888
	ds_read_b128 v[242:245], v212 offset:38912
	ds_read_b128 v[246:249], v212 offset:39936
	global_load_lds_dwordx4 v[202:203], off
	v_lshl_add_u64 v[188:189], v[188:189], 0, v[164:165]
	s_mov_b32 m0, s64
	s_nop 0
	global_load_lds_dwordx4 v[188:189], off
	s_waitcnt vmcnt(8)
	s_waitcnt lgkmcnt(0)
	s_barrier
; #define PG8_STAGE(bufoff, gbase, voff) do { _Pragma("unroll") for (int _i = 0; _i < 2; ++_i) \
;         __builtin_amdgcn_global_load_lds((const unsigned*)((const char*)(gbase) + (voff)[_i]), (LAS unsigned*)(lds + (bufoff) + ldsw + _i * 8192), 16, 0, 0); } while (0)
; #define PG8_LDA(dst, b, h) do { _Pragma("unroll") for (int m = 0; m < 4; ++m) _Pragma("unroll") for (int k = 0; k < 2; ++k) dst[m][k] = *(const LAS bf16x8*)(lds + PG8_SA(b, h) + aoff + m * 2048 + k * 1024); } while (0)
; #define PG8_WAIT_V(n) asm volatile("s_waitcnt vmcnt(" #n ")" ::: "memory")
; #define PG8_WAIT_L(n) asm volatile("s_waitcnt lgkmcnt(" #n ")" ::: "memory")
; #define PG8_BAR __builtin_amdgcn_s_barrier()
; #define PG8_SCHED __builtin_amdgcn_sched_barrier(0)
;     ...
;             PG8_WAIT_V(8); PG8_WAIT_L(0); PG8_BAR; PG8_MMA(0, 0, At, B0); PG8_MMA(0, 1, At, B1); PG8_BAR; PG8_SCHED;
;             PG8_LDA(At, 1, 1); PG8_STAGE(PG8_SB(1, 0), b3, voffB); PG8_STAGE(PG8_SB(1, 1), b3 + hstepB, voffB); PG8_STAGE(PG8_SA(1, 0), a3, voffA);
;             PG8_WAIT_V(8); PG8_WAIT_L(0); PG8_BAR; PG8_MMA(1, 0, At, B0); PG8_MMA(1, 1, At, B1); PG8_BAR; PG8_SCHED;
	s_setprio 1
	v_mfma_f32_16x16x128_f8f6f4 v[160:163], v[4:11], v[214:221], v[160:163]
	v_mfma_f32_16x16x128_f8f6f4 v[156:159], v[12:19], v[214:221], v[156:159]
	v_mfma_f32_16x16x128_f8f6f4 v[144:147], v[4:11], v[226:233], v[144:147]
	v_mfma_f32_16x16x128_f8f6f4 v[140:143], v[12:19], v[226:233], v[140:143]
	v_mfma_f32_16x16x128_f8f6f4 v[128:131], v[4:11], v[234:241], v[128:131]
	v_mfma_f32_16x16x128_f8f6f4 v[124:127], v[12:19], v[234:241], v[124:127]
	v_mfma_f32_16x16x128_f8f6f4 v[112:115], v[4:11], v[242:249], v[112:115]
	v_mfma_f32_16x16x128_f8f6f4 v[108:111], v[12:19], v[242:249], v[108:111]
	v_mfma_f32_16x16x128_f8f6f4 v[152:155], v[20:27], v[214:221], v[152:155]
	v_mfma_f32_16x16x128_f8f6f4 v[148:151], v[28:35], v[214:221], v[148:151]
	v_mfma_f32_16x16x128_f8f6f4 v[136:139], v[20:27], v[226:233], v[136:139]
	v_mfma_f32_16x16x128_f8f6f4 v[132:135], v[28:35], v[226:233], v[132:135]
	v_mfma_f32_16x16x128_f8f6f4 v[120:123], v[20:27], v[234:241], v[120:123]
	v_mfma_f32_16x16x128_f8f6f4 v[116:119], v[28:35], v[234:241], v[116:119]
	v_mfma_f32_16x16x128_f8f6f4 v[104:107], v[20:27], v[242:249], v[104:107]
	v_mfma_f32_16x16x128_f8f6f4 v[100:103], v[28:35], v[242:249], v[100:103]
	s_setprio 0
	s_barrier
	s_add_i32 s43, s43, s33
	v_lshl_add_u64 v[188:189], v[190:191], 0, s[52:53]
	s_mov_b32 m0, s43
	ds_read_b128 v[214:217], v212 offset:49152
	ds_read_b128 v[218:221], v212 offset:50176
	ds_read_b128 v[226:229], v212 offset:51200
	ds_read_b128 v[230:233], v212 offset:52224
	ds_read_b128 v[234:237], v212 offset:53248
	ds_read_b128 v[238:241], v212 offset:54272
	ds_read_b128 v[242:245], v212 offset:55296
	ds_read_b128 v[246:249], v212 offset:56320
	global_load_lds_dwordx4 v[188:189], off
	v_lshl_add_u64 v[188:189], v[192:193], 0, s[52:53]
	s_add_i32 m0, s43, 0x2000
	s_add_i32 s43, s75, s33
	global_load_lds_dwordx4 v[188:189], off
	v_lshl_add_u64 v[188:189], v[194:195], 0, s[52:53]
	s_mov_b32 m0, s43
	s_nop 0
	global_load_lds_dwordx4 v[188:189], off
	v_lshl_add_u64 v[188:189], v[196:197], 0, s[52:53]
	s_add_i32 m0, s43, 0x2000
	s_nop 0
	global_load_lds_dwordx4 v[188:189], off
	v_lshl_add_u64 v[188:189], v[198:199], 0, s[52:53]
	s_mov_b32 m0, s65
	s_nop 0
	global_load_lds_dwordx4 v[188:189], off
	v_lshl_add_u64 v[188:189], v[200:201], 0, s[52:53]
	s_mov_b32 m0, s66
	s_nop 0
	global_load_lds_dwordx4 v[188:189], off
	s_waitcnt vmcnt(8)
	s_waitcnt lgkmcnt(0)
	s_barrier
	s_setprio 1
	v_mfma_f32_16x16x128_f8f6f4 v[96:99], v[4:11], v[214:221], v[96:99]
	v_mfma_f32_16x16x128_f8f6f4 v[92:95], v[12:19], v[214:221], v[92:95]
	v_mfma_f32_16x16x128_f8f6f4 v[80:83], v[4:11], v[226:233], v[80:83]
	v_mfma_f32_16x16x128_f8f6f4 v[76:79], v[12:19], v[226:233], v[76:79]
	v_mfma_f32_16x16x128_f8f6f4 v[64:67], v[4:11], v[234:241], v[64:67]
	v_mfma_f32_16x16x128_f8f6f4 v[60:63], v[12:19], v[234:241], v[60:63]
	v_mfma_f32_16x16x128_f8f6f4 v[48:51], v[4:11], v[242:249], v[48:51]
	v_mfma_f32_16x16x128_f8f6f4 v[44:47], v[12:19], v[242:249], v[44:47]
	v_mfma_f32_16x16x128_f8f6f4 v[88:91], v[20:27], v[214:221], v[88:91]
	v_mfma_f32_16x16x128_f8f6f4 v[84:87], v[28:35], v[214:221], v[84:87]
	v_mfma_f32_16x16x128_f8f6f4 v[72:75], v[20:27], v[226:233], v[72:75]
	v_mfma_f32_16x16x128_f8f6f4 v[68:71], v[28:35], v[226:233], v[68:71]
	v_mfma_f32_16x16x128_f8f6f4 v[56:59], v[20:27], v[234:241], v[56:59]
	v_mfma_f32_16x16x128_f8f6f4 v[52:55], v[28:35], v[234:241], v[52:55]
	v_mfma_f32_16x16x128_f8f6f4 v[40:43], v[20:27], v[242:249], v[40:43]
	v_mfma_f32_16x16x128_f8f6f4 v[36:39], v[28:35], v[242:249], v[36:39]
	s_setprio 0
	s_barrier
	s_add_i32 s42, s42, 2
	s_add_u32 s28, s28, 0x100
	s_addc_u32 s29, s29, 0
	s_cmp_gt_u32 s42, 29
	s_cbranch_scc0 .LBB0_818
	s_and_b64 vcc, exec, s[60:61]
	s_cbranch_vccz .LBB0_821
	s_barrier

; #define PG8_STAGE(bufoff, gbase, voff) do { _Pragma("unroll") for (int _i = 0; _i < 2; ++_i) \
;         __builtin_amdgcn_global_load_lds((const unsigned*)((const char*)(gbase) + (voff)[_i]), (LAS unsigned*)(lds + (bufoff) + ldsw + _i * 8192), 16, 0, 0); } while (0)
; #define PG8_LDA(dst, b, h) do { _Pragma("unroll") for (int m = 0; m < 4; ++m) _Pragma("unroll") for (int k = 0; k < 2; ++k) dst[m][k] = *(const LAS bf16x8*)(lds + PG8_SA(b, h) + aoff + m * 2048 + k * 1024); } while (0)
; #define PG8_LDB(dst, b, h) do { _Pragma("unroll") for (int n = 0; n < 2; ++n) _Pragma("unroll") for (int k = 0; k < 2; ++k) dst[n][k] = *(const LAS bf16x8*)(lds + PG8_SB(b, h) + boff + n * 2048 + k * 1024); } while (0)
; #define PG8_WAIT_V(n) asm volatile("s_waitcnt vmcnt(" #n ")" ::: "memory")
; #define PG8_WAIT_L(n) asm volatile("s_waitcnt lgkmcnt(" #n ")" ::: "memory")
; #define PG8_BAR __builtin_amdgcn_s_barrier()
; #define PG8_SCHED __builtin_amdgcn_sched_barrier(0)
;     ...
;             PG8_LDB(B0, 0, 0); PG8_LDB(B1, 0, 1); PG8_SCHED; PG8_LDA(At, 0, 0); PG8_STAGE(PG8_SA(1, 1), a1 + hstepA, voffA);
;             PG8_WAIT_V(8); PG8_WAIT_L(0); PG8_BAR; PG8_MMA(0, 0, At, B0); PG8_MMA(0, 1, At, B1); PG8_BAR; PG8_SCHED;
;     ...
; #pragma unroll
;         for (int a = 0; a < 2; ++a)
; #pragma unroll
;             for (int b = 0; b < 2; ++b)
; #pragma unroll
;                 for (int m = 0; m < 4; ++m)
; #pragma unroll
;                     for (int n = 0; n < 2; ++n) acc[a][b][m][n] = (f32x4){0.f, 0.f, 0.f, 0.f};
.LBB0_911:
	v_lshl_add_u64 v[6:7], v[148:149], 0, s[52:53]
	v_lshl_add_u64 v[154:155], v[4:5], 0, s[4:5]
	v_mov_b32_e32 v4, 0
	v_lshl_add_u64 v[150:151], v[6:7], 0, v[140:141]
	v_lshl_add_u64 v[152:153], v[6:7], 0, v[142:143]
	s_mov_b32 s58, -2
	s_mov_b64 s[38:39], 0
	v_mov_b32_e32 v5, v4
	v_mov_b32_e32 v6, v4
	v_mov_b32_e32 v7, v4
	v_mov_b32_e32 v8, v4
	v_mov_b32_e32 v9, v4
	v_mov_b32_e32 v10, v4
	v_mov_b32_e32 v11, v4
	v_mov_b32_e32 v12, v4
	v_mov_b32_e32 v13, v4
	v_mov_b32_e32 v14, v4
	v_mov_b32_e32 v15, v4
	v_mov_b32_e32 v16, v4
	v_mov_b32_e32 v17, v4
	v_mov_b32_e32 v18, v4
	v_mov_b32_e32 v19, v4
	v_mov_b32_e32 v20, v4
	v_mov_b32_e32 v21, v4
	v_mov_b32_e32 v22, v4
	v_mov_b32_e32 v23, v4
	v_mov_b32_e32 v24, v4
	v_mov_b32_e32 v25, v4
	v_mov_b32_e32 v26, v4
	v_mov_b32_e32 v27, v4
	v_mov_b32_e32 v28, v4
	v_mov_b32_e32 v29, v4
	v_mov_b32_e32 v30, v4
	v_mov_b32_e32 v31, v4
	v_mov_b32_e32 v32, v4
	v_mov_b32_e32 v33, v4
	v_mov_b32_e32 v34, v4
	v_mov_b32_e32 v35, v4
	v_mov_b32_e32 v36, v4
	v_mov_b32_e32 v37, v4
	v_mov_b32_e32 v38, v4
	v_mov_b32_e32 v39, v4
	v_mov_b32_e32 v40, v4
	v_mov_b32_e32 v41, v4
	v_mov_b32_e32 v42, v4
	v_mov_b32_e32 v43, v4
	v_mov_b32_e32 v44, v4
	v_mov_b32_e32 v45, v4
	v_mov_b32_e32 v46, v4
	v_mov_b32_e32 v47, v4
	v_mov_b32_e32 v48, v4
	v_mov_b32_e32 v49, v4
	v_mov_b32_e32 v50, v4
	v_mov_b32_e32 v51, v4
	v_mov_b32_e32 v52, v4
	v_mov_b32_e32 v53, v4
	v_mov_b32_e32 v54, v4
	v_mov_b32_e32 v55, v4
	v_mov_b32_e32 v56, v4
	v_mov_b32_e32 v57, v4
	v_mov_b32_e32 v58, v4
	v_mov_b32_e32 v59, v4
	v_mov_b32_e32 v60, v4
	v_mov_b32_e32 v61, v4
	v_mov_b32_e32 v62, v4
	v_mov_b32_e32 v63, v4
	v_mov_b32_e32 v64, v4
	v_mov_b32_e32 v65, v4
	v_mov_b32_e32 v66, v4
	v_mov_b32_e32 v67, v4
	v_mov_b32_e32 v68, v4
	v_mov_b32_e32 v69, v4
	v_mov_b32_e32 v70, v4
	v_mov_b32_e32 v71, v4
	v_mov_b32_e32 v72, v4
	v_mov_b32_e32 v73, v4
	v_mov_b32_e32 v74, v4
	v_mov_b32_e32 v75, v4
	v_mov_b32_e32 v76, v4
	v_mov_b32_e32 v77, v4
	v_mov_b32_e32 v78, v4
	v_mov_b32_e32 v79, v4
	v_mov_b32_e32 v80, v4
	v_mov_b32_e32 v81, v4
	v_mov_b32_e32 v82, v4
	v_mov_b32_e32 v83, v4
	v_mov_b32_e32 v84, v4
	v_mov_b32_e32 v85, v4
	v_mov_b32_e32 v86, v4
	v_mov_b32_e32 v87, v4
	v_mov_b32_e32 v88, v4
	v_mov_b32_e32 v89, v4
	v_mov_b32_e32 v90, v4
	v_mov_b32_e32 v91, v4
	v_mov_b32_e32 v92, v4
	v_mov_b32_e32 v93, v4
	v_mov_b32_e32 v94, v4
	v_mov_b32_e32 v95, v4
	v_mov_b32_e32 v96, v4
	v_mov_b32_e32 v97, v4
	v_mov_b32_e32 v98, v4
	v_mov_b32_e32 v99, v4
	v_mov_b32_e32 v100, v4
	v_mov_b32_e32 v101, v4
	v_mov_b32_e32 v102, v4
	v_mov_b32_e32 v103, v4
	v_mov_b32_e32 v104, v4
	v_mov_b32_e32 v105, v4
	v_mov_b32_e32 v106, v4
	v_mov_b32_e32 v107, v4
	v_mov_b32_e32 v108, v4
	v_mov_b32_e32 v109, v4
	v_mov_b32_e32 v110, v4
	v_mov_b32_e32 v111, v4
	v_mov_b32_e32 v112, v4
	v_mov_b32_e32 v113, v4
	v_mov_b32_e32 v114, v4
	v_mov_b32_e32 v115, v4
	v_mov_b32_e32 v116, v4
	v_mov_b32_e32 v117, v4
	v_mov_b32_e32 v118, v4
	v_mov_b32_e32 v119, v4
	v_mov_b32_e32 v120, v4
	v_mov_b32_e32 v121, v4
	v_mov_b32_e32 v122, v4
	v_mov_b32_e32 v123, v4
	v_mov_b32_e32 v124, v4
	v_mov_b32_e32 v125, v4
	v_mov_b32_e32 v126, v4
	v_mov_b32_e32 v127, v4
	v_mov_b32_e32 v128, v4
	v_mov_b32_e32 v129, v4
	v_mov_b32_e32 v130, v4
	v_mov_b32_e32 v131, v4
	v_add_u32_e32 v246, 0x10000, v158
	v_add_u32_e32 v247, 0x14000, v158
	v_add_u32_e32 v248, 0x18000, v158
	v_add_u32_e32 v249, 0x1c000, v158
.LBB0_912:
	s_add_i32 s59, 0, 0x10000
	v_lshl_add_u64 v[162:163], v[148:149], 0, s[38:39]
	s_cmpk_eq_i32 s38, 0xf00
	v_lshl_add_u64 v[162:163], v[162:163], 0, s[4:5]
	s_cselect_b64 vcc, -1, 0
	s_add_i32 s75, 0, 0x14000
	v_lshl_add_u64 v[178:179], v[154:155], 0, s[38:39]
	v_cndmask_b32_e32 v231, v163, v145, vcc
	v_cndmask_b32_e32 v230, v162, v144, vcc
	ds_read_b128 v[162:165], v246
	ds_read_b128 v[166:169], v246 offset:1024
	ds_read_b128 v[170:173], v246 offset:2048
	ds_read_b128 v[174:177], v246 offset:3072
	v_cndmask_b32_e32 v233, v179, v147, vcc
	v_cndmask_b32_e32 v232, v178, v146, vcc
	ds_read_b128 v[178:181], v247
	ds_read_b128 v[182:185], v247 offset:1024
	ds_read_b128 v[186:189], v247 offset:2048
	ds_read_b128 v[190:193], v247 offset:3072
	v_lshl_add_u64 v[234:235], v[152:153], 0, s[38:39]
	s_add_i32 m0, s60, 0xc000
	ds_read_b128 v[194:197], v160
	ds_read_b128 v[198:201], v160 offset:1024
	ds_read_b128 v[202:205], v160 offset:2048
	ds_read_b128 v[206:209], v160 offset:3072
	ds_read_b128 v[210:213], v160 offset:4096
	ds_read_b128 v[214:217], v160 offset:5120
	ds_read_b128 v[218:221], v160 offset:6144
	ds_read_b128 v[226:229], v160 offset:7168
	global_load_lds_dwordx4 v[234:235], off
	v_lshl_add_u64 v[234:235], v[150:151], 0, s[38:39]
	s_add_i32 m0, s60, 0xe000
	s_nop 0
	global_load_lds_dwordx4 v[234:235], off
	s_waitcnt vmcnt(8)
	s_waitcnt lgkmcnt(0)
	s_barrier
; #define PG8_STAGE(bufoff, gbase, voff) do { _Pragma("unroll") for (int _i = 0; _i < 2; ++_i) \
;         __builtin_amdgcn_global_load_lds((const unsigned*)((const char*)(gbase) + (voff)[_i]), (LAS unsigned*)(lds + (bufoff) + ldsw + _i * 8192), 16, 0, 0); } while (0)
; #define PG8_LDA(dst, b, h) do { _Pragma("unroll") for (int m = 0; m < 4; ++m) _Pragma("unroll") for (int k = 0; k < 2; ++k) dst[m][k] = *(const LAS bf16x8*)(lds + PG8_SA(b, h) + aoff + m * 2048 + k * 1024); } while (0)
; #define PG8_WAIT_V(n) asm volatile("s_waitcnt vmcnt(" #n ")" ::: "memory")
; #define PG8_WAIT_L(n) asm volatile("s_waitcnt lgkmcnt(" #n ")" ::: "memory")
; #define PG8_BAR __builtin_amdgcn_s_barrier()
; #define PG8_SCHED __builtin_amdgcn_sched_barrier(0)
;     ...
;             PG8_WAIT_V(8); PG8_WAIT_L(0); PG8_BAR; PG8_MMA(0, 0, At, B0); PG8_MMA(0, 1, At, B1); PG8_BAR; PG8_SCHED;
;             PG8_LDA(At, 0, 1); PG8_STAGE(PG8_SB(0, 0), b2, voffB); PG8_STAGE(PG8_SB(0, 1), b2 + hstepB, voffB); PG8_STAGE(PG8_SA(0, 0), a2, voffA);
;             PG8_WAIT_V(8); PG8_WAIT_L(0); PG8_BAR; PG8_MMA(1, 0, At, B0); PG8_MMA(1, 1, At, B1); PG8_BAR; PG8_SCHED;
	s_setprio 1
	v_mfma_i32_16x16x64_i8 v[128:131], v[162:165], v[194:197], v[128:131]
	v_mfma_i32_16x16x64_i8 v[124:127], v[170:173], v[194:197], v[124:127]
	v_mfma_i32_16x16x64_i8 v[120:123], v[162:165], v[202:205], v[120:123]
	v_mfma_i32_16x16x64_i8 v[116:119], v[170:173], v[202:205], v[116:119]
	v_mfma_i32_16x16x64_i8 v[112:115], v[162:165], v[210:213], v[112:115]
	v_mfma_i32_16x16x64_i8 v[108:111], v[170:173], v[210:213], v[108:111]
	v_mfma_i32_16x16x64_i8 v[104:107], v[162:165], v[218:221], v[104:107]
	v_mfma_i32_16x16x64_i8 v[100:103], v[170:173], v[218:221], v[100:103]
	v_mfma_i32_16x16x64_i8 v[128:131], v[166:169], v[198:201], v[128:131]
	v_mfma_i32_16x16x64_i8 v[124:127], v[174:177], v[198:201], v[124:127]
	v_mfma_i32_16x16x64_i8 v[120:123], v[166:169], v[206:209], v[120:123]
	v_mfma_i32_16x16x64_i8 v[116:119], v[174:177], v[206:209], v[116:119]
	v_mfma_i32_16x16x64_i8 v[112:115], v[166:169], v[214:217], v[112:115]
	v_mfma_i32_16x16x64_i8 v[108:111], v[174:177], v[214:217], v[108:111]
	v_mfma_i32_16x16x64_i8 v[104:107], v[166:169], v[226:229], v[104:107]
	v_mfma_i32_16x16x64_i8 v[100:103], v[174:177], v[226:229], v[100:103]
	v_mfma_i32_16x16x64_i8 v[96:99], v[178:181], v[194:197], v[96:99]
	v_mfma_i32_16x16x64_i8 v[92:95], v[186:189], v[194:197], v[92:95]
	v_mfma_i32_16x16x64_i8 v[88:91], v[178:181], v[202:205], v[88:91]
	v_mfma_i32_16x16x64_i8 v[84:87], v[186:189], v[202:205], v[84:87]
	v_mfma_i32_16x16x64_i8 v[80:83], v[178:181], v[210:213], v[80:83]
	v_mfma_i32_16x16x64_i8 v[76:79], v[186:189], v[210:213], v[76:79]
	v_mfma_i32_16x16x64_i8 v[72:75], v[178:181], v[218:221], v[72:75]
	v_mfma_i32_16x16x64_i8 v[68:71], v[186:189], v[218:221], v[68:71]
	v_mfma_i32_16x16x64_i8 v[96:99], v[182:185], v[198:201], v[96:99]
	v_mfma_i32_16x16x64_i8 v[92:95], v[190:193], v[198:201], v[92:95]
	v_mfma_i32_16x16x64_i8 v[88:91], v[182:185], v[206:209], v[88:91]
	v_mfma_i32_16x16x64_i8 v[84:87], v[190:193], v[206:209], v[84:87]
	v_mfma_i32_16x16x64_i8 v[80:83], v[182:185], v[214:217], v[80:83]
	v_mfma_i32_16x16x64_i8 v[76:79], v[190:193], v[214:217], v[76:79]
	v_mfma_i32_16x16x64_i8 v[72:75], v[182:185], v[226:229], v[72:75]
	v_mfma_i32_16x16x64_i8 v[68:71], v[190:193], v[226:229], v[68:71]
	s_setprio 0
	s_barrier
	s_add_i32 s59, s59, s57
	v_lshl_add_u64 v[234:235], v[232:233], 0, v[2:3]
	s_mov_b32 m0, s59
	ds_read_b128 v[194:197], v160 offset:16384
	ds_read_b128 v[198:201], v160 offset:17408
	ds_read_b128 v[202:205], v160 offset:18432
	ds_read_b128 v[206:209], v160 offset:19456
	ds_read_b128 v[210:213], v160 offset:20480
	ds_read_b128 v[214:217], v160 offset:21504
	ds_read_b128 v[218:221], v160 offset:22528
	ds_read_b128 v[226:229], v160 offset:23552
	global_load_lds_dwordx4 v[234:235], off
	v_lshl_add_u64 v[236:237], v[232:233], 0, v[134:135]
	s_add_i32 m0, s59, 0x2000
	v_lshl_add_u64 v[232:233], v[232:233], 0, v[138:139]
	s_add_i32 s59, s75, s57
	global_load_lds_dwordx4 v[236:237], off
	v_lshl_add_u64 v[238:239], v[232:233], 0, v[2:3]
	s_mov_b32 m0, s59
	v_lshl_add_u64 v[232:233], v[232:233], 0, v[134:135]
	global_load_lds_dwordx4 v[238:239], off
	s_add_i32 m0, s59, 0x2000
	v_lshl_add_u64 v[240:241], v[230:231], 0, v[0:1]
	global_load_lds_dwordx4 v[232:233], off
	s_mov_b32 m0, s60
	v_lshl_add_u64 v[242:243], v[230:231], 0, v[132:133]
	global_load_lds_dwordx4 v[240:241], off
	s_mov_b32 m0, s61
	s_nop 0
	global_load_lds_dwordx4 v[242:243], off
	s_waitcnt vmcnt(8)
	s_waitcnt lgkmcnt(0)
	s_barrier
	s_setprio 1
	v_mfma_i32_16x16x64_i8 v[64:67], v[162:165], v[194:197], v[64:67]
	v_mfma_i32_16x16x64_i8 v[60:63], v[170:173], v[194:197], v[60:63]
	v_mfma_i32_16x16x64_i8 v[56:59], v[162:165], v[202:205], v[56:59]
	v_mfma_i32_16x16x64_i8 v[52:55], v[170:173], v[202:205], v[52:55]
	v_mfma_i32_16x16x64_i8 v[48:51], v[162:165], v[210:213], v[48:51]
	v_mfma_i32_16x16x64_i8 v[44:47], v[170:173], v[210:213], v[44:47]
	v_mfma_i32_16x16x64_i8 v[40:43], v[162:165], v[218:221], v[40:43]
	v_mfma_i32_16x16x64_i8 v[36:39], v[170:173], v[218:221], v[36:39]
	v_mfma_i32_16x16x64_i8 v[64:67], v[166:169], v[198:201], v[64:67]
	v_mfma_i32_16x16x64_i8 v[60:63], v[174:177], v[198:201], v[60:63]
	v_mfma_i32_16x16x64_i8 v[56:59], v[166:169], v[206:209], v[56:59]
	v_mfma_i32_16x16x64_i8 v[52:55], v[174:177], v[206:209], v[52:55]
	v_mfma_i32_16x16x64_i8 v[48:51], v[166:169], v[214:217], v[48:51]
	v_mfma_i32_16x16x64_i8 v[44:47], v[174:177], v[214:217], v[44:47]
	v_mfma_i32_16x16x64_i8 v[40:43], v[166:169], v[226:229], v[40:43]
	v_mfma_i32_16x16x64_i8 v[36:39], v[174:177], v[226:229], v[36:39]
	v_mfma_i32_16x16x64_i8 v[32:35], v[178:181], v[194:197], v[32:35]
	v_mfma_i32_16x16x64_i8 v[28:31], v[186:189], v[194:197], v[28:31]
	v_mfma_i32_16x16x64_i8 v[24:27], v[178:181], v[202:205], v[24:27]
	v_mfma_i32_16x16x64_i8 v[20:23], v[186:189], v[202:205], v[20:23]
	v_mfma_i32_16x16x64_i8 v[16:19], v[178:181], v[210:213], v[16:19]
	v_mfma_i32_16x16x64_i8 v[12:15], v[186:189], v[210:213], v[12:15]
	v_mfma_i32_16x16x64_i8 v[8:11], v[178:181], v[218:221], v[8:11]
	v_mfma_i32_16x16x64_i8 v[4:7], v[186:189], v[218:221], v[4:7]
	v_mfma_i32_16x16x64_i8 v[32:35], v[182:185], v[198:201], v[32:35]
	v_mfma_i32_16x16x64_i8 v[28:31], v[190:193], v[198:201], v[28:31]
	v_mfma_i32_16x16x64_i8 v[24:27], v[182:185], v[206:209], v[24:27]
	v_mfma_i32_16x16x64_i8 v[20:23], v[190:193], v[206:209], v[20:23]
	v_mfma_i32_16x16x64_i8 v[16:19], v[182:185], v[214:217], v[16:19]
	v_mfma_i32_16x16x64_i8 v[12:15], v[190:193], v[214:217], v[12:15]
	v_mfma_i32_16x16x64_i8 v[8:11], v[182:185], v[226:229], v[8:11]
	v_mfma_i32_16x16x64_i8 v[4:7], v[190:193], v[226:229], v[4:7]
	s_setprio 0
	s_barrier
; #define PG8_STAGE(bufoff, gbase, voff) do { _Pragma("unroll") for (int _i = 0; _i < 2; ++_i) \
;         __builtin_amdgcn_global_load_lds((const unsigned*)((const char*)(gbase) + (voff)[_i]), (LAS unsigned*)(lds + (bufoff) + ldsw + _i * 8192), 16, 0, 0); } while (0)
; #define PG8_LDA(dst, b, h) do { _Pragma("unroll") for (int m = 0; m < 4; ++m) _Pragma("unroll") for (int k = 0; k < 2; ++k) dst[m][k] = *(const LAS bf16x8*)(lds + PG8_SA(b, h) + aoff + m * 2048 + k * 1024); } while (0)
; #define PG8_LDB(dst, b, h) do { _Pragma("unroll") for (int n = 0; n < 2; ++n) _Pragma("unroll") for (int k = 0; k < 2; ++k) dst[n][k] = *(const LAS bf16x8*)(lds + PG8_SB(b, h) + boff + n * 2048 + k * 1024); } while (0)
; #define PG8_WAIT_V(n) asm volatile("s_waitcnt vmcnt(" #n ")" ::: "memory")
; #define PG8_WAIT_L(n) asm volatile("s_waitcnt lgkmcnt(" #n ")" ::: "memory")
; #define PG8_BAR __builtin_amdgcn_s_barrier()
; #define PG8_SCHED __builtin_amdgcn_sched_barrier(0)
;     ...
;             PG8_LDB(B0, 1, 0); PG8_LDB(B1, 1, 1); PG8_SCHED; PG8_LDA(At, 1, 0); PG8_STAGE(PG8_SA(0, 1), a2 + hstepA, voffA);
;             PG8_WAIT_V(8); PG8_WAIT_L(0); PG8_BAR; PG8_MMA(0, 0, At, B0); PG8_MMA(0, 1, At, B1); PG8_BAR; PG8_SCHED;
;             PG8_LDA(At, 1, 1); PG8_STAGE(PG8_SB(1, 0), b3, voffB); PG8_STAGE(PG8_SB(1, 1), b3 + hstepB, voffB); PG8_STAGE(PG8_SA(1, 0), a3, voffA);
;             PG8_WAIT_V(8); PG8_WAIT_L(0); PG8_BAR; PG8_MMA(1, 0, At, B0); PG8_MMA(1, 1, At, B1); PG8_BAR; PG8_SCHED;
	s_add_i32 s59, 0, 0x18000
	s_add_i32 s75, 0, 0x1c000
	ds_read_b128 v[162:165], v248
	ds_read_b128 v[166:169], v248 offset:1024
	ds_read_b128 v[170:173], v248 offset:2048
	ds_read_b128 v[174:177], v248 offset:3072
	ds_read_b128 v[178:181], v249
	ds_read_b128 v[182:185], v249 offset:1024
	ds_read_b128 v[186:189], v249 offset:2048
	ds_read_b128 v[190:193], v249 offset:3072
	v_lshl_add_u64 v[230:231], v[230:231], 0, v[136:137]
	s_mov_b32 m0, s62
	v_lshl_add_u64 v[244:245], v[230:231], 0, v[0:1]
	ds_read_b128 v[194:197], v160 offset:32768
	ds_read_b128 v[198:201], v160 offset:33792
	ds_read_b128 v[202:205], v160 offset:34816
	ds_read_b128 v[206:209], v160 offset:35840
	ds_read_b128 v[210:213], v160 offset:36864
	ds_read_b128 v[214:217], v160 offset:37888
	ds_read_b128 v[218:221], v160 offset:38912
	ds_read_b128 v[226:229], v160 offset:39936
	global_load_lds_dwordx4 v[244:245], off
	v_lshl_add_u64 v[230:231], v[230:231], 0, v[132:133]
	s_mov_b32 m0, s63
	s_nop 0
	global_load_lds_dwordx4 v[230:231], off
	s_waitcnt vmcnt(8)
	s_waitcnt lgkmcnt(0)
	s_barrier
	s_setprio 1
	v_mfma_i32_16x16x64_i8 v[128:131], v[162:165], v[194:197], v[128:131]
	v_mfma_i32_16x16x64_i8 v[124:127], v[170:173], v[194:197], v[124:127]
	v_mfma_i32_16x16x64_i8 v[120:123], v[162:165], v[202:205], v[120:123]
	v_mfma_i32_16x16x64_i8 v[116:119], v[170:173], v[202:205], v[116:119]
	v_mfma_i32_16x16x64_i8 v[112:115], v[162:165], v[210:213], v[112:115]
	v_mfma_i32_16x16x64_i8 v[108:111], v[170:173], v[210:213], v[108:111]
	v_mfma_i32_16x16x64_i8 v[104:107], v[162:165], v[218:221], v[104:107]
	v_mfma_i32_16x16x64_i8 v[100:103], v[170:173], v[218:221], v[100:103]
	v_mfma_i32_16x16x64_i8 v[128:131], v[166:169], v[198:201], v[128:131]
	v_mfma_i32_16x16x64_i8 v[124:127], v[174:177], v[198:201], v[124:127]
	v_mfma_i32_16x16x64_i8 v[120:123], v[166:169], v[206:209], v[120:123]
	v_mfma_i32_16x16x64_i8 v[116:119], v[174:177], v[206:209], v[116:119]
	v_mfma_i32_16x16x64_i8 v[112:115], v[166:169], v[214:217], v[112:115]
	v_mfma_i32_16x16x64_i8 v[108:111], v[174:177], v[214:217], v[108:111]
	v_mfma_i32_16x16x64_i8 v[104:107], v[166:169], v[226:229], v[104:107]
	v_mfma_i32_16x16x64_i8 v[100:103], v[174:177], v[226:229], v[100:103]
	v_mfma_i32_16x16x64_i8 v[96:99], v[178:181], v[194:197], v[96:99]
	v_mfma_i32_16x16x64_i8 v[92:95], v[186:189], v[194:197], v[92:95]
	v_mfma_i32_16x16x64_i8 v[88:91], v[178:181], v[202:205], v[88:91]
	v_mfma_i32_16x16x64_i8 v[84:87], v[186:189], v[202:205], v[84:87]
	v_mfma_i32_16x16x64_i8 v[80:83], v[178:181], v[210:213], v[80:83]
	v_mfma_i32_16x16x64_i8 v[76:79], v[186:189], v[210:213], v[76:79]
	v_mfma_i32_16x16x64_i8 v[72:75], v[178:181], v[218:221], v[72:75]
	v_mfma_i32_16x16x64_i8 v[68:71], v[186:189], v[218:221], v[68:71]
	v_mfma_i32_16x16x64_i8 v[96:99], v[182:185], v[198:201], v[96:99]
	v_mfma_i32_16x16x64_i8 v[92:95], v[190:193], v[198:201], v[92:95]
	v_mfma_i32_16x16x64_i8 v[88:91], v[182:185], v[206:209], v[88:91]
	v_mfma_i32_16x16x64_i8 v[84:87], v[190:193], v[206:209], v[84:87]
	v_mfma_i32_16x16x64_i8 v[80:83], v[182:185], v[214:217], v[80:83]
	v_mfma_i32_16x16x64_i8 v[76:79], v[190:193], v[214:217], v[76:79]
	v_mfma_i32_16x16x64_i8 v[72:75], v[182:185], v[226:229], v[72:75]
	v_mfma_i32_16x16x64_i8 v[68:71], v[190:193], v[226:229], v[68:71]
	s_setprio 0
	s_barrier
	s_add_i32 s59, s59, s57
	v_lshl_add_u64 v[230:231], v[234:235], 0, s[52:53]
	s_mov_b32 m0, s59
	ds_read_b128 v[194:197], v160 offset:49152
	ds_read_b128 v[198:201], v160 offset:50176
	ds_read_b128 v[202:205], v160 offset:51200
	ds_read_b128 v[206:209], v160 offset:52224
	ds_read_b128 v[210:213], v160 offset:53248
	ds_read_b128 v[214:217], v160 offset:54272
	ds_read_b128 v[218:221], v160 offset:55296
	ds_read_b128 v[226:229], v160 offset:56320
	global_load_lds_dwordx4 v[230:231], off
	v_lshl_add_u64 v[230:231], v[236:237], 0, s[52:53]
	s_add_i32 m0, s59, 0x2000
	s_add_i32 s59, s75, s57
	global_load_lds_dwordx4 v[230:231], off
	v_lshl_add_u64 v[230:231], v[238:239], 0, s[52:53]
	s_mov_b32 m0, s59
	s_nop 0
	global_load_lds_dwordx4 v[230:231], off
	v_lshl_add_u64 v[230:231], v[232:233], 0, s[52:53]
	s_add_i32 m0, s59, 0x2000
	s_nop 0
	global_load_lds_dwordx4 v[230:231], off
	v_lshl_add_u64 v[230:231], v[240:241], 0, s[52:53]
	s_mov_b32 m0, s64
	s_nop 0
	global_load_lds_dwordx4 v[230:231], off
	v_lshl_add_u64 v[230:231], v[242:243], 0, s[52:53]
	s_mov_b32 m0, s65
	s_nop 0
	global_load_lds_dwordx4 v[230:231], off
	s_waitcnt vmcnt(8)
	s_waitcnt lgkmcnt(0)
	s_barrier
	s_setprio 1
	v_mfma_i32_16x16x64_i8 v[64:67], v[162:165], v[194:197], v[64:67]
	v_mfma_i32_16x16x64_i8 v[60:63], v[170:173], v[194:197], v[60:63]
	v_mfma_i32_16x16x64_i8 v[56:59], v[162:165], v[202:205], v[56:59]
	v_mfma_i32_16x16x64_i8 v[52:55], v[170:173], v[202:205], v[52:55]
	v_mfma_i32_16x16x64_i8 v[48:51], v[162:165], v[210:213], v[48:51]
	v_mfma_i32_16x16x64_i8 v[44:47], v[170:173], v[210:213], v[44:47]
	v_mfma_i32_16x16x64_i8 v[40:43], v[162:165], v[218:221], v[40:43]
	v_mfma_i32_16x16x64_i8 v[36:39], v[170:173], v[218:221], v[36:39]
	v_mfma_i32_16x16x64_i8 v[64:67], v[166:169], v[198:201], v[64:67]
	v_mfma_i32_16x16x64_i8 v[60:63], v[174:177], v[198:201], v[60:63]
	v_mfma_i32_16x16x64_i8 v[56:59], v[166:169], v[206:209], v[56:59]
	v_mfma_i32_16x16x64_i8 v[52:55], v[174:177], v[206:209], v[52:55]
	v_mfma_i32_16x16x64_i8 v[48:51], v[166:169], v[214:217], v[48:51]
	v_mfma_i32_16x16x64_i8 v[44:47], v[174:177], v[214:217], v[44:47]
	v_mfma_i32_16x16x64_i8 v[40:43], v[166:169], v[226:229], v[40:43]
	v_mfma_i32_16x16x64_i8 v[36:39], v[174:177], v[226:229], v[36:39]
	v_mfma_i32_16x16x64_i8 v[32:35], v[178:181], v[194:197], v[32:35]
	v_mfma_i32_16x16x64_i8 v[28:31], v[186:189], v[194:197], v[28:31]
	v_mfma_i32_16x16x64_i8 v[24:27], v[178:181], v[202:205], v[24:27]
	v_mfma_i32_16x16x64_i8 v[20:23], v[186:189], v[202:205], v[20:23]
	v_mfma_i32_16x16x64_i8 v[16:19], v[178:181], v[210:213], v[16:19]
	v_mfma_i32_16x16x64_i8 v[12:15], v[186:189], v[210:213], v[12:15]
	v_mfma_i32_16x16x64_i8 v[8:11], v[178:181], v[218:221], v[8:11]
	v_mfma_i32_16x16x64_i8 v[4:7], v[186:189], v[218:221], v[4:7]
	v_mfma_i32_16x16x64_i8 v[32:35], v[182:185], v[198:201], v[32:35]
	v_mfma_i32_16x16x64_i8 v[28:31], v[190:193], v[198:201], v[28:31]
	v_mfma_i32_16x16x64_i8 v[24:27], v[182:185], v[206:209], v[24:27]
	v_mfma_i32_16x16x64_i8 v[20:23], v[190:193], v[206:209], v[20:23]
	v_mfma_i32_16x16x64_i8 v[16:19], v[182:185], v[214:217], v[16:19]
	v_mfma_i32_16x16x64_i8 v[12:15], v[190:193], v[214:217], v[12:15]
	v_mfma_i32_16x16x64_i8 v[8:11], v[182:185], v[226:229], v[8:11]
	v_mfma_i32_16x16x64_i8 v[4:7], v[190:193], v[226:229], v[4:7]
	s_setprio 0
	s_barrier
	s_add_i32 s58, s58, 2
	s_add_u32 s38, s38, 0x100
	s_addc_u32 s39, s39, 0
	s_cmp_gt_u32 s58, 29
	s_cbranch_scc0 .LBB0_912
	s_and_b64 vcc, exec, s[50:51]
	s_cbranch_vccz .LBB0_915
	s_barrier

; #define PG8_STAGE(bufoff, gbase, voff) do { _Pragma("unroll") for (int _i = 0; _i < 2; ++_i) \
;         __builtin_amdgcn_global_load_lds((const unsigned*)((const char*)(gbase) + (voff)[_i]), (LAS unsigned*)(lds + (bufoff) + ldsw + _i * 8192), 16, 0, 0); } while (0)
; #define PG8_LDA(dst, b, h) do { _Pragma("unroll") for (int m = 0; m < 4; ++m) _Pragma("unroll") for (int k = 0; k < 2; ++k) dst[m][k] = *(const LAS bf16x8*)(lds + PG8_SA(b, h) + aoff + m * 2048 + k * 1024); } while (0)
; #define PG8_LDB(dst, b, h) do { _Pragma("unroll") for (int n = 0; n < 2; ++n) _Pragma("unroll") for (int k = 0; k < 2; ++k) dst[n][k] = *(const LAS bf16x8*)(lds + PG8_SB(b, h) + boff + n * 2048 + k * 1024); } while (0)
; #define PG8_WAIT_V(n) asm volatile("s_waitcnt vmcnt(" #n ")" ::: "memory")
; #define PG8_WAIT_L(n) asm volatile("s_waitcnt lgkmcnt(" #n ")" ::: "memory")
; #define PG8_BAR __builtin_amdgcn_s_barrier()
; #define PG8_SCHED __builtin_amdgcn_sched_barrier(0)
;     ...
;             PG8_LDB(B0, 0, 0); PG8_LDB(B1, 0, 1); PG8_SCHED; PG8_LDA(At, 0, 0); PG8_STAGE(PG8_SA(1, 1), a1 + hstepA, voffA);
;             PG8_WAIT_V(8); PG8_WAIT_L(0); PG8_BAR; PG8_MMA(0, 0, At, B0); PG8_MMA(0, 1, At, B1); PG8_BAR; PG8_SCHED;
;     ...
; #pragma unroll
;         for (int a = 0; a < 2; ++a)
; #pragma unroll
;             for (int b = 0; b < 2; ++b)
; #pragma unroll
;                 for (int m = 0; m < 4; ++m)
; #pragma unroll
;                     for (int n = 0; n < 2; ++n) acc[a][b][m][n] = (f32x4){0.f, 0.f, 0.f, 0.f};
.LBB0_1045:
	v_lshl_add_u64 v[158:159], v[0:1], 0, s[20:21]
	v_mov_b32_e32 v0, 0
	v_lshl_add_u64 v[154:155], v[152:153], 0, v[140:141]
	v_lshl_add_u64 v[156:157], v[152:153], 0, v[142:143]
	s_mov_b32 s38, -2
	s_mov_b64 s[24:25], 0
	v_mov_b32_e32 v1, v0
	v_mov_b32_e32 v2, v0
	v_mov_b32_e32 v3, v0
	v_mov_b32_e32 v4, v0
	v_mov_b32_e32 v5, v0
	v_mov_b32_e32 v6, v0
	v_mov_b32_e32 v7, v0
	v_mov_b32_e32 v8, v0
	v_mov_b32_e32 v9, v0
	v_mov_b32_e32 v10, v0
	v_mov_b32_e32 v11, v0
	v_mov_b32_e32 v12, v0
	v_mov_b32_e32 v13, v0
	v_mov_b32_e32 v14, v0
	v_mov_b32_e32 v15, v0
	v_mov_b32_e32 v16, v0
	v_mov_b32_e32 v17, v0
	v_mov_b32_e32 v18, v0
	v_mov_b32_e32 v19, v0
	v_mov_b32_e32 v20, v0
	v_mov_b32_e32 v21, v0
	v_mov_b32_e32 v22, v0
	v_mov_b32_e32 v23, v0
	v_mov_b32_e32 v24, v0
	v_mov_b32_e32 v25, v0
	v_mov_b32_e32 v26, v0
	v_mov_b32_e32 v27, v0
	v_mov_b32_e32 v28, v0
	v_mov_b32_e32 v29, v0
	v_mov_b32_e32 v30, v0
	v_mov_b32_e32 v31, v0
	v_mov_b32_e32 v32, v0
	v_mov_b32_e32 v33, v0
	v_mov_b32_e32 v34, v0
	v_mov_b32_e32 v35, v0
	v_mov_b32_e32 v36, v0
	v_mov_b32_e32 v37, v0
	v_mov_b32_e32 v38, v0
	v_mov_b32_e32 v39, v0
	v_mov_b32_e32 v40, v0
	v_mov_b32_e32 v41, v0
	v_mov_b32_e32 v42, v0
	v_mov_b32_e32 v43, v0
	v_mov_b32_e32 v44, v0
	v_mov_b32_e32 v45, v0
	v_mov_b32_e32 v46, v0
	v_mov_b32_e32 v47, v0
	v_mov_b32_e32 v48, v0
	v_mov_b32_e32 v49, v0
	v_mov_b32_e32 v50, v0
	v_mov_b32_e32 v51, v0
	v_mov_b32_e32 v52, v0
	v_mov_b32_e32 v53, v0
	v_mov_b32_e32 v54, v0
	v_mov_b32_e32 v55, v0
	v_mov_b32_e32 v56, v0
	v_mov_b32_e32 v57, v0
	v_mov_b32_e32 v58, v0
	v_mov_b32_e32 v59, v0
	v_mov_b32_e32 v60, v0
	v_mov_b32_e32 v61, v0
	v_mov_b32_e32 v62, v0
	v_mov_b32_e32 v63, v0
	v_mov_b32_e32 v64, v0
	v_mov_b32_e32 v65, v0
	v_mov_b32_e32 v66, v0
	v_mov_b32_e32 v67, v0
	v_mov_b32_e32 v68, v0
	v_mov_b32_e32 v69, v0
	v_mov_b32_e32 v70, v0
	v_mov_b32_e32 v71, v0
	v_mov_b32_e32 v72, v0
	v_mov_b32_e32 v73, v0
	v_mov_b32_e32 v74, v0
	v_mov_b32_e32 v75, v0
	v_mov_b32_e32 v76, v0
	v_mov_b32_e32 v77, v0
	v_mov_b32_e32 v78, v0
	v_mov_b32_e32 v79, v0
	v_mov_b32_e32 v80, v0
	v_mov_b32_e32 v81, v0
	v_mov_b32_e32 v82, v0
	v_mov_b32_e32 v83, v0
	v_mov_b32_e32 v84, v0
	v_mov_b32_e32 v85, v0
	v_mov_b32_e32 v86, v0
	v_mov_b32_e32 v87, v0
	v_mov_b32_e32 v88, v0
	v_mov_b32_e32 v89, v0
	v_mov_b32_e32 v90, v0
	v_mov_b32_e32 v91, v0
	v_mov_b32_e32 v92, v0
	v_mov_b32_e32 v93, v0
	v_mov_b32_e32 v94, v0
	v_mov_b32_e32 v95, v0
	v_mov_b32_e32 v96, v0
	v_mov_b32_e32 v97, v0
	v_mov_b32_e32 v98, v0
	v_mov_b32_e32 v99, v0
	v_mov_b32_e32 v100, v0
	v_mov_b32_e32 v101, v0
	v_mov_b32_e32 v102, v0
	v_mov_b32_e32 v103, v0
	v_mov_b32_e32 v104, v0
	v_mov_b32_e32 v105, v0
	v_mov_b32_e32 v106, v0
	v_mov_b32_e32 v107, v0
	v_mov_b32_e32 v108, v0
	v_mov_b32_e32 v109, v0
	v_mov_b32_e32 v110, v0
	v_mov_b32_e32 v111, v0
	v_mov_b32_e32 v112, v0
	v_mov_b32_e32 v113, v0
	v_mov_b32_e32 v114, v0
	v_mov_b32_e32 v115, v0
	v_mov_b32_e32 v116, v0
	v_mov_b32_e32 v117, v0
	v_mov_b32_e32 v118, v0
	v_mov_b32_e32 v119, v0
	v_mov_b32_e32 v120, v0
	v_mov_b32_e32 v121, v0
	v_mov_b32_e32 v122, v0
	v_mov_b32_e32 v123, v0
	v_mov_b32_e32 v124, v0
	v_mov_b32_e32 v125, v0
	v_mov_b32_e32 v126, v0
	v_mov_b32_e32 v127, v0
	v_add_u32_e32 v248, 0x18000, v162
	v_add_u32_e32 v249, 0x1c000, v162
.LBB0_1046:
	v_lshl_add_u64 v[168:169], v[152:153], 0, s[24:25]
	s_cmpk_eq_i32 s24, 0xf00
	v_lshl_add_u64 v[168:169], v[168:169], 0, s[20:21]
	v_lshl_add_u64 v[184:185], v[158:159], 0, s[24:25]
	s_cselect_b64 vcc, -1, 0
	v_cndmask_b32_e32 v233, v169, v149, vcc
	v_cndmask_b32_e32 v232, v168, v148, vcc
	ds_read_b128 v[168:171], v164
	ds_read_b128 v[172:175], v164 offset:1024
	ds_read_b128 v[176:179], v164 offset:2048
	ds_read_b128 v[180:183], v164 offset:3072
	v_cndmask_b32_e32 v235, v185, v151, vcc
	v_cndmask_b32_e32 v234, v184, v150, vcc
	ds_read_b128 v[184:187], v165
	ds_read_b128 v[188:191], v165 offset:1024
	ds_read_b128 v[192:195], v165 offset:2048
	ds_read_b128 v[196:199], v165 offset:3072
	s_mov_b32 m0, s44
	v_lshl_add_u64 v[236:237], v[156:157], 0, s[24:25]
	ds_read_b128 v[200:203], v166
	ds_read_b128 v[204:207], v166 offset:1024
	ds_read_b128 v[208:211], v166 offset:2048
	ds_read_b128 v[212:215], v166 offset:3072
	ds_read_b128 v[216:219], v166 offset:4096
	ds_read_b128 v[220:223], v166 offset:5120
	ds_read_b128 v[224:227], v166 offset:6144
	ds_read_b128 v[228:231], v166 offset:7168
	global_load_lds_dwordx4 v[236:237], off
	v_lshl_add_u64 v[236:237], v[154:155], 0, s[24:25]
	s_mov_b32 m0, s45
	s_nop 0
	global_load_lds_dwordx4 v[236:237], off
	s_waitcnt vmcnt(8)
	s_waitcnt lgkmcnt(0)
	s_barrier
; #define PG8_STAGE(bufoff, gbase, voff) do { _Pragma("unroll") for (int _i = 0; _i < 2; ++_i) \
;         __builtin_amdgcn_global_load_lds((const unsigned*)((const char*)(gbase) + (voff)[_i]), (LAS unsigned*)(lds + (bufoff) + ldsw + _i * 8192), 16, 0, 0); } while (0)
; #define PG8_LDA(dst, b, h) do { _Pragma("unroll") for (int m = 0; m < 4; ++m) _Pragma("unroll") for (int k = 0; k < 2; ++k) dst[m][k] = *(const LAS bf16x8*)(lds + PG8_SA(b, h) + aoff + m * 2048 + k * 1024); } while (0)
; #define PG8_WAIT_V(n) asm volatile("s_waitcnt vmcnt(" #n ")" ::: "memory")
; #define PG8_WAIT_L(n) asm volatile("s_waitcnt lgkmcnt(" #n ")" ::: "memory")
; #define PG8_BAR __builtin_amdgcn_s_barrier()
; #define PG8_SCHED __builtin_amdgcn_sched_barrier(0)
;     ...
;             PG8_WAIT_V(8); PG8_WAIT_L(0); PG8_BAR; PG8_MMA(0, 0, At, B0); PG8_MMA(0, 1, At, B1); PG8_BAR; PG8_SCHED;
;             PG8_LDA(At, 0, 1); PG8_STAGE(PG8_SB(0, 0), b2, voffB); PG8_STAGE(PG8_SB(0, 1), b2 + hstepB, voffB); PG8_STAGE(PG8_SA(0, 0), a2, voffA);
;             PG8_WAIT_V(8); PG8_WAIT_L(0); PG8_BAR; PG8_MMA(1, 0, At, B0); PG8_MMA(1, 1, At, B1); PG8_BAR; PG8_SCHED;
	s_setprio 1
	v_mfma_i32_16x16x64_i8 v[124:127], v[168:171], v[200:203], v[124:127]
	v_mfma_i32_16x16x64_i8 v[120:123], v[176:179], v[200:203], v[120:123]
	v_mfma_i32_16x16x64_i8 v[116:119], v[168:171], v[208:211], v[116:119]
	v_mfma_i32_16x16x64_i8 v[112:115], v[176:179], v[208:211], v[112:115]
	v_mfma_i32_16x16x64_i8 v[108:111], v[168:171], v[216:219], v[108:111]
	v_mfma_i32_16x16x64_i8 v[104:107], v[176:179], v[216:219], v[104:107]
	v_mfma_i32_16x16x64_i8 v[100:103], v[168:171], v[224:227], v[100:103]
	v_mfma_i32_16x16x64_i8 v[96:99], v[176:179], v[224:227], v[96:99]
	v_mfma_i32_16x16x64_i8 v[124:127], v[172:175], v[204:207], v[124:127]
	v_mfma_i32_16x16x64_i8 v[120:123], v[180:183], v[204:207], v[120:123]
	v_mfma_i32_16x16x64_i8 v[116:119], v[172:175], v[212:215], v[116:119]
	v_mfma_i32_16x16x64_i8 v[112:115], v[180:183], v[212:215], v[112:115]
	v_mfma_i32_16x16x64_i8 v[108:111], v[172:175], v[220:223], v[108:111]
	v_mfma_i32_16x16x64_i8 v[104:107], v[180:183], v[220:223], v[104:107]
	v_mfma_i32_16x16x64_i8 v[100:103], v[172:175], v[228:231], v[100:103]
	v_mfma_i32_16x16x64_i8 v[96:99], v[180:183], v[228:231], v[96:99]
	v_mfma_i32_16x16x64_i8 v[92:95], v[184:187], v[200:203], v[92:95]
	v_mfma_i32_16x16x64_i8 v[88:91], v[192:195], v[200:203], v[88:91]
	v_mfma_i32_16x16x64_i8 v[84:87], v[184:187], v[208:211], v[84:87]
	v_mfma_i32_16x16x64_i8 v[80:83], v[192:195], v[208:211], v[80:83]
	v_mfma_i32_16x16x64_i8 v[76:79], v[184:187], v[216:219], v[76:79]
	v_mfma_i32_16x16x64_i8 v[72:75], v[192:195], v[216:219], v[72:75]
	v_mfma_i32_16x16x64_i8 v[68:71], v[184:187], v[224:227], v[68:71]
	v_mfma_i32_16x16x64_i8 v[64:67], v[192:195], v[224:227], v[64:67]
	v_mfma_i32_16x16x64_i8 v[92:95], v[188:191], v[204:207], v[92:95]
	v_mfma_i32_16x16x64_i8 v[88:91], v[196:199], v[204:207], v[88:91]
	v_mfma_i32_16x16x64_i8 v[84:87], v[188:191], v[212:215], v[84:87]
	v_mfma_i32_16x16x64_i8 v[80:83], v[196:199], v[212:215], v[80:83]
	v_mfma_i32_16x16x64_i8 v[76:79], v[188:191], v[220:223], v[76:79]
	v_mfma_i32_16x16x64_i8 v[72:75], v[196:199], v[220:223], v[72:75]
	v_mfma_i32_16x16x64_i8 v[68:71], v[188:191], v[228:231], v[68:71]
	v_mfma_i32_16x16x64_i8 v[64:67], v[196:199], v[228:231], v[64:67]
	s_setprio 0
	s_barrier
	s_mov_b32 m0, s46
	v_lshl_add_u64 v[236:237], v[234:235], 0, v[136:137]
	ds_read_b128 v[200:203], v166 offset:16384
	ds_read_b128 v[204:207], v166 offset:17408
	ds_read_b128 v[208:211], v166 offset:18432
	ds_read_b128 v[212:215], v166 offset:19456
	ds_read_b128 v[216:219], v166 offset:20480
	ds_read_b128 v[220:223], v166 offset:21504
	ds_read_b128 v[224:227], v166 offset:22528
	ds_read_b128 v[228:231], v166 offset:23552
	global_load_lds_dwordx4 v[236:237], off
	v_lshl_add_u64 v[238:239], v[234:235], 0, v[132:133]
	s_add_i32 m0, s46, 0x2000
	v_lshl_add_u64 v[234:235], v[234:235], 0, v[130:131]
	s_add_i32 s39, s43, s2
	global_load_lds_dwordx4 v[238:239], off
	v_lshl_add_u64 v[240:241], v[234:235], 0, v[136:137]
	s_mov_b32 m0, s39
	v_lshl_add_u64 v[234:235], v[234:235], 0, v[132:133]
	global_load_lds_dwordx4 v[240:241], off
	s_add_i32 m0, s39, 0x2000
	v_lshl_add_u64 v[242:243], v[232:233], 0, v[138:139]
	global_load_lds_dwordx4 v[234:235], off
	s_mov_b32 m0, s26
	v_lshl_add_u64 v[244:245], v[232:233], 0, v[134:135]
	global_load_lds_dwordx4 v[242:243], off
	s_mov_b32 m0, s27
	s_nop 0
	global_load_lds_dwordx4 v[244:245], off
	s_waitcnt vmcnt(8)
	s_waitcnt lgkmcnt(0)
	s_barrier
	s_setprio 1
	v_mfma_i32_16x16x64_i8 v[60:63], v[168:171], v[200:203], v[60:63]
	v_mfma_i32_16x16x64_i8 v[56:59], v[176:179], v[200:203], v[56:59]
	v_mfma_i32_16x16x64_i8 v[52:55], v[168:171], v[208:211], v[52:55]
	v_mfma_i32_16x16x64_i8 v[48:51], v[176:179], v[208:211], v[48:51]
	v_mfma_i32_16x16x64_i8 v[44:47], v[168:171], v[216:219], v[44:47]
	v_mfma_i32_16x16x64_i8 v[40:43], v[176:179], v[216:219], v[40:43]
	v_mfma_i32_16x16x64_i8 v[36:39], v[168:171], v[224:227], v[36:39]
	v_mfma_i32_16x16x64_i8 v[32:35], v[176:179], v[224:227], v[32:35]
	v_mfma_i32_16x16x64_i8 v[60:63], v[172:175], v[204:207], v[60:63]
	v_mfma_i32_16x16x64_i8 v[56:59], v[180:183], v[204:207], v[56:59]
	v_mfma_i32_16x16x64_i8 v[52:55], v[172:175], v[212:215], v[52:55]
	v_mfma_i32_16x16x64_i8 v[48:51], v[180:183], v[212:215], v[48:51]
	v_mfma_i32_16x16x64_i8 v[44:47], v[172:175], v[220:223], v[44:47]
	v_mfma_i32_16x16x64_i8 v[40:43], v[180:183], v[220:223], v[40:43]
	v_mfma_i32_16x16x64_i8 v[36:39], v[172:175], v[228:231], v[36:39]
	v_mfma_i32_16x16x64_i8 v[32:35], v[180:183], v[228:231], v[32:35]
	v_mfma_i32_16x16x64_i8 v[28:31], v[184:187], v[200:203], v[28:31]
	v_mfma_i32_16x16x64_i8 v[24:27], v[192:195], v[200:203], v[24:27]
	v_mfma_i32_16x16x64_i8 v[20:23], v[184:187], v[208:211], v[20:23]
	v_mfma_i32_16x16x64_i8 v[16:19], v[192:195], v[208:211], v[16:19]
	v_mfma_i32_16x16x64_i8 v[12:15], v[184:187], v[216:219], v[12:15]
	v_mfma_i32_16x16x64_i8 v[8:11], v[192:195], v[216:219], v[8:11]
	v_mfma_i32_16x16x64_i8 v[4:7], v[184:187], v[224:227], v[4:7]
	v_mfma_i32_16x16x64_i8 v[0:3], v[192:195], v[224:227], v[0:3]
	v_mfma_i32_16x16x64_i8 v[28:31], v[188:191], v[204:207], v[28:31]
	v_mfma_i32_16x16x64_i8 v[24:27], v[196:199], v[204:207], v[24:27]
	v_mfma_i32_16x16x64_i8 v[20:23], v[188:191], v[212:215], v[20:23]
	v_mfma_i32_16x16x64_i8 v[16:19], v[196:199], v[212:215], v[16:19]
	v_mfma_i32_16x16x64_i8 v[12:15], v[188:191], v[220:223], v[12:15]
	v_mfma_i32_16x16x64_i8 v[8:11], v[196:199], v[220:223], v[8:11]
	v_mfma_i32_16x16x64_i8 v[4:7], v[188:191], v[228:231], v[4:7]
	v_mfma_i32_16x16x64_i8 v[0:3], v[196:199], v[228:231], v[0:3]
	s_setprio 0
	s_barrier
; #define PG8_STAGE(bufoff, gbase, voff) do { _Pragma("unroll") for (int _i = 0; _i < 2; ++_i) \
;         __builtin_amdgcn_global_load_lds((const unsigned*)((const char*)(gbase) + (voff)[_i]), (LAS unsigned*)(lds + (bufoff) + ldsw + _i * 8192), 16, 0, 0); } while (0)
; #define PG8_LDA(dst, b, h) do { _Pragma("unroll") for (int m = 0; m < 4; ++m) _Pragma("unroll") for (int k = 0; k < 2; ++k) dst[m][k] = *(const LAS bf16x8*)(lds + PG8_SA(b, h) + aoff + m * 2048 + k * 1024); } while (0)
; #define PG8_LDB(dst, b, h) do { _Pragma("unroll") for (int n = 0; n < 2; ++n) _Pragma("unroll") for (int k = 0; k < 2; ++k) dst[n][k] = *(const LAS bf16x8*)(lds + PG8_SB(b, h) + boff + n * 2048 + k * 1024); } while (0)
; #define PG8_WAIT_V(n) asm volatile("s_waitcnt vmcnt(" #n ")" ::: "memory")
; #define PG8_WAIT_L(n) asm volatile("s_waitcnt lgkmcnt(" #n ")" ::: "memory")
; #define PG8_BAR __builtin_amdgcn_s_barrier()
; #define PG8_SCHED __builtin_amdgcn_sched_barrier(0)
;     ...
;             PG8_LDB(B0, 1, 0); PG8_LDB(B1, 1, 1); PG8_SCHED; PG8_LDA(At, 1, 0); PG8_STAGE(PG8_SA(0, 1), a2 + hstepA, voffA);
;             PG8_WAIT_V(8); PG8_WAIT_L(0); PG8_BAR; PG8_MMA(0, 0, At, B0); PG8_MMA(0, 1, At, B1); PG8_BAR; PG8_SCHED;
;             PG8_LDA(At, 1, 1); PG8_STAGE(PG8_SB(1, 0), b3, voffB); PG8_STAGE(PG8_SB(1, 1), b3 + hstepB, voffB); PG8_STAGE(PG8_SA(1, 0), a3, voffA);
;             PG8_WAIT_V(8); PG8_WAIT_L(0); PG8_BAR; PG8_MMA(1, 0, At, B0); PG8_MMA(1, 1, At, B1); PG8_BAR; PG8_SCHED;
	s_add_i32 s39, 0, 0x18000
	s_add_i32 s51, 0, 0x1c000
	ds_read_b128 v[168:171], v248
	ds_read_b128 v[172:175], v248 offset:1024
	ds_read_b128 v[176:179], v248 offset:2048
	ds_read_b128 v[180:183], v248 offset:3072
	ds_read_b128 v[184:187], v249
	ds_read_b128 v[188:191], v249 offset:1024
	ds_read_b128 v[192:195], v249 offset:2048
	ds_read_b128 v[196:199], v249 offset:3072
	v_lshl_add_u64 v[232:233], v[232:233], 0, v[128:129]
	s_mov_b32 m0, s28
	v_lshl_add_u64 v[246:247], v[232:233], 0, v[138:139]
	ds_read_b128 v[200:203], v166 offset:32768
	ds_read_b128 v[204:207], v166 offset:33792
	ds_read_b128 v[208:211], v166 offset:34816
	ds_read_b128 v[212:215], v166 offset:35840
	ds_read_b128 v[216:219], v166 offset:36864
	ds_read_b128 v[220:223], v166 offset:37888
	ds_read_b128 v[224:227], v166 offset:38912
	ds_read_b128 v[228:231], v166 offset:39936
	global_load_lds_dwordx4 v[246:247], off
	v_lshl_add_u64 v[232:233], v[232:233], 0, v[134:135]
	s_mov_b32 m0, s29
	s_nop 0
	global_load_lds_dwordx4 v[232:233], off
	s_waitcnt vmcnt(8)
	s_waitcnt lgkmcnt(0)
	s_barrier
	s_setprio 1
	v_mfma_i32_16x16x64_i8 v[124:127], v[168:171], v[200:203], v[124:127]
	v_mfma_i32_16x16x64_i8 v[120:123], v[176:179], v[200:203], v[120:123]
	v_mfma_i32_16x16x64_i8 v[116:119], v[168:171], v[208:211], v[116:119]
	v_mfma_i32_16x16x64_i8 v[112:115], v[176:179], v[208:211], v[112:115]
	v_mfma_i32_16x16x64_i8 v[108:111], v[168:171], v[216:219], v[108:111]
	v_mfma_i32_16x16x64_i8 v[104:107], v[176:179], v[216:219], v[104:107]
	v_mfma_i32_16x16x64_i8 v[100:103], v[168:171], v[224:227], v[100:103]
	v_mfma_i32_16x16x64_i8 v[96:99], v[176:179], v[224:227], v[96:99]
	v_mfma_i32_16x16x64_i8 v[124:127], v[172:175], v[204:207], v[124:127]
	v_mfma_i32_16x16x64_i8 v[120:123], v[180:183], v[204:207], v[120:123]
	v_mfma_i32_16x16x64_i8 v[116:119], v[172:175], v[212:215], v[116:119]
	v_mfma_i32_16x16x64_i8 v[112:115], v[180:183], v[212:215], v[112:115]
	v_mfma_i32_16x16x64_i8 v[108:111], v[172:175], v[220:223], v[108:111]
	v_mfma_i32_16x16x64_i8 v[104:107], v[180:183], v[220:223], v[104:107]
	v_mfma_i32_16x16x64_i8 v[100:103], v[172:175], v[228:231], v[100:103]
	v_mfma_i32_16x16x64_i8 v[96:99], v[180:183], v[228:231], v[96:99]
	v_mfma_i32_16x16x64_i8 v[92:95], v[184:187], v[200:203], v[92:95]
	v_mfma_i32_16x16x64_i8 v[88:91], v[192:195], v[200:203], v[88:91]
	v_mfma_i32_16x16x64_i8 v[84:87], v[184:187], v[208:211], v[84:87]
	v_mfma_i32_16x16x64_i8 v[80:83], v[192:195], v[208:211], v[80:83]
	v_mfma_i32_16x16x64_i8 v[76:79], v[184:187], v[216:219], v[76:79]
	v_mfma_i32_16x16x64_i8 v[72:75], v[192:195], v[216:219], v[72:75]
	v_mfma_i32_16x16x64_i8 v[68:71], v[184:187], v[224:227], v[68:71]
	v_mfma_i32_16x16x64_i8 v[64:67], v[192:195], v[224:227], v[64:67]
	v_mfma_i32_16x16x64_i8 v[92:95], v[188:191], v[204:207], v[92:95]
	v_mfma_i32_16x16x64_i8 v[88:91], v[196:199], v[204:207], v[88:91]
	v_mfma_i32_16x16x64_i8 v[84:87], v[188:191], v[212:215], v[84:87]
	v_mfma_i32_16x16x64_i8 v[80:83], v[196:199], v[212:215], v[80:83]
	v_mfma_i32_16x16x64_i8 v[76:79], v[188:191], v[220:223], v[76:79]
	v_mfma_i32_16x16x64_i8 v[72:75], v[196:199], v[220:223], v[72:75]
	v_mfma_i32_16x16x64_i8 v[68:71], v[188:191], v[228:231], v[68:71]
	v_mfma_i32_16x16x64_i8 v[64:67], v[196:199], v[228:231], v[64:67]
	s_setprio 0
	s_barrier
	s_add_i32 s39, s39, s2
	v_lshl_add_u64 v[232:233], v[236:237], 0, s[16:17]
	s_mov_b32 m0, s39
	ds_read_b128 v[200:203], v166 offset:49152
	ds_read_b128 v[204:207], v166 offset:50176
	ds_read_b128 v[208:211], v166 offset:51200
	ds_read_b128 v[212:215], v166 offset:52224
	ds_read_b128 v[216:219], v166 offset:53248
	ds_read_b128 v[220:223], v166 offset:54272
	ds_read_b128 v[224:227], v166 offset:55296
	ds_read_b128 v[228:231], v166 offset:56320
	global_load_lds_dwordx4 v[232:233], off
	v_lshl_add_u64 v[232:233], v[238:239], 0, s[16:17]
	s_add_i32 m0, s39, 0x2000
	s_add_i32 s39, s51, s2
	global_load_lds_dwordx4 v[232:233], off
	v_lshl_add_u64 v[232:233], v[240:241], 0, s[16:17]
	s_mov_b32 m0, s39
	s_nop 0
	global_load_lds_dwordx4 v[232:233], off
	v_lshl_add_u64 v[232:233], v[234:235], 0, s[16:17]
	s_add_i32 m0, s39, 0x2000
	s_nop 0
	global_load_lds_dwordx4 v[232:233], off
	v_lshl_add_u64 v[232:233], v[242:243], 0, s[16:17]
	s_mov_b32 m0, s40
	s_nop 0
	global_load_lds_dwordx4 v[232:233], off
	v_lshl_add_u64 v[232:233], v[244:245], 0, s[16:17]
	s_mov_b32 m0, s41
	s_nop 0
	global_load_lds_dwordx4 v[232:233], off
	s_waitcnt vmcnt(8)
	s_waitcnt lgkmcnt(0)
	s_barrier
	s_setprio 1
	v_mfma_i32_16x16x64_i8 v[60:63], v[168:171], v[200:203], v[60:63]
	v_mfma_i32_16x16x64_i8 v[56:59], v[176:179], v[200:203], v[56:59]
	v_mfma_i32_16x16x64_i8 v[52:55], v[168:171], v[208:211], v[52:55]
	v_mfma_i32_16x16x64_i8 v[48:51], v[176:179], v[208:211], v[48:51]
	v_mfma_i32_16x16x64_i8 v[44:47], v[168:171], v[216:219], v[44:47]
	v_mfma_i32_16x16x64_i8 v[40:43], v[176:179], v[216:219], v[40:43]
	v_mfma_i32_16x16x64_i8 v[36:39], v[168:171], v[224:227], v[36:39]
	v_mfma_i32_16x16x64_i8 v[32:35], v[176:179], v[224:227], v[32:35]
	v_mfma_i32_16x16x64_i8 v[60:63], v[172:175], v[204:207], v[60:63]
	v_mfma_i32_16x16x64_i8 v[56:59], v[180:183], v[204:207], v[56:59]
	v_mfma_i32_16x16x64_i8 v[52:55], v[172:175], v[212:215], v[52:55]
	v_mfma_i32_16x16x64_i8 v[48:51], v[180:183], v[212:215], v[48:51]
	v_mfma_i32_16x16x64_i8 v[44:47], v[172:175], v[220:223], v[44:47]
	v_mfma_i32_16x16x64_i8 v[40:43], v[180:183], v[220:223], v[40:43]
	v_mfma_i32_16x16x64_i8 v[36:39], v[172:175], v[228:231], v[36:39]
	v_mfma_i32_16x16x64_i8 v[32:35], v[180:183], v[228:231], v[32:35]
	v_mfma_i32_16x16x64_i8 v[28:31], v[184:187], v[200:203], v[28:31]
	v_mfma_i32_16x16x64_i8 v[24:27], v[192:195], v[200:203], v[24:27]
	v_mfma_i32_16x16x64_i8 v[20:23], v[184:187], v[208:211], v[20:23]
	v_mfma_i32_16x16x64_i8 v[16:19], v[192:195], v[208:211], v[16:19]
	v_mfma_i32_16x16x64_i8 v[12:15], v[184:187], v[216:219], v[12:15]
	v_mfma_i32_16x16x64_i8 v[8:11], v[192:195], v[216:219], v[8:11]
	v_mfma_i32_16x16x64_i8 v[4:7], v[184:187], v[224:227], v[4:7]
	v_mfma_i32_16x16x64_i8 v[0:3], v[192:195], v[224:227], v[0:3]
	v_mfma_i32_16x16x64_i8 v[28:31], v[188:191], v[204:207], v[28:31]
	v_mfma_i32_16x16x64_i8 v[24:27], v[196:199], v[204:207], v[24:27]
	v_mfma_i32_16x16x64_i8 v[20:23], v[188:191], v[212:215], v[20:23]
	v_mfma_i32_16x16x64_i8 v[16:19], v[196:199], v[212:215], v[16:19]
	v_mfma_i32_16x16x64_i8 v[12:15], v[188:191], v[220:223], v[12:15]
	v_mfma_i32_16x16x64_i8 v[8:11], v[196:199], v[220:223], v[8:11]
	v_mfma_i32_16x16x64_i8 v[4:7], v[188:191], v[228:231], v[4:7]
	v_mfma_i32_16x16x64_i8 v[0:3], v[196:199], v[228:231], v[0:3]
	s_setprio 0
	s_barrier
	s_add_i32 s38, s38, 2
	s_add_u32 s24, s24, 0x100
	s_addc_u32 s25, s25, 0
	s_cmp_gt_u32 s38, 29
	s_cbranch_scc0 .LBB0_1046
	s_and_b64 vcc, exec, s[18:19]
	s_cbranch_vccz .LBB0_1049
	s_barrier

; #define PG8_STAGE(bufoff, gbase, voff) do { _Pragma("unroll") for (int _i = 0; _i < 2; ++_i) \
;         __builtin_amdgcn_global_load_lds((const unsigned*)((const char*)(gbase) + (voff)[_i]), (LAS unsigned*)(lds + (bufoff) + ldsw + _i * 8192), 16, 0, 0); } while (0)
; #define PG8_LDA(dst, b, h) do { _Pragma("unroll") for (int m = 0; m < 4; ++m) _Pragma("unroll") for (int k = 0; k < 2; ++k) dst[m][k] = *(const LAS bf16x8*)(lds + PG8_SA(b, h) + aoff + m * 2048 + k * 1024); } while (0)
; #define PG8_LDB(dst, b, h) do { _Pragma("unroll") for (int n = 0; n < 2; ++n) _Pragma("unroll") for (int k = 0; k < 2; ++k) dst[n][k] = *(const LAS bf16x8*)(lds + PG8_SB(b, h) + boff + n * 2048 + k * 1024); } while (0)
; #define PG8_WAIT_V(n) asm volatile("s_waitcnt vmcnt(" #n ")" ::: "memory")
; #define PG8_WAIT_L(n) asm volatile("s_waitcnt lgkmcnt(" #n ")" ::: "memory")
; #define PG8_BAR __builtin_amdgcn_s_barrier()
; #define PG8_SCHED __builtin_amdgcn_sched_barrier(0)
;     ...
;             PG8_LDB(B0, 0, 0); PG8_LDB(B1, 0, 1); PG8_SCHED; PG8_LDA(At, 0, 0); PG8_STAGE(PG8_SA(1, 1), a1 + hstepA, voffA);
;             PG8_WAIT_V(8); PG8_WAIT_L(0); PG8_BAR; PG8_MMA(0, 0, At, B0); PG8_MMA(0, 1, At, B1); PG8_BAR; PG8_SCHED;
;     ...
; #pragma unroll
;         for (int a = 0; a < 2; ++a)
; #pragma unroll
;             for (int b = 0; b < 2; ++b)
; #pragma unroll
;                 for (int m = 0; m < 4; ++m)
; #pragma unroll
;                     for (int n = 0; n < 2; ++n) acc[a][b][m][n] = (f32x4){0.f, 0.f, 0.f, 0.f};
.LBB0_1065:
	v_lshl_add_u64 v[158:159], v[0:1], 0, s[16:17]
	v_mov_b32_e32 v0, 0
	v_lshl_add_u64 v[154:155], v[152:153], 0, v[140:141]
	v_lshl_add_u64 v[156:157], v[152:153], 0, v[142:143]
	s_mov_b32 s38, -2
	s_mov_b64 s[18:19], 0
	v_mov_b32_e32 v1, v0
	v_mov_b32_e32 v2, v0
	v_mov_b32_e32 v3, v0
	v_mov_b32_e32 v4, v0
	v_mov_b32_e32 v5, v0
	v_mov_b32_e32 v6, v0
	v_mov_b32_e32 v7, v0
	v_mov_b32_e32 v16, v0
	v_mov_b32_e32 v17, v0
	v_mov_b32_e32 v18, v0
	v_mov_b32_e32 v19, v0
	v_mov_b32_e32 v20, v0
	v_mov_b32_e32 v21, v0
	v_mov_b32_e32 v22, v0
	v_mov_b32_e32 v23, v0
	v_mov_b32_e32 v32, v0
	v_mov_b32_e32 v33, v0
	v_mov_b32_e32 v34, v0
	v_mov_b32_e32 v35, v0
	v_mov_b32_e32 v36, v0
	v_mov_b32_e32 v37, v0
	v_mov_b32_e32 v38, v0
	v_mov_b32_e32 v39, v0
	v_mov_b32_e32 v48, v0
	v_mov_b32_e32 v49, v0
	v_mov_b32_e32 v50, v0
	v_mov_b32_e32 v51, v0
	v_mov_b32_e32 v52, v0
	v_mov_b32_e32 v53, v0
	v_mov_b32_e32 v54, v0
	v_mov_b32_e32 v55, v0
	v_mov_b32_e32 v8, v0
	v_mov_b32_e32 v9, v0
	v_mov_b32_e32 v10, v0
	v_mov_b32_e32 v11, v0
	v_mov_b32_e32 v12, v0
	v_mov_b32_e32 v13, v0
	v_mov_b32_e32 v14, v0
	v_mov_b32_e32 v15, v0
	v_mov_b32_e32 v24, v0
	v_mov_b32_e32 v25, v0
	v_mov_b32_e32 v26, v0
	v_mov_b32_e32 v27, v0
	v_mov_b32_e32 v28, v0
	v_mov_b32_e32 v29, v0
	v_mov_b32_e32 v30, v0
	v_mov_b32_e32 v31, v0
	v_mov_b32_e32 v40, v0
	v_mov_b32_e32 v41, v0
	v_mov_b32_e32 v42, v0
	v_mov_b32_e32 v43, v0
	v_mov_b32_e32 v44, v0
	v_mov_b32_e32 v45, v0
	v_mov_b32_e32 v46, v0
	v_mov_b32_e32 v47, v0
	v_mov_b32_e32 v56, v0
	v_mov_b32_e32 v57, v0
	v_mov_b32_e32 v58, v0
	v_mov_b32_e32 v59, v0
	v_mov_b32_e32 v60, v0
	v_mov_b32_e32 v61, v0
	v_mov_b32_e32 v62, v0
	v_mov_b32_e32 v63, v0
	v_mov_b32_e32 v64, v0
	v_mov_b32_e32 v65, v0
	v_mov_b32_e32 v66, v0
	v_mov_b32_e32 v67, v0
	v_mov_b32_e32 v68, v0
	v_mov_b32_e32 v69, v0
	v_mov_b32_e32 v70, v0
	v_mov_b32_e32 v71, v0
	v_mov_b32_e32 v80, v0
	v_mov_b32_e32 v81, v0
	v_mov_b32_e32 v82, v0
	v_mov_b32_e32 v83, v0
	v_mov_b32_e32 v84, v0
	v_mov_b32_e32 v85, v0
	v_mov_b32_e32 v86, v0
	v_mov_b32_e32 v87, v0
	v_mov_b32_e32 v96, v0
	v_mov_b32_e32 v97, v0
	v_mov_b32_e32 v98, v0
	v_mov_b32_e32 v99, v0
	v_mov_b32_e32 v100, v0
	v_mov_b32_e32 v101, v0
	v_mov_b32_e32 v102, v0
	v_mov_b32_e32 v103, v0
	v_mov_b32_e32 v112, v0
	v_mov_b32_e32 v113, v0
	v_mov_b32_e32 v114, v0
	v_mov_b32_e32 v115, v0
	v_mov_b32_e32 v116, v0
	v_mov_b32_e32 v117, v0
	v_mov_b32_e32 v118, v0
	v_mov_b32_e32 v119, v0
	v_mov_b32_e32 v72, v0
	v_mov_b32_e32 v73, v0
	v_mov_b32_e32 v74, v0
	v_mov_b32_e32 v75, v0
	v_mov_b32_e32 v76, v0
	v_mov_b32_e32 v77, v0
	v_mov_b32_e32 v78, v0
	v_mov_b32_e32 v79, v0
	v_mov_b32_e32 v88, v0
	v_mov_b32_e32 v89, v0
	v_mov_b32_e32 v90, v0
	v_mov_b32_e32 v91, v0
	v_mov_b32_e32 v92, v0
	v_mov_b32_e32 v93, v0
	v_mov_b32_e32 v94, v0
	v_mov_b32_e32 v95, v0
	v_mov_b32_e32 v104, v0
	v_mov_b32_e32 v105, v0
	v_mov_b32_e32 v106, v0
	v_mov_b32_e32 v107, v0
	v_mov_b32_e32 v108, v0
	v_mov_b32_e32 v109, v0
	v_mov_b32_e32 v110, v0
	v_mov_b32_e32 v111, v0
	v_mov_b32_e32 v120, v0
	v_mov_b32_e32 v121, v0
	v_mov_b32_e32 v122, v0
	v_mov_b32_e32 v123, v0
	v_mov_b32_e32 v124, v0
	v_mov_b32_e32 v125, v0
	v_mov_b32_e32 v126, v0
	v_mov_b32_e32 v127, v0
	v_add_u32_e32 v248, 0x18000, v162
	v_add_u32_e32 v249, 0x1c000, v162
.LBB0_1066:
	v_lshl_add_u64 v[168:169], v[152:153], 0, s[18:19]
	s_cmpk_eq_i32 s18, 0x1f00
	v_lshl_add_u64 v[168:169], v[168:169], 0, s[16:17]
	v_lshl_add_u64 v[184:185], v[158:159], 0, s[18:19]
	s_cselect_b64 vcc, -1, 0
	v_cndmask_b32_e32 v233, v169, v149, vcc
	v_cndmask_b32_e32 v232, v168, v148, vcc
	ds_read_b128 v[168:171], v164
	ds_read_b128 v[172:175], v164 offset:1024
	ds_read_b128 v[176:179], v164 offset:2048
	ds_read_b128 v[180:183], v164 offset:3072
	v_cndmask_b32_e32 v235, v185, v151, vcc
	v_cndmask_b32_e32 v234, v184, v150, vcc
	ds_read_b128 v[184:187], v165
	ds_read_b128 v[188:191], v165 offset:1024
	ds_read_b128 v[192:195], v165 offset:2048
	ds_read_b128 v[196:199], v165 offset:3072
	s_mov_b32 m0, s35
	v_lshl_add_u64 v[236:237], v[156:157], 0, s[18:19]
	ds_read_b128 v[200:203], v166
	ds_read_b128 v[204:207], v166 offset:1024
	ds_read_b128 v[208:211], v166 offset:2048
	ds_read_b128 v[212:215], v166 offset:3072
	ds_read_b128 v[216:219], v166 offset:4096
	ds_read_b128 v[220:223], v166 offset:5120
	ds_read_b128 v[224:227], v166 offset:6144
	ds_read_b128 v[228:231], v166 offset:7168
	global_load_lds_dwordx4 v[236:237], off
	v_lshl_add_u64 v[236:237], v[154:155], 0, s[18:19]
	s_mov_b32 m0, s40
	s_nop 0
	global_load_lds_dwordx4 v[236:237], off
	s_waitcnt vmcnt(8)
	s_waitcnt lgkmcnt(0)
	s_barrier
; #define PG8_STAGE(bufoff, gbase, voff) do { _Pragma("unroll") for (int _i = 0; _i < 2; ++_i) \
;         __builtin_amdgcn_global_load_lds((const unsigned*)((const char*)(gbase) + (voff)[_i]), (LAS unsigned*)(lds + (bufoff) + ldsw + _i * 8192), 16, 0, 0); } while (0)
; #define PG8_LDA(dst, b, h) do { _Pragma("unroll") for (int m = 0; m < 4; ++m) _Pragma("unroll") for (int k = 0; k < 2; ++k) dst[m][k] = *(const LAS bf16x8*)(lds + PG8_SA(b, h) + aoff + m * 2048 + k * 1024); } while (0)
; #define PG8_WAIT_V(n) asm volatile("s_waitcnt vmcnt(" #n ")" ::: "memory")
; #define PG8_WAIT_L(n) asm volatile("s_waitcnt lgkmcnt(" #n ")" ::: "memory")
; #define PG8_BAR __builtin_amdgcn_s_barrier()
; #define PG8_SCHED __builtin_amdgcn_sched_barrier(0)
;     ...
;             PG8_WAIT_V(8); PG8_WAIT_L(0); PG8_BAR; PG8_MMA(0, 0, At, B0); PG8_MMA(0, 1, At, B1); PG8_BAR; PG8_SCHED;
;             PG8_LDA(At, 0, 1); PG8_STAGE(PG8_SB(0, 0), b2, voffB); PG8_STAGE(PG8_SB(0, 1), b2 + hstepB, voffB); PG8_STAGE(PG8_SA(0, 0), a2, voffA);
;             PG8_WAIT_V(8); PG8_WAIT_L(0); PG8_BAR; PG8_MMA(1, 0, At, B0); PG8_MMA(1, 1, At, B1); PG8_BAR; PG8_SCHED;
	s_setprio 1
	v_mfma_f32_16x16x32_bf16 v[124:127], v[168:171], v[200:203], v[124:127]
	v_mfma_f32_16x16x32_bf16 v[120:123], v[176:179], v[200:203], v[120:123]
	v_mfma_f32_16x16x32_bf16 v[108:111], v[168:171], v[208:211], v[108:111]
	v_mfma_f32_16x16x32_bf16 v[104:107], v[176:179], v[208:211], v[104:107]
	v_mfma_f32_16x16x32_bf16 v[92:95], v[168:171], v[216:219], v[92:95]
	v_mfma_f32_16x16x32_bf16 v[88:91], v[176:179], v[216:219], v[88:91]
	v_mfma_f32_16x16x32_bf16 v[76:79], v[168:171], v[224:227], v[76:79]
	v_mfma_f32_16x16x32_bf16 v[72:75], v[176:179], v[224:227], v[72:75]
	v_mfma_f32_16x16x32_bf16 v[124:127], v[172:175], v[204:207], v[124:127]
	v_mfma_f32_16x16x32_bf16 v[120:123], v[180:183], v[204:207], v[120:123]
	v_mfma_f32_16x16x32_bf16 v[108:111], v[172:175], v[212:215], v[108:111]
	v_mfma_f32_16x16x32_bf16 v[104:107], v[180:183], v[212:215], v[104:107]
	v_mfma_f32_16x16x32_bf16 v[92:95], v[172:175], v[220:223], v[92:95]
	v_mfma_f32_16x16x32_bf16 v[88:91], v[180:183], v[220:223], v[88:91]
	v_mfma_f32_16x16x32_bf16 v[76:79], v[172:175], v[228:231], v[76:79]
	v_mfma_f32_16x16x32_bf16 v[72:75], v[180:183], v[228:231], v[72:75]
	v_mfma_f32_16x16x32_bf16 v[116:119], v[184:187], v[200:203], v[116:119]
	v_mfma_f32_16x16x32_bf16 v[112:115], v[192:195], v[200:203], v[112:115]
	v_mfma_f32_16x16x32_bf16 v[100:103], v[184:187], v[208:211], v[100:103]
	v_mfma_f32_16x16x32_bf16 v[96:99], v[192:195], v[208:211], v[96:99]
	v_mfma_f32_16x16x32_bf16 v[84:87], v[184:187], v[216:219], v[84:87]
	v_mfma_f32_16x16x32_bf16 v[80:83], v[192:195], v[216:219], v[80:83]
	v_mfma_f32_16x16x32_bf16 v[68:71], v[184:187], v[224:227], v[68:71]
	v_mfma_f32_16x16x32_bf16 v[64:67], v[192:195], v[224:227], v[64:67]
	v_mfma_f32_16x16x32_bf16 v[116:119], v[188:191], v[204:207], v[116:119]
	v_mfma_f32_16x16x32_bf16 v[112:115], v[196:199], v[204:207], v[112:115]
	v_mfma_f32_16x16x32_bf16 v[100:103], v[188:191], v[212:215], v[100:103]
	v_mfma_f32_16x16x32_bf16 v[96:99], v[196:199], v[212:215], v[96:99]
	v_mfma_f32_16x16x32_bf16 v[84:87], v[188:191], v[220:223], v[84:87]
	v_mfma_f32_16x16x32_bf16 v[80:83], v[196:199], v[220:223], v[80:83]
	v_mfma_f32_16x16x32_bf16 v[68:71], v[188:191], v[228:231], v[68:71]
	v_mfma_f32_16x16x32_bf16 v[64:67], v[196:199], v[228:231], v[64:67]
	s_setprio 0
	s_barrier
	s_mov_b32 m0, s41
	v_lshl_add_u64 v[236:237], v[234:235], 0, v[136:137]
	ds_read_b128 v[200:203], v166 offset:16384
	ds_read_b128 v[204:207], v166 offset:17408
	ds_read_b128 v[208:211], v166 offset:18432
	ds_read_b128 v[212:215], v166 offset:19456
	ds_read_b128 v[216:219], v166 offset:20480
	ds_read_b128 v[220:223], v166 offset:21504
	ds_read_b128 v[224:227], v166 offset:22528
	ds_read_b128 v[228:231], v166 offset:23552
	global_load_lds_dwordx4 v[236:237], off
	v_lshl_add_u64 v[238:239], v[234:235], 0, v[132:133]
	s_add_i32 m0, s41, 0x2000
	v_lshl_add_u64 v[234:235], v[234:235], 0, v[130:131]
	s_add_i32 s39, s34, s2
	global_load_lds_dwordx4 v[238:239], off
	v_lshl_add_u64 v[240:241], v[234:235], 0, v[136:137]
	s_mov_b32 m0, s39
	v_lshl_add_u64 v[234:235], v[234:235], 0, v[132:133]
	global_load_lds_dwordx4 v[240:241], off
	s_add_i32 m0, s39, 0x2000
	v_lshl_add_u64 v[242:243], v[232:233], 0, v[138:139]
	global_load_lds_dwordx4 v[234:235], off
	s_mov_b32 m0, s21
	v_lshl_add_u64 v[244:245], v[232:233], 0, v[134:135]
	global_load_lds_dwordx4 v[242:243], off
	s_mov_b32 m0, s22
	s_nop 0
	global_load_lds_dwordx4 v[244:245], off
	s_waitcnt vmcnt(8)
	s_waitcnt lgkmcnt(0)
	s_barrier
	s_setprio 1
	v_mfma_f32_16x16x32_bf16 v[60:63], v[168:171], v[200:203], v[60:63]
	v_mfma_f32_16x16x32_bf16 v[56:59], v[176:179], v[200:203], v[56:59]
	v_mfma_f32_16x16x32_bf16 v[44:47], v[168:171], v[208:211], v[44:47]
	v_mfma_f32_16x16x32_bf16 v[40:43], v[176:179], v[208:211], v[40:43]
	v_mfma_f32_16x16x32_bf16 v[28:31], v[168:171], v[216:219], v[28:31]
	v_mfma_f32_16x16x32_bf16 v[24:27], v[176:179], v[216:219], v[24:27]
	v_mfma_f32_16x16x32_bf16 v[12:15], v[168:171], v[224:227], v[12:15]
	v_mfma_f32_16x16x32_bf16 v[8:11], v[176:179], v[224:227], v[8:11]
	v_mfma_f32_16x16x32_bf16 v[60:63], v[172:175], v[204:207], v[60:63]
	v_mfma_f32_16x16x32_bf16 v[56:59], v[180:183], v[204:207], v[56:59]
	v_mfma_f32_16x16x32_bf16 v[44:47], v[172:175], v[212:215], v[44:47]
	v_mfma_f32_16x16x32_bf16 v[40:43], v[180:183], v[212:215], v[40:43]
	v_mfma_f32_16x16x32_bf16 v[28:31], v[172:175], v[220:223], v[28:31]
	v_mfma_f32_16x16x32_bf16 v[24:27], v[180:183], v[220:223], v[24:27]
	v_mfma_f32_16x16x32_bf16 v[12:15], v[172:175], v[228:231], v[12:15]
	v_mfma_f32_16x16x32_bf16 v[8:11], v[180:183], v[228:231], v[8:11]
	v_mfma_f32_16x16x32_bf16 v[52:55], v[184:187], v[200:203], v[52:55]
	v_mfma_f32_16x16x32_bf16 v[48:51], v[192:195], v[200:203], v[48:51]
	v_mfma_f32_16x16x32_bf16 v[36:39], v[184:187], v[208:211], v[36:39]
	v_mfma_f32_16x16x32_bf16 v[32:35], v[192:195], v[208:211], v[32:35]
	v_mfma_f32_16x16x32_bf16 v[20:23], v[184:187], v[216:219], v[20:23]
	v_mfma_f32_16x16x32_bf16 v[16:19], v[192:195], v[216:219], v[16:19]
	v_mfma_f32_16x16x32_bf16 v[4:7], v[184:187], v[224:227], v[4:7]
	v_mfma_f32_16x16x32_bf16 v[0:3], v[192:195], v[224:227], v[0:3]
	v_mfma_f32_16x16x32_bf16 v[52:55], v[188:191], v[204:207], v[52:55]
	v_mfma_f32_16x16x32_bf16 v[48:51], v[196:199], v[204:207], v[48:51]
	v_mfma_f32_16x16x32_bf16 v[36:39], v[188:191], v[212:215], v[36:39]
	v_mfma_f32_16x16x32_bf16 v[32:35], v[196:199], v[212:215], v[32:35]
	v_mfma_f32_16x16x32_bf16 v[20:23], v[188:191], v[220:223], v[20:23]
	v_mfma_f32_16x16x32_bf16 v[16:19], v[196:199], v[220:223], v[16:19]
	v_mfma_f32_16x16x32_bf16 v[4:7], v[188:191], v[228:231], v[4:7]
	v_mfma_f32_16x16x32_bf16 v[0:3], v[196:199], v[228:231], v[0:3]
	s_setprio 0
	s_barrier
; #define PG8_STAGE(bufoff, gbase, voff) do { _Pragma("unroll") for (int _i = 0; _i < 2; ++_i) \
;         __builtin_amdgcn_global_load_lds((const unsigned*)((const char*)(gbase) + (voff)[_i]), (LAS unsigned*)(lds + (bufoff) + ldsw + _i * 8192), 16, 0, 0); } while (0)
; #define PG8_LDA(dst, b, h) do { _Pragma("unroll") for (int m = 0; m < 4; ++m) _Pragma("unroll") for (int k = 0; k < 2; ++k) dst[m][k] = *(const LAS bf16x8*)(lds + PG8_SA(b, h) + aoff + m * 2048 + k * 1024); } while (0)
; #define PG8_LDB(dst, b, h) do { _Pragma("unroll") for (int n = 0; n < 2; ++n) _Pragma("unroll") for (int k = 0; k < 2; ++k) dst[n][k] = *(const LAS bf16x8*)(lds + PG8_SB(b, h) + boff + n * 2048 + k * 1024); } while (0)
; #define PG8_WAIT_V(n) asm volatile("s_waitcnt vmcnt(" #n ")" ::: "memory")
; #define PG8_WAIT_L(n) asm volatile("s_waitcnt lgkmcnt(" #n ")" ::: "memory")
; #define PG8_BAR __builtin_amdgcn_s_barrier()
; #define PG8_SCHED __builtin_amdgcn_sched_barrier(0)
;     ...
;             PG8_LDB(B0, 1, 0); PG8_LDB(B1, 1, 1); PG8_SCHED; PG8_LDA(At, 1, 0); PG8_STAGE(PG8_SA(0, 1), a2 + hstepA, voffA);
;             PG8_WAIT_V(8); PG8_WAIT_L(0); PG8_BAR; PG8_MMA(0, 0, At, B0); PG8_MMA(0, 1, At, B1); PG8_BAR; PG8_SCHED;
;             PG8_LDA(At, 1, 1); PG8_STAGE(PG8_SB(1, 0), b3, voffB); PG8_STAGE(PG8_SB(1, 1), b3 + hstepB, voffB); PG8_STAGE(PG8_SA(1, 0), a3, voffA);
;             PG8_WAIT_V(8); PG8_WAIT_L(0); PG8_BAR; PG8_MMA(1, 0, At, B0); PG8_MMA(1, 1, At, B1); PG8_BAR; PG8_SCHED;
	s_add_i32 s39, 0, 0x18000
	s_add_i32 s46, 0, 0x1c000
	ds_read_b128 v[168:171], v248
	ds_read_b128 v[172:175], v248 offset:1024
	ds_read_b128 v[176:179], v248 offset:2048
	ds_read_b128 v[180:183], v248 offset:3072
	ds_read_b128 v[184:187], v249
	ds_read_b128 v[188:191], v249 offset:1024
	ds_read_b128 v[192:195], v249 offset:2048
	ds_read_b128 v[196:199], v249 offset:3072
	v_lshl_add_u64 v[232:233], v[232:233], 0, v[128:129]
	s_mov_b32 m0, s23
	v_lshl_add_u64 v[246:247], v[232:233], 0, v[138:139]
	ds_read_b128 v[200:203], v166 offset:32768
	ds_read_b128 v[204:207], v166 offset:33792
	ds_read_b128 v[208:211], v166 offset:34816
	ds_read_b128 v[212:215], v166 offset:35840
	ds_read_b128 v[216:219], v166 offset:36864
	ds_read_b128 v[220:223], v166 offset:37888
	ds_read_b128 v[224:227], v166 offset:38912
	ds_read_b128 v[228:231], v166 offset:39936
	global_load_lds_dwordx4 v[246:247], off
	v_lshl_add_u64 v[232:233], v[232:233], 0, v[134:135]
	s_mov_b32 m0, s24
	s_nop 0
	global_load_lds_dwordx4 v[232:233], off
	s_waitcnt vmcnt(8)
	s_waitcnt lgkmcnt(0)
	s_barrier
	s_setprio 1
	v_mfma_f32_16x16x32_bf16 v[124:127], v[168:171], v[200:203], v[124:127]
	v_mfma_f32_16x16x32_bf16 v[120:123], v[176:179], v[200:203], v[120:123]
	v_mfma_f32_16x16x32_bf16 v[108:111], v[168:171], v[208:211], v[108:111]
	v_mfma_f32_16x16x32_bf16 v[104:107], v[176:179], v[208:211], v[104:107]
	v_mfma_f32_16x16x32_bf16 v[92:95], v[168:171], v[216:219], v[92:95]
	v_mfma_f32_16x16x32_bf16 v[88:91], v[176:179], v[216:219], v[88:91]
	v_mfma_f32_16x16x32_bf16 v[76:79], v[168:171], v[224:227], v[76:79]
	v_mfma_f32_16x16x32_bf16 v[72:75], v[176:179], v[224:227], v[72:75]
	v_mfma_f32_16x16x32_bf16 v[124:127], v[172:175], v[204:207], v[124:127]
	v_mfma_f32_16x16x32_bf16 v[120:123], v[180:183], v[204:207], v[120:123]
	v_mfma_f32_16x16x32_bf16 v[108:111], v[172:175], v[212:215], v[108:111]
	v_mfma_f32_16x16x32_bf16 v[104:107], v[180:183], v[212:215], v[104:107]
	v_mfma_f32_16x16x32_bf16 v[92:95], v[172:175], v[220:223], v[92:95]
	v_mfma_f32_16x16x32_bf16 v[88:91], v[180:183], v[220:223], v[88:91]
	v_mfma_f32_16x16x32_bf16 v[76:79], v[172:175], v[228:231], v[76:79]
	v_mfma_f32_16x16x32_bf16 v[72:75], v[180:183], v[228:231], v[72:75]
	v_mfma_f32_16x16x32_bf16 v[116:119], v[184:187], v[200:203], v[116:119]
	v_mfma_f32_16x16x32_bf16 v[112:115], v[192:195], v[200:203], v[112:115]
	v_mfma_f32_16x16x32_bf16 v[100:103], v[184:187], v[208:211], v[100:103]
	v_mfma_f32_16x16x32_bf16 v[96:99], v[192:195], v[208:211], v[96:99]
	v_mfma_f32_16x16x32_bf16 v[84:87], v[184:187], v[216:219], v[84:87]
	v_mfma_f32_16x16x32_bf16 v[80:83], v[192:195], v[216:219], v[80:83]
	v_mfma_f32_16x16x32_bf16 v[68:71], v[184:187], v[224:227], v[68:71]
	v_mfma_f32_16x16x32_bf16 v[64:67], v[192:195], v[224:227], v[64:67]
	v_mfma_f32_16x16x32_bf16 v[116:119], v[188:191], v[204:207], v[116:119]
	v_mfma_f32_16x16x32_bf16 v[112:115], v[196:199], v[204:207], v[112:115]
	v_mfma_f32_16x16x32_bf16 v[100:103], v[188:191], v[212:215], v[100:103]
	v_mfma_f32_16x16x32_bf16 v[96:99], v[196:199], v[212:215], v[96:99]
	v_mfma_f32_16x16x32_bf16 v[84:87], v[188:191], v[220:223], v[84:87]
	v_mfma_f32_16x16x32_bf16 v[80:83], v[196:199], v[220:223], v[80:83]
	v_mfma_f32_16x16x32_bf16 v[68:71], v[188:191], v[228:231], v[68:71]
	v_mfma_f32_16x16x32_bf16 v[64:67], v[196:199], v[228:231], v[64:67]
	s_setprio 0
	s_barrier
	s_add_i32 s39, s39, s2
	v_lshl_add_u64 v[232:233], v[236:237], 0, s[12:13]
	s_mov_b32 m0, s39
	ds_read_b128 v[200:203], v166 offset:49152
	ds_read_b128 v[204:207], v166 offset:50176
	ds_read_b128 v[208:211], v166 offset:51200
	ds_read_b128 v[212:215], v166 offset:52224
	ds_read_b128 v[216:219], v166 offset:53248
	ds_read_b128 v[220:223], v166 offset:54272
	ds_read_b128 v[224:227], v166 offset:55296
	ds_read_b128 v[228:231], v166 offset:56320
	global_load_lds_dwordx4 v[232:233], off
	v_lshl_add_u64 v[232:233], v[238:239], 0, s[12:13]
	s_add_i32 m0, s39, 0x2000
	s_add_i32 s39, s46, s2
	global_load_lds_dwordx4 v[232:233], off
	v_lshl_add_u64 v[232:233], v[240:241], 0, s[12:13]
	s_mov_b32 m0, s39
	s_nop 0
	global_load_lds_dwordx4 v[232:233], off
	v_lshl_add_u64 v[232:233], v[234:235], 0, s[12:13]
	s_add_i32 m0, s39, 0x2000
	s_nop 0
	global_load_lds_dwordx4 v[232:233], off
	v_lshl_add_u64 v[232:233], v[242:243], 0, s[12:13]
	s_mov_b32 m0, s30
	s_nop 0
	global_load_lds_dwordx4 v[232:233], off
	v_lshl_add_u64 v[232:233], v[244:245], 0, s[12:13]
	s_mov_b32 m0, s31
	s_nop 0
	global_load_lds_dwordx4 v[232:233], off
	s_waitcnt vmcnt(8)
	s_waitcnt lgkmcnt(0)
	s_barrier
	s_setprio 1
	v_mfma_f32_16x16x32_bf16 v[60:63], v[168:171], v[200:203], v[60:63]
	v_mfma_f32_16x16x32_bf16 v[56:59], v[176:179], v[200:203], v[56:59]
	v_mfma_f32_16x16x32_bf16 v[44:47], v[168:171], v[208:211], v[44:47]
	v_mfma_f32_16x16x32_bf16 v[40:43], v[176:179], v[208:211], v[40:43]
	v_mfma_f32_16x16x32_bf16 v[28:31], v[168:171], v[216:219], v[28:31]
	v_mfma_f32_16x16x32_bf16 v[24:27], v[176:179], v[216:219], v[24:27]
	v_mfma_f32_16x16x32_bf16 v[12:15], v[168:171], v[224:227], v[12:15]
	v_mfma_f32_16x16x32_bf16 v[8:11], v[176:179], v[224:227], v[8:11]
	v_mfma_f32_16x16x32_bf16 v[60:63], v[172:175], v[204:207], v[60:63]
	v_mfma_f32_16x16x32_bf16 v[56:59], v[180:183], v[204:207], v[56:59]
	v_mfma_f32_16x16x32_bf16 v[44:47], v[172:175], v[212:215], v[44:47]
	v_mfma_f32_16x16x32_bf16 v[40:43], v[180:183], v[212:215], v[40:43]
	v_mfma_f32_16x16x32_bf16 v[28:31], v[172:175], v[220:223], v[28:31]
	v_mfma_f32_16x16x32_bf16 v[24:27], v[180:183], v[220:223], v[24:27]
	v_mfma_f32_16x16x32_bf16 v[12:15], v[172:175], v[228:231], v[12:15]
	v_mfma_f32_16x16x32_bf16 v[8:11], v[180:183], v[228:231], v[8:11]
	v_mfma_f32_16x16x32_bf16 v[52:55], v[184:187], v[200:203], v[52:55]
	v_mfma_f32_16x16x32_bf16 v[48:51], v[192:195], v[200:203], v[48:51]
	v_mfma_f32_16x16x32_bf16 v[36:39], v[184:187], v[208:211], v[36:39]
	v_mfma_f32_16x16x32_bf16 v[32:35], v[192:195], v[208:211], v[32:35]
	v_mfma_f32_16x16x32_bf16 v[20:23], v[184:187], v[216:219], v[20:23]
	v_mfma_f32_16x16x32_bf16 v[16:19], v[192:195], v[216:219], v[16:19]
	v_mfma_f32_16x16x32_bf16 v[4:7], v[184:187], v[224:227], v[4:7]
	v_mfma_f32_16x16x32_bf16 v[0:3], v[192:195], v[224:227], v[0:3]
	v_mfma_f32_16x16x32_bf16 v[52:55], v[188:191], v[204:207], v[52:55]
	v_mfma_f32_16x16x32_bf16 v[48:51], v[196:199], v[204:207], v[48:51]
	v_mfma_f32_16x16x32_bf16 v[36:39], v[188:191], v[212:215], v[36:39]
	v_mfma_f32_16x16x32_bf16 v[32:35], v[196:199], v[212:215], v[32:35]
	v_mfma_f32_16x16x32_bf16 v[20:23], v[188:191], v[220:223], v[20:23]
	v_mfma_f32_16x16x32_bf16 v[16:19], v[196:199], v[220:223], v[16:19]
	v_mfma_f32_16x16x32_bf16 v[4:7], v[188:191], v[228:231], v[4:7]
	v_mfma_f32_16x16x32_bf16 v[0:3], v[196:199], v[228:231], v[0:3]
	s_setprio 0
	s_barrier
	s_add_i32 s38, s38, 2
	s_add_u32 s18, s18, 0x100
	s_addc_u32 s19, s19, 0
	s_cmp_gt_u32 s38, 61
	s_cbranch_scc0 .LBB0_1066
	s_and_b64 vcc, exec, s[14:15]
	s_cbranch_vccz .LBB0_1069
	s_barrier

; #define PG8_STAGE(bufoff, gbase, voff) do { _Pragma("unroll") for (int _i = 0; _i < 2; ++_i) \
;         __builtin_amdgcn_global_load_lds((const unsigned*)((const char*)(gbase) + (voff)[_i]), (LAS unsigned*)(lds + (bufoff) + ldsw + _i * 8192), 16, 0, 0); } while (0)
; #define PG8_LDA(dst, b, h) do { _Pragma("unroll") for (int m = 0; m < 4; ++m) _Pragma("unroll") for (int k = 0; k < 2; ++k) dst[m][k] = *(const LAS bf16x8*)(lds + PG8_SA(b, h) + aoff + m * 2048 + k * 1024); } while (0)
; #define PG8_LDB(dst, b, h) do { _Pragma("unroll") for (int n = 0; n < 2; ++n) _Pragma("unroll") for (int k = 0; k < 2; ++k) dst[n][k] = *(const LAS bf16x8*)(lds + PG8_SB(b, h) + boff + n * 2048 + k * 1024); } while (0)
; #define PG8_WAIT_V(n) asm volatile("s_waitcnt vmcnt(" #n ")" ::: "memory")
; #define PG8_WAIT_L(n) asm volatile("s_waitcnt lgkmcnt(" #n ")" ::: "memory")
; #define PG8_BAR __builtin_amdgcn_s_barrier()
; #define PG8_SCHED __builtin_amdgcn_sched_barrier(0)
;     ...
;             PG8_LDB(B0, 0, 0); PG8_LDB(B1, 0, 1); PG8_SCHED; PG8_LDA(At, 0, 0); PG8_STAGE(PG8_SA(1, 1), a1 + hstepA, voffA);
;             PG8_WAIT_V(8); PG8_WAIT_L(0); PG8_BAR; PG8_MMA(0, 0, At, B0); PG8_MMA(0, 1, At, B1); PG8_BAR; PG8_SCHED;
;     ...
; #pragma unroll
;         for (int a = 0; a < 2; ++a)
; #pragma unroll
;             for (int b = 0; b < 2; ++b)
; #pragma unroll
;                 for (int m = 0; m < 4; ++m)
; #pragma unroll
;                     for (int n = 0; n < 2; ++n) acc[a][b][m][n] = (f32x4){0.f, 0.f, 0.f, 0.f};
.LBB0_1147:
	v_lshl_add_u64 v[158:159], v[0:1], 0, s[16:17]
	v_mov_b32_e32 v0, 0
	v_lshl_add_u64 v[154:155], v[152:153], 0, v[140:141]
	v_lshl_add_u64 v[156:157], v[152:153], 0, v[142:143]
	s_mov_b32 s20, -2
	s_mov_b64 s[18:19], 0
	v_mov_b32_e32 v1, v0
	v_mov_b32_e32 v2, v0
	v_mov_b32_e32 v3, v0
	v_mov_b32_e32 v4, v0
	v_mov_b32_e32 v5, v0
	v_mov_b32_e32 v6, v0
	v_mov_b32_e32 v7, v0
	v_mov_b32_e32 v16, v0
	v_mov_b32_e32 v17, v0
	v_mov_b32_e32 v18, v0
	v_mov_b32_e32 v19, v0
	v_mov_b32_e32 v20, v0
	v_mov_b32_e32 v21, v0
	v_mov_b32_e32 v22, v0
	v_mov_b32_e32 v23, v0
	v_mov_b32_e32 v32, v0
	v_mov_b32_e32 v33, v0
	v_mov_b32_e32 v34, v0
	v_mov_b32_e32 v35, v0
	v_mov_b32_e32 v36, v0
	v_mov_b32_e32 v37, v0
	v_mov_b32_e32 v38, v0
	v_mov_b32_e32 v39, v0
	v_mov_b32_e32 v48, v0
	v_mov_b32_e32 v49, v0
	v_mov_b32_e32 v50, v0
	v_mov_b32_e32 v51, v0
	v_mov_b32_e32 v52, v0
	v_mov_b32_e32 v53, v0
	v_mov_b32_e32 v54, v0
	v_mov_b32_e32 v55, v0
	v_mov_b32_e32 v8, v0
	v_mov_b32_e32 v9, v0
	v_mov_b32_e32 v10, v0
	v_mov_b32_e32 v11, v0
	v_mov_b32_e32 v12, v0
	v_mov_b32_e32 v13, v0
	v_mov_b32_e32 v14, v0
	v_mov_b32_e32 v15, v0
	v_mov_b32_e32 v24, v0
	v_mov_b32_e32 v25, v0
	v_mov_b32_e32 v26, v0
	v_mov_b32_e32 v27, v0
	v_mov_b32_e32 v28, v0
	v_mov_b32_e32 v29, v0
	v_mov_b32_e32 v30, v0
	v_mov_b32_e32 v31, v0
	v_mov_b32_e32 v40, v0
	v_mov_b32_e32 v41, v0
	v_mov_b32_e32 v42, v0
	v_mov_b32_e32 v43, v0
	v_mov_b32_e32 v44, v0
	v_mov_b32_e32 v45, v0
	v_mov_b32_e32 v46, v0
	v_mov_b32_e32 v47, v0
	v_mov_b32_e32 v56, v0
	v_mov_b32_e32 v57, v0
	v_mov_b32_e32 v58, v0
	v_mov_b32_e32 v59, v0
	v_mov_b32_e32 v60, v0
	v_mov_b32_e32 v61, v0
	v_mov_b32_e32 v62, v0
	v_mov_b32_e32 v63, v0
	v_mov_b32_e32 v64, v0
	v_mov_b32_e32 v65, v0
	v_mov_b32_e32 v66, v0
	v_mov_b32_e32 v67, v0
	v_mov_b32_e32 v68, v0
	v_mov_b32_e32 v69, v0
	v_mov_b32_e32 v70, v0
	v_mov_b32_e32 v71, v0
	v_mov_b32_e32 v80, v0
	v_mov_b32_e32 v81, v0
	v_mov_b32_e32 v82, v0
	v_mov_b32_e32 v83, v0
	v_mov_b32_e32 v84, v0
	v_mov_b32_e32 v85, v0
	v_mov_b32_e32 v86, v0
	v_mov_b32_e32 v87, v0
	v_mov_b32_e32 v96, v0
	v_mov_b32_e32 v97, v0
	v_mov_b32_e32 v98, v0
	v_mov_b32_e32 v99, v0
	v_mov_b32_e32 v100, v0
	v_mov_b32_e32 v101, v0
	v_mov_b32_e32 v102, v0
	v_mov_b32_e32 v103, v0
	v_mov_b32_e32 v112, v0
	v_mov_b32_e32 v113, v0
	v_mov_b32_e32 v114, v0
	v_mov_b32_e32 v115, v0
	v_mov_b32_e32 v116, v0
	v_mov_b32_e32 v117, v0
	v_mov_b32_e32 v118, v0
	v_mov_b32_e32 v119, v0
	v_mov_b32_e32 v72, v0
	v_mov_b32_e32 v73, v0
	v_mov_b32_e32 v74, v0
	v_mov_b32_e32 v75, v0
	v_mov_b32_e32 v76, v0
	v_mov_b32_e32 v77, v0
	v_mov_b32_e32 v78, v0
	v_mov_b32_e32 v79, v0
	v_mov_b32_e32 v88, v0
	v_mov_b32_e32 v89, v0
	v_mov_b32_e32 v90, v0
	v_mov_b32_e32 v91, v0
	v_mov_b32_e32 v92, v0
	v_mov_b32_e32 v93, v0
	v_mov_b32_e32 v94, v0
	v_mov_b32_e32 v95, v0
	v_mov_b32_e32 v104, v0
	v_mov_b32_e32 v105, v0
	v_mov_b32_e32 v106, v0
	v_mov_b32_e32 v107, v0
	v_mov_b32_e32 v108, v0
	v_mov_b32_e32 v109, v0
	v_mov_b32_e32 v110, v0
	v_mov_b32_e32 v111, v0
	v_mov_b32_e32 v120, v0
	v_mov_b32_e32 v121, v0
	v_mov_b32_e32 v122, v0
	v_mov_b32_e32 v123, v0
	v_mov_b32_e32 v124, v0
	v_mov_b32_e32 v125, v0
	v_mov_b32_e32 v126, v0
	v_mov_b32_e32 v127, v0
	v_add_u32_e32 v248, 0x18000, v162
	v_add_u32_e32 v249, 0x1c000, v162
.LBB0_1148:
	v_lshl_add_u64 v[168:169], v[152:153], 0, s[18:19]
	s_cmpk_eq_i32 s18, 0x7f00
	v_lshl_add_u64 v[168:169], v[168:169], 0, s[16:17]
	v_lshl_add_u64 v[184:185], v[158:159], 0, s[18:19]
	s_cselect_b64 vcc, -1, 0
	v_cndmask_b32_e32 v233, v169, v149, vcc
	v_cndmask_b32_e32 v232, v168, v148, vcc
	ds_read_b128 v[168:171], v164
	ds_read_b128 v[172:175], v164 offset:1024
	ds_read_b128 v[176:179], v164 offset:2048
	ds_read_b128 v[180:183], v164 offset:3072
	v_cndmask_b32_e32 v235, v185, v151, vcc
	v_cndmask_b32_e32 v234, v184, v150, vcc
	ds_read_b128 v[184:187], v165
	ds_read_b128 v[188:191], v165 offset:1024
	ds_read_b128 v[192:195], v165 offset:2048
	ds_read_b128 v[196:199], v165 offset:3072
	v_lshl_add_u64 v[236:237], v[156:157], 0, s[18:19]
	s_add_i32 m0, s3, 0xc000
	ds_read_b128 v[200:203], v166
	ds_read_b128 v[204:207], v166 offset:1024
	ds_read_b128 v[208:211], v166 offset:2048
	ds_read_b128 v[212:215], v166 offset:3072
	ds_read_b128 v[216:219], v166 offset:4096
	ds_read_b128 v[220:223], v166 offset:5120
	ds_read_b128 v[224:227], v166 offset:6144
	ds_read_b128 v[228:231], v166 offset:7168
	global_load_lds_dwordx4 v[236:237], off
	v_lshl_add_u64 v[236:237], v[154:155], 0, s[18:19]
	s_add_i32 m0, s3, 0xe000
	s_nop 0
	global_load_lds_dwordx4 v[236:237], off
	s_waitcnt vmcnt(8)
	s_waitcnt lgkmcnt(0)
	s_barrier
; #define PG8_STAGE(bufoff, gbase, voff) do { _Pragma("unroll") for (int _i = 0; _i < 2; ++_i) \
;         __builtin_amdgcn_global_load_lds((const unsigned*)((const char*)(gbase) + (voff)[_i]), (LAS unsigned*)(lds + (bufoff) + ldsw + _i * 8192), 16, 0, 0); } while (0)
; #define PG8_LDA(dst, b, h) do { _Pragma("unroll") for (int m = 0; m < 4; ++m) _Pragma("unroll") for (int k = 0; k < 2; ++k) dst[m][k] = *(const LAS bf16x8*)(lds + PG8_SA(b, h) + aoff + m * 2048 + k * 1024); } while (0)
; #define PG8_WAIT_V(n) asm volatile("s_waitcnt vmcnt(" #n ")" ::: "memory")
; #define PG8_WAIT_L(n) asm volatile("s_waitcnt lgkmcnt(" #n ")" ::: "memory")
; #define PG8_BAR __builtin_amdgcn_s_barrier()
; #define PG8_SCHED __builtin_amdgcn_sched_barrier(0)
;     ...
;             PG8_WAIT_V(8); PG8_WAIT_L(0); PG8_BAR; PG8_MMA(0, 0, At, B0); PG8_MMA(0, 1, At, B1); PG8_BAR; PG8_SCHED;
;             PG8_LDA(At, 0, 1); PG8_STAGE(PG8_SB(0, 0), b2, voffB); PG8_STAGE(PG8_SB(0, 1), b2 + hstepB, voffB); PG8_STAGE(PG8_SA(0, 0), a2, voffA);
;             PG8_WAIT_V(8); PG8_WAIT_L(0); PG8_BAR; PG8_MMA(1, 0, At, B0); PG8_MMA(1, 1, At, B1); PG8_BAR; PG8_SCHED;
	s_setprio 1
	v_mfma_f32_16x16x32_bf16 v[124:127], v[168:171], v[200:203], v[124:127]
	v_mfma_f32_16x16x32_bf16 v[120:123], v[176:179], v[200:203], v[120:123]
	v_mfma_f32_16x16x32_bf16 v[108:111], v[168:171], v[208:211], v[108:111]
	v_mfma_f32_16x16x32_bf16 v[104:107], v[176:179], v[208:211], v[104:107]
	v_mfma_f32_16x16x32_bf16 v[92:95], v[168:171], v[216:219], v[92:95]
	v_mfma_f32_16x16x32_bf16 v[88:91], v[176:179], v[216:219], v[88:91]
	v_mfma_f32_16x16x32_bf16 v[76:79], v[168:171], v[224:227], v[76:79]
	v_mfma_f32_16x16x32_bf16 v[72:75], v[176:179], v[224:227], v[72:75]
	v_mfma_f32_16x16x32_bf16 v[124:127], v[172:175], v[204:207], v[124:127]
	v_mfma_f32_16x16x32_bf16 v[120:123], v[180:183], v[204:207], v[120:123]
	v_mfma_f32_16x16x32_bf16 v[108:111], v[172:175], v[212:215], v[108:111]
	v_mfma_f32_16x16x32_bf16 v[104:107], v[180:183], v[212:215], v[104:107]
	v_mfma_f32_16x16x32_bf16 v[92:95], v[172:175], v[220:223], v[92:95]
	v_mfma_f32_16x16x32_bf16 v[88:91], v[180:183], v[220:223], v[88:91]
	v_mfma_f32_16x16x32_bf16 v[76:79], v[172:175], v[228:231], v[76:79]
	v_mfma_f32_16x16x32_bf16 v[72:75], v[180:183], v[228:231], v[72:75]
	v_mfma_f32_16x16x32_bf16 v[116:119], v[184:187], v[200:203], v[116:119]
	v_mfma_f32_16x16x32_bf16 v[112:115], v[192:195], v[200:203], v[112:115]
	v_mfma_f32_16x16x32_bf16 v[100:103], v[184:187], v[208:211], v[100:103]
	v_mfma_f32_16x16x32_bf16 v[96:99], v[192:195], v[208:211], v[96:99]
	v_mfma_f32_16x16x32_bf16 v[84:87], v[184:187], v[216:219], v[84:87]
	v_mfma_f32_16x16x32_bf16 v[80:83], v[192:195], v[216:219], v[80:83]
	v_mfma_f32_16x16x32_bf16 v[68:71], v[184:187], v[224:227], v[68:71]
	v_mfma_f32_16x16x32_bf16 v[64:67], v[192:195], v[224:227], v[64:67]
	v_mfma_f32_16x16x32_bf16 v[116:119], v[188:191], v[204:207], v[116:119]
	v_mfma_f32_16x16x32_bf16 v[112:115], v[196:199], v[204:207], v[112:115]
	v_mfma_f32_16x16x32_bf16 v[100:103], v[188:191], v[212:215], v[100:103]
	v_mfma_f32_16x16x32_bf16 v[96:99], v[196:199], v[212:215], v[96:99]
	v_mfma_f32_16x16x32_bf16 v[84:87], v[188:191], v[220:223], v[84:87]
	v_mfma_f32_16x16x32_bf16 v[80:83], v[196:199], v[220:223], v[80:83]
	v_mfma_f32_16x16x32_bf16 v[68:71], v[188:191], v[228:231], v[68:71]
	v_mfma_f32_16x16x32_bf16 v[64:67], v[196:199], v[228:231], v[64:67]
	s_setprio 0
	s_barrier
	s_add_i32 s21, s43, s2
	v_lshl_add_u64 v[236:237], v[234:235], 0, v[130:131]
	s_mov_b32 m0, s21
	ds_read_b128 v[200:203], v166 offset:16384
	ds_read_b128 v[204:207], v166 offset:17408
	ds_read_b128 v[208:211], v166 offset:18432
	ds_read_b128 v[212:215], v166 offset:19456
	ds_read_b128 v[216:219], v166 offset:20480
	ds_read_b128 v[220:223], v166 offset:21504
	ds_read_b128 v[224:227], v166 offset:22528
	ds_read_b128 v[228:231], v166 offset:23552
	global_load_lds_dwordx4 v[236:237], off
	v_lshl_add_u64 v[238:239], v[234:235], 0, v[134:135]
	s_add_i32 m0, s21, 0x2000
	v_lshl_add_u64 v[234:235], v[234:235], 0, v[138:139]
	s_add_i32 s21, s46, s2
	global_load_lds_dwordx4 v[238:239], off
	v_lshl_add_u64 v[240:241], v[234:235], 0, v[130:131]
	s_mov_b32 m0, s21
	v_lshl_add_u64 v[234:235], v[234:235], 0, v[134:135]
	global_load_lds_dwordx4 v[240:241], off
	s_add_i32 m0, s21, 0x2000
	v_lshl_add_u64 v[242:243], v[232:233], 0, v[128:129]
	global_load_lds_dwordx4 v[234:235], off
	s_mov_b32 m0, s3
	v_lshl_add_u64 v[244:245], v[232:233], 0, v[132:133]
	global_load_lds_dwordx4 v[242:243], off
	s_mov_b32 m0, s22
	s_nop 0
	global_load_lds_dwordx4 v[244:245], off
	s_waitcnt vmcnt(8)
	s_waitcnt lgkmcnt(0)
	s_barrier
	s_setprio 1
	v_mfma_f32_16x16x32_bf16 v[60:63], v[168:171], v[200:203], v[60:63]
	v_mfma_f32_16x16x32_bf16 v[56:59], v[176:179], v[200:203], v[56:59]
	v_mfma_f32_16x16x32_bf16 v[44:47], v[168:171], v[208:211], v[44:47]
	v_mfma_f32_16x16x32_bf16 v[40:43], v[176:179], v[208:211], v[40:43]
	v_mfma_f32_16x16x32_bf16 v[28:31], v[168:171], v[216:219], v[28:31]
	v_mfma_f32_16x16x32_bf16 v[24:27], v[176:179], v[216:219], v[24:27]
	v_mfma_f32_16x16x32_bf16 v[12:15], v[168:171], v[224:227], v[12:15]
	v_mfma_f32_16x16x32_bf16 v[8:11], v[176:179], v[224:227], v[8:11]
	v_mfma_f32_16x16x32_bf16 v[60:63], v[172:175], v[204:207], v[60:63]
	v_mfma_f32_16x16x32_bf16 v[56:59], v[180:183], v[204:207], v[56:59]
	v_mfma_f32_16x16x32_bf16 v[44:47], v[172:175], v[212:215], v[44:47]
	v_mfma_f32_16x16x32_bf16 v[40:43], v[180:183], v[212:215], v[40:43]
	v_mfma_f32_16x16x32_bf16 v[28:31], v[172:175], v[220:223], v[28:31]
	v_mfma_f32_16x16x32_bf16 v[24:27], v[180:183], v[220:223], v[24:27]
	v_mfma_f32_16x16x32_bf16 v[12:15], v[172:175], v[228:231], v[12:15]
	v_mfma_f32_16x16x32_bf16 v[8:11], v[180:183], v[228:231], v[8:11]
	v_mfma_f32_16x16x32_bf16 v[52:55], v[184:187], v[200:203], v[52:55]
	v_mfma_f32_16x16x32_bf16 v[48:51], v[192:195], v[200:203], v[48:51]
	v_mfma_f32_16x16x32_bf16 v[36:39], v[184:187], v[208:211], v[36:39]
	v_mfma_f32_16x16x32_bf16 v[32:35], v[192:195], v[208:211], v[32:35]
	v_mfma_f32_16x16x32_bf16 v[20:23], v[184:187], v[216:219], v[20:23]
	v_mfma_f32_16x16x32_bf16 v[16:19], v[192:195], v[216:219], v[16:19]
	v_mfma_f32_16x16x32_bf16 v[4:7], v[184:187], v[224:227], v[4:7]
	v_mfma_f32_16x16x32_bf16 v[0:3], v[192:195], v[224:227], v[0:3]
	v_mfma_f32_16x16x32_bf16 v[52:55], v[188:191], v[204:207], v[52:55]
	v_mfma_f32_16x16x32_bf16 v[48:51], v[196:199], v[204:207], v[48:51]
	v_mfma_f32_16x16x32_bf16 v[36:39], v[188:191], v[212:215], v[36:39]
	v_mfma_f32_16x16x32_bf16 v[32:35], v[196:199], v[212:215], v[32:35]
	v_mfma_f32_16x16x32_bf16 v[20:23], v[188:191], v[220:223], v[20:23]
	v_mfma_f32_16x16x32_bf16 v[16:19], v[196:199], v[220:223], v[16:19]
	v_mfma_f32_16x16x32_bf16 v[4:7], v[188:191], v[228:231], v[4:7]
	v_mfma_f32_16x16x32_bf16 v[0:3], v[196:199], v[228:231], v[0:3]
	s_setprio 0
	s_barrier
; #define PG8_STAGE(bufoff, gbase, voff) do { _Pragma("unroll") for (int _i = 0; _i < 2; ++_i) \
;         __builtin_amdgcn_global_load_lds((const unsigned*)((const char*)(gbase) + (voff)[_i]), (LAS unsigned*)(lds + (bufoff) + ldsw + _i * 8192), 16, 0, 0); } while (0)
; #define PG8_LDA(dst, b, h) do { _Pragma("unroll") for (int m = 0; m < 4; ++m) _Pragma("unroll") for (int k = 0; k < 2; ++k) dst[m][k] = *(const LAS bf16x8*)(lds + PG8_SA(b, h) + aoff + m * 2048 + k * 1024); } while (0)
; #define PG8_LDB(dst, b, h) do { _Pragma("unroll") for (int n = 0; n < 2; ++n) _Pragma("unroll") for (int k = 0; k < 2; ++k) dst[n][k] = *(const LAS bf16x8*)(lds + PG8_SB(b, h) + boff + n * 2048 + k * 1024); } while (0)
; #define PG8_WAIT_V(n) asm volatile("s_waitcnt vmcnt(" #n ")" ::: "memory")
; #define PG8_WAIT_L(n) asm volatile("s_waitcnt lgkmcnt(" #n ")" ::: "memory")
; #define PG8_BAR __builtin_amdgcn_s_barrier()
; #define PG8_SCHED __builtin_amdgcn_sched_barrier(0)
;     ...
;             PG8_LDB(B0, 1, 0); PG8_LDB(B1, 1, 1); PG8_SCHED; PG8_LDA(At, 1, 0); PG8_STAGE(PG8_SA(0, 1), a2 + hstepA, voffA);
;             PG8_WAIT_V(8); PG8_WAIT_L(0); PG8_BAR; PG8_MMA(0, 0, At, B0); PG8_MMA(0, 1, At, B1); PG8_BAR; PG8_SCHED;
;             PG8_LDA(At, 1, 1); PG8_STAGE(PG8_SB(1, 0), b3, voffB); PG8_STAGE(PG8_SB(1, 1), b3 + hstepB, voffB); PG8_STAGE(PG8_SA(1, 0), a3, voffA);
;             PG8_WAIT_V(8); PG8_WAIT_L(0); PG8_BAR; PG8_MMA(1, 0, At, B0); PG8_MMA(1, 1, At, B1); PG8_BAR; PG8_SCHED;
	s_add_i32 s21, 0, 0x18000
	s_add_i32 s40, 0, 0x1c000
	ds_read_b128 v[168:171], v248
	ds_read_b128 v[172:175], v248 offset:1024
	ds_read_b128 v[176:179], v248 offset:2048
	ds_read_b128 v[180:183], v248 offset:3072
	ds_read_b128 v[184:187], v249
	ds_read_b128 v[188:191], v249 offset:1024
	ds_read_b128 v[192:195], v249 offset:2048
	ds_read_b128 v[196:199], v249 offset:3072
	v_lshl_add_u64 v[232:233], v[232:233], 0, v[136:137]
	s_mov_b32 m0, s23
	v_lshl_add_u64 v[246:247], v[232:233], 0, v[128:129]
	ds_read_b128 v[200:203], v166 offset:32768
	ds_read_b128 v[204:207], v166 offset:33792
	ds_read_b128 v[208:211], v166 offset:34816
	ds_read_b128 v[212:215], v166 offset:35840
	ds_read_b128 v[216:219], v166 offset:36864
	ds_read_b128 v[220:223], v166 offset:37888
	ds_read_b128 v[224:227], v166 offset:38912
	ds_read_b128 v[228:231], v166 offset:39936
	global_load_lds_dwordx4 v[246:247], off
	v_lshl_add_u64 v[232:233], v[232:233], 0, v[132:133]
	s_mov_b32 m0, s24
	s_nop 0
	global_load_lds_dwordx4 v[232:233], off
	s_waitcnt vmcnt(8)
	s_waitcnt lgkmcnt(0)
	s_barrier
	s_setprio 1
	v_mfma_f32_16x16x32_bf16 v[124:127], v[168:171], v[200:203], v[124:127]
	v_mfma_f32_16x16x32_bf16 v[120:123], v[176:179], v[200:203], v[120:123]
	v_mfma_f32_16x16x32_bf16 v[108:111], v[168:171], v[208:211], v[108:111]
	v_mfma_f32_16x16x32_bf16 v[104:107], v[176:179], v[208:211], v[104:107]
	v_mfma_f32_16x16x32_bf16 v[92:95], v[168:171], v[216:219], v[92:95]
	v_mfma_f32_16x16x32_bf16 v[88:91], v[176:179], v[216:219], v[88:91]
	v_mfma_f32_16x16x32_bf16 v[76:79], v[168:171], v[224:227], v[76:79]
	v_mfma_f32_16x16x32_bf16 v[72:75], v[176:179], v[224:227], v[72:75]
	v_mfma_f32_16x16x32_bf16 v[124:127], v[172:175], v[204:207], v[124:127]
	v_mfma_f32_16x16x32_bf16 v[120:123], v[180:183], v[204:207], v[120:123]
	v_mfma_f32_16x16x32_bf16 v[108:111], v[172:175], v[212:215], v[108:111]
	v_mfma_f32_16x16x32_bf16 v[104:107], v[180:183], v[212:215], v[104:107]
	v_mfma_f32_16x16x32_bf16 v[92:95], v[172:175], v[220:223], v[92:95]
	v_mfma_f32_16x16x32_bf16 v[88:91], v[180:183], v[220:223], v[88:91]
	v_mfma_f32_16x16x32_bf16 v[76:79], v[172:175], v[228:231], v[76:79]
	v_mfma_f32_16x16x32_bf16 v[72:75], v[180:183], v[228:231], v[72:75]
	v_mfma_f32_16x16x32_bf16 v[116:119], v[184:187], v[200:203], v[116:119]
	v_mfma_f32_16x16x32_bf16 v[112:115], v[192:195], v[200:203], v[112:115]
	v_mfma_f32_16x16x32_bf16 v[100:103], v[184:187], v[208:211], v[100:103]
	v_mfma_f32_16x16x32_bf16 v[96:99], v[192:195], v[208:211], v[96:99]
	v_mfma_f32_16x16x32_bf16 v[84:87], v[184:187], v[216:219], v[84:87]
	v_mfma_f32_16x16x32_bf16 v[80:83], v[192:195], v[216:219], v[80:83]
	v_mfma_f32_16x16x32_bf16 v[68:71], v[184:187], v[224:227], v[68:71]
	v_mfma_f32_16x16x32_bf16 v[64:67], v[192:195], v[224:227], v[64:67]
	v_mfma_f32_16x16x32_bf16 v[116:119], v[188:191], v[204:207], v[116:119]
	v_mfma_f32_16x16x32_bf16 v[112:115], v[196:199], v[204:207], v[112:115]
	v_mfma_f32_16x16x32_bf16 v[100:103], v[188:191], v[212:215], v[100:103]
	v_mfma_f32_16x16x32_bf16 v[96:99], v[196:199], v[212:215], v[96:99]
	v_mfma_f32_16x16x32_bf16 v[84:87], v[188:191], v[220:223], v[84:87]
	v_mfma_f32_16x16x32_bf16 v[80:83], v[196:199], v[220:223], v[80:83]
	v_mfma_f32_16x16x32_bf16 v[68:71], v[188:191], v[228:231], v[68:71]
	v_mfma_f32_16x16x32_bf16 v[64:67], v[196:199], v[228:231], v[64:67]
	s_setprio 0
	s_barrier
	s_add_i32 s21, s21, s2
	v_lshl_add_u64 v[232:233], v[236:237], 0, s[12:13]
	s_mov_b32 m0, s21
	ds_read_b128 v[200:203], v166 offset:49152
	ds_read_b128 v[204:207], v166 offset:50176
	ds_read_b128 v[208:211], v166 offset:51200
	ds_read_b128 v[212:215], v166 offset:52224
	ds_read_b128 v[216:219], v166 offset:53248
	ds_read_b128 v[220:223], v166 offset:54272
	ds_read_b128 v[224:227], v166 offset:55296
	ds_read_b128 v[228:231], v166 offset:56320
	global_load_lds_dwordx4 v[232:233], off
	v_lshl_add_u64 v[232:233], v[238:239], 0, s[12:13]
	s_add_i32 m0, s21, 0x2000
	s_add_i32 s21, s40, s2
	global_load_lds_dwordx4 v[232:233], off
	v_lshl_add_u64 v[232:233], v[240:241], 0, s[12:13]
	s_mov_b32 m0, s21
	s_nop 0
	global_load_lds_dwordx4 v[232:233], off
	v_lshl_add_u64 v[232:233], v[234:235], 0, s[12:13]
	s_add_i32 m0, s21, 0x2000
	s_nop 0
	global_load_lds_dwordx4 v[232:233], off
	v_lshl_add_u64 v[232:233], v[242:243], 0, s[12:13]
	s_mov_b32 m0, s30
	s_nop 0
	global_load_lds_dwordx4 v[232:233], off
	v_lshl_add_u64 v[232:233], v[244:245], 0, s[12:13]
	s_mov_b32 m0, s31
	s_nop 0
	global_load_lds_dwordx4 v[232:233], off
	s_waitcnt vmcnt(8)
	s_waitcnt lgkmcnt(0)
	s_barrier
	s_setprio 1
	v_mfma_f32_16x16x32_bf16 v[60:63], v[168:171], v[200:203], v[60:63]
	v_mfma_f32_16x16x32_bf16 v[56:59], v[176:179], v[200:203], v[56:59]
	v_mfma_f32_16x16x32_bf16 v[44:47], v[168:171], v[208:211], v[44:47]
	v_mfma_f32_16x16x32_bf16 v[40:43], v[176:179], v[208:211], v[40:43]
	v_mfma_f32_16x16x32_bf16 v[28:31], v[168:171], v[216:219], v[28:31]
	v_mfma_f32_16x16x32_bf16 v[24:27], v[176:179], v[216:219], v[24:27]
	v_mfma_f32_16x16x32_bf16 v[12:15], v[168:171], v[224:227], v[12:15]
	v_mfma_f32_16x16x32_bf16 v[8:11], v[176:179], v[224:227], v[8:11]
	v_mfma_f32_16x16x32_bf16 v[60:63], v[172:175], v[204:207], v[60:63]
	v_mfma_f32_16x16x32_bf16 v[56:59], v[180:183], v[204:207], v[56:59]
	v_mfma_f32_16x16x32_bf16 v[44:47], v[172:175], v[212:215], v[44:47]
	v_mfma_f32_16x16x32_bf16 v[40:43], v[180:183], v[212:215], v[40:43]
	v_mfma_f32_16x16x32_bf16 v[28:31], v[172:175], v[220:223], v[28:31]
	v_mfma_f32_16x16x32_bf16 v[24:27], v[180:183], v[220:223], v[24:27]
	v_mfma_f32_16x16x32_bf16 v[12:15], v[172:175], v[228:231], v[12:15]
	v_mfma_f32_16x16x32_bf16 v[8:11], v[180:183], v[228:231], v[8:11]
	v_mfma_f32_16x16x32_bf16 v[52:55], v[184:187], v[200:203], v[52:55]
	v_mfma_f32_16x16x32_bf16 v[48:51], v[192:195], v[200:203], v[48:51]
	v_mfma_f32_16x16x32_bf16 v[36:39], v[184:187], v[208:211], v[36:39]
	v_mfma_f32_16x16x32_bf16 v[32:35], v[192:195], v[208:211], v[32:35]
	v_mfma_f32_16x16x32_bf16 v[20:23], v[184:187], v[216:219], v[20:23]
	v_mfma_f32_16x16x32_bf16 v[16:19], v[192:195], v[216:219], v[16:19]
	v_mfma_f32_16x16x32_bf16 v[4:7], v[184:187], v[224:227], v[4:7]
	v_mfma_f32_16x16x32_bf16 v[0:3], v[192:195], v[224:227], v[0:3]
	v_mfma_f32_16x16x32_bf16 v[52:55], v[188:191], v[204:207], v[52:55]
	v_mfma_f32_16x16x32_bf16 v[48:51], v[196:199], v[204:207], v[48:51]
	v_mfma_f32_16x16x32_bf16 v[36:39], v[188:191], v[212:215], v[36:39]
	v_mfma_f32_16x16x32_bf16 v[32:35], v[196:199], v[212:215], v[32:35]
	v_mfma_f32_16x16x32_bf16 v[20:23], v[188:191], v[220:223], v[20:23]
	v_mfma_f32_16x16x32_bf16 v[16:19], v[196:199], v[220:223], v[16:19]
	v_mfma_f32_16x16x32_bf16 v[4:7], v[188:191], v[228:231], v[4:7]
	v_mfma_f32_16x16x32_bf16 v[0:3], v[196:199], v[228:231], v[0:3]
	s_setprio 0
	s_barrier
	s_add_i32 s20, s20, 2
	s_add_u32 s18, s18, 0x100
	s_addc_u32 s19, s19, 0
	s_cmpk_gt_u32 s20, 0xfd
	s_cbranch_scc0 .LBB0_1148
	s_and_b64 vcc, exec, s[14:15]
	s_cbranch_vccz .LBB0_1151
	s_barrier
